# v30 plus extra s_setprio 0/1 flip points after every 8 MFMAs (all GEMM K-loops)
# baseline (speedup 1.0000x reference)
; #define PG8_STAGE(bufoff, gbase, voff) do { _Pragma("unroll") for (int _i = 0; _i < 2; ++_i) \
;         __builtin_amdgcn_global_load_lds((const unsigned*)((const char*)(gbase) + (voff)[_i]), (LAS unsigned*)(lds + (bufoff) + ldsw + _i * 8192), 16, 0, 0); } while (0)
; #define PG8_LDA(dst, b, h) do { _Pragma("unroll") for (int m = 0; m < 4; ++m) _Pragma("unroll") for (int k = 0; k < 2; ++k) dst[m][k] = *(const LAS bf16x8*)(lds + PG8_SA(b, h) + aoff + m * 2048 + k * 1024); } while (0)
; #define PG8_BAR __builtin_amdgcn_s_barrier()
; template <class Epi, class Sched, bool ALIGN_EPI = false, bool SP2 = false, bool TWOA = false, bool AGM = false>
; __device__ __forceinline__ void gemm_phase(LAS unsigned char* lds, const Gemm g, const Sched& S, const Epi& E, int wid) {
;     ...
;         for (int t = 0; t < nt; t += 2) {
;             const bool last = (t == nt - 2);
;             const char* cA2 = TWOA ? (const char*)g.A2 + (cA - (const char*)g.A) - (size_t)nh * kstepA : cA;
;             const char* a1_ = (TWOA && t + 1 >= nh ? cA2 : cA) + (size_t)(t + 1) * kstepA;
;             const char* a2_ = last ? nA : (TWOA && t + 2 >= nh ? cA2 : cA) + (size_t)(t + 2) * kstepA; const char* a1 = a1_; const char* a2 = a2_; const char* b2 = last ? nB : cB + (size_t)(t + 2) * kstep;
;             if constexpr (TWOA) { asm volatile("" : "+s"(a1)); asm volatile("" : "+s"(a2)); }
;             const char* a3 = a2 + kstepA; const char* b3 = b2 + kstep;
;             if (last && has_next) S.a_ready(nxt);
;             if constexpr (has_mid<Epi>::value) { if (t == nh) E.mid(acc, cur, wr, wc, fr, fq); }
;             if constexpr (SP2) {
;             PG8_LDB(B0, 0, 0); PG8_LDB(B1, 0, 1); PG8_SCHED; PG8_LDA(At, 0, 0); PG8_STAGE(PG8_SA(1, 1), a1 + hstepA, voffA);
;             PG8_WAIT_V(8); PG8_WAIT_L(0); PG8_BAR; PG8_MMA(0, 0, At, B0); PG8_MMA(0, 1, At, B1); PG8_BAR; PG8_SCHED;
;             PG8_LDA(At, 0, 1); PG8_STAGE(PG8_SB(0, 0), b2, voffB); PG8_STAGE(PG8_SB(0, 1), b2 + hstep, voffB); PG8_STAGE(PG8_SA(0, 0), a2, voffA);
;             PG8_WAIT_V(8); PG8_WAIT_L(0); PG8_BAR; PG8_MMA(1, 0, At, B0); PG8_MMA(1, 1, At, B1); PG8_BAR; PG8_SCHED;
;             PG8_LDB(B0, 1, 0); PG8_LDB(B1, 1, 1); PG8_SCHED; PG8_LDA(At, 1, 0); PG8_STAGE(PG8_SA(0, 1), a2 + hstepA, voffA);
;             PG8_WAIT_V(8); PG8_WAIT_L(0); PG8_BAR; PG8_MMA(0, 0, At, B0); PG8_MMA(0, 1, At, B1); PG8_BAR; PG8_SCHED;
.LBB0_230:
	ds_read_b128 v[146:149], v155
	ds_read_b128 v[160:163], v155 offset:1024
	ds_read_b128 v[164:167], v155 offset:2048
	ds_read_b128 v[168:171], v155 offset:3072
	ds_read_b128 v[172:175], v156
	ds_read_b128 v[176:179], v156 offset:1024
	ds_read_b128 v[180:183], v156 offset:2048
	ds_read_b128 v[184:187], v156 offset:3072
	s_add_u32 s12, s10, 0xfff00080
	s_addc_u32 s13, s11, -1
	s_cmp_eq_u32 s70, 60
	s_cselect_b32 s67, s7, s13
	s_cselect_b32 s66, s9, s12
	s_cselect_b32 s13, s53, s69
	s_cselect_b32 s12, s55, s68
	s_add_i32 m0, s76, 0xc000
	ds_read_b128 v[188:191], v157
	ds_read_b128 v[192:195], v157 offset:1024
	ds_read_b128 v[196:199], v157 offset:2048
	ds_read_b128 v[200:203], v157 offset:3072
	ds_read_b128 v[204:207], v157 offset:4096
	ds_read_b128 v[208:211], v157 offset:5120
	ds_read_b128 v[212:215], v157 offset:6144
	ds_read_b128 v[216:219], v157 offset:7168
	global_load_lds_dwordx4 v138, s[10:11]
	s_add_i32 m0, s76, 0xe000
	s_nop 0
	global_load_lds_dwordx4 v140, s[10:11]
	s_waitcnt vmcnt(8)
	s_waitcnt lgkmcnt(0)
	s_barrier
	s_setprio 1
	s_waitcnt lgkmcnt(0)
	v_mfma_f32_16x16x32_bf16 v[124:127], v[146:149], v[188:191], v[124:127]
	v_mfma_f32_16x16x32_bf16 v[120:123], v[164:167], v[188:191], v[120:123]
	v_mfma_f32_16x16x32_bf16 v[108:111], v[146:149], v[196:199], v[108:111]
	v_mfma_f32_16x16x32_bf16 v[104:107], v[164:167], v[196:199], v[104:107]
	v_mfma_f32_16x16x32_bf16 v[92:95], v[146:149], v[204:207], v[92:95]
	v_mfma_f32_16x16x32_bf16 v[88:91], v[164:167], v[204:207], v[88:91]
	v_mfma_f32_16x16x32_bf16 v[76:79], v[146:149], v[212:215], v[76:79]
	v_mfma_f32_16x16x32_bf16 v[72:75], v[164:167], v[212:215], v[72:75]
	s_setprio 0
	s_setprio 1
	v_mfma_f32_16x16x32_bf16 v[124:127], v[160:163], v[192:195], v[124:127]
	v_mfma_f32_16x16x32_bf16 v[120:123], v[168:171], v[192:195], v[120:123]
	v_mfma_f32_16x16x32_bf16 v[108:111], v[160:163], v[200:203], v[108:111]
	v_mfma_f32_16x16x32_bf16 v[104:107], v[168:171], v[200:203], v[104:107]
	v_mfma_f32_16x16x32_bf16 v[92:95], v[160:163], v[208:211], v[92:95]
	v_mfma_f32_16x16x32_bf16 v[88:91], v[168:171], v[208:211], v[88:91]
	v_mfma_f32_16x16x32_bf16 v[76:79], v[160:163], v[216:219], v[76:79]
	v_mfma_f32_16x16x32_bf16 v[72:75], v[168:171], v[216:219], v[72:75]
	s_setprio 0
	s_setprio 1
	v_mfma_f32_16x16x32_bf16 v[116:119], v[172:175], v[188:191], v[116:119]
	v_mfma_f32_16x16x32_bf16 v[112:115], v[180:183], v[188:191], v[112:115]
	v_mfma_f32_16x16x32_bf16 v[100:103], v[172:175], v[196:199], v[100:103]
	v_mfma_f32_16x16x32_bf16 v[96:99], v[180:183], v[196:199], v[96:99]
	v_mfma_f32_16x16x32_bf16 v[84:87], v[172:175], v[204:207], v[84:87]
	v_mfma_f32_16x16x32_bf16 v[80:83], v[180:183], v[204:207], v[80:83]
	v_mfma_f32_16x16x32_bf16 v[68:71], v[172:175], v[212:215], v[68:71]
	v_mfma_f32_16x16x32_bf16 v[64:67], v[180:183], v[212:215], v[64:67]
	s_setprio 0
	s_setprio 1
	v_mfma_f32_16x16x32_bf16 v[116:119], v[176:179], v[192:195], v[116:119]
	v_mfma_f32_16x16x32_bf16 v[112:115], v[184:187], v[192:195], v[112:115]
	v_mfma_f32_16x16x32_bf16 v[100:103], v[176:179], v[200:203], v[100:103]
	v_mfma_f32_16x16x32_bf16 v[96:99], v[184:187], v[200:203], v[96:99]
	v_mfma_f32_16x16x32_bf16 v[84:87], v[176:179], v[208:211], v[84:87]
	v_mfma_f32_16x16x32_bf16 v[80:83], v[184:187], v[208:211], v[80:83]
	v_mfma_f32_16x16x32_bf16 v[68:71], v[176:179], v[216:219], v[68:71]
	v_mfma_f32_16x16x32_bf16 v[64:67], v[184:187], v[216:219], v[64:67]
	s_setprio 0
	s_barrier
	s_add_i32 s34, s95, s75
	s_mov_b32 m0, s34
	ds_read_b128 v[188:191], v157 offset:16384
	ds_read_b128 v[192:195], v157 offset:17408
	ds_read_b128 v[196:199], v157 offset:18432
	ds_read_b128 v[200:203], v157 offset:19456
	ds_read_b128 v[204:207], v157 offset:20480
	ds_read_b128 v[208:211], v157 offset:21504
	ds_read_b128 v[212:215], v157 offset:22528
	ds_read_b128 v[216:219], v157 offset:23552
	global_load_lds_dwordx4 v130, s[12:13]
	s_add_i32 m0, s34, 0x2000
	s_add_u32 s34, s12, 0x100000
	s_addc_u32 s35, s13, 0
	s_add_i32 s71, s96, s75
	global_load_lds_dwordx4 v134, s[12:13]
	s_mov_b32 m0, s71
	s_nop 0
	global_load_lds_dwordx4 v130, s[34:35]
	s_add_i32 m0, s71, 0x2000
	s_nop 0
	global_load_lds_dwordx4 v134, s[34:35]
	s_mov_b32 m0, s76
	s_nop 0
	global_load_lds_dwordx4 v128, s[66:67]
	s_mov_b32 m0, s77
	s_nop 0
	global_load_lds_dwordx4 v132, s[66:67]
	s_waitcnt vmcnt(8)
	s_waitcnt lgkmcnt(0)
	s_barrier
	s_setprio 1
	s_waitcnt lgkmcnt(0)
	v_mfma_f32_16x16x32_bf16 v[60:63], v[146:149], v[188:191], v[60:63]
	v_mfma_f32_16x16x32_bf16 v[56:59], v[164:167], v[188:191], v[56:59]
	v_mfma_f32_16x16x32_bf16 v[44:47], v[146:149], v[196:199], v[44:47]
	v_mfma_f32_16x16x32_bf16 v[40:43], v[164:167], v[196:199], v[40:43]
	v_mfma_f32_16x16x32_bf16 v[28:31], v[146:149], v[204:207], v[28:31]
	v_mfma_f32_16x16x32_bf16 v[24:27], v[164:167], v[204:207], v[24:27]
	v_mfma_f32_16x16x32_bf16 v[12:15], v[146:149], v[212:215], v[12:15]
	v_mfma_f32_16x16x32_bf16 v[8:11], v[164:167], v[212:215], v[8:11]
	s_setprio 0
	s_setprio 1
	v_mfma_f32_16x16x32_bf16 v[60:63], v[160:163], v[192:195], v[60:63]
	v_mfma_f32_16x16x32_bf16 v[56:59], v[168:171], v[192:195], v[56:59]
	v_mfma_f32_16x16x32_bf16 v[44:47], v[160:163], v[200:203], v[44:47]
	v_mfma_f32_16x16x32_bf16 v[40:43], v[168:171], v[200:203], v[40:43]
	v_mfma_f32_16x16x32_bf16 v[28:31], v[160:163], v[208:211], v[28:31]
	v_mfma_f32_16x16x32_bf16 v[24:27], v[168:171], v[208:211], v[24:27]
	v_mfma_f32_16x16x32_bf16 v[12:15], v[160:163], v[216:219], v[12:15]
	v_mfma_f32_16x16x32_bf16 v[8:11], v[168:171], v[216:219], v[8:11]
	s_setprio 0
	s_setprio 1
	v_mfma_f32_16x16x32_bf16 v[52:55], v[172:175], v[188:191], v[52:55]
	v_mfma_f32_16x16x32_bf16 v[48:51], v[180:183], v[188:191], v[48:51]
	v_mfma_f32_16x16x32_bf16 v[36:39], v[172:175], v[196:199], v[36:39]
	v_mfma_f32_16x16x32_bf16 v[32:35], v[180:183], v[196:199], v[32:35]
	v_mfma_f32_16x16x32_bf16 v[20:23], v[172:175], v[204:207], v[20:23]
	v_mfma_f32_16x16x32_bf16 v[16:19], v[180:183], v[204:207], v[16:19]
	v_mfma_f32_16x16x32_bf16 v[4:7], v[172:175], v[212:215], v[4:7]
	v_mfma_f32_16x16x32_bf16 v[0:3], v[180:183], v[212:215], v[0:3]
	s_setprio 0
	s_setprio 1
	v_mfma_f32_16x16x32_bf16 v[52:55], v[176:179], v[192:195], v[52:55]
	v_mfma_f32_16x16x32_bf16 v[48:51], v[184:187], v[192:195], v[48:51]
	v_mfma_f32_16x16x32_bf16 v[36:39], v[176:179], v[200:203], v[36:39]
	v_mfma_f32_16x16x32_bf16 v[32:35], v[184:187], v[200:203], v[32:35]
	v_mfma_f32_16x16x32_bf16 v[20:23], v[176:179], v[208:211], v[20:23]
	v_mfma_f32_16x16x32_bf16 v[16:19], v[184:187], v[208:211], v[16:19]
	v_mfma_f32_16x16x32_bf16 v[4:7], v[176:179], v[216:219], v[4:7]
	v_mfma_f32_16x16x32_bf16 v[0:3], v[184:187], v[216:219], v[0:3]
	s_setprio 0
	s_barrier
; #define PG8_STAGE(bufoff, gbase, voff) do { _Pragma("unroll") for (int _i = 0; _i < 2; ++_i) \
;         __builtin_amdgcn_global_load_lds((const unsigned*)((const char*)(gbase) + (voff)[_i]), (LAS unsigned*)(lds + (bufoff) + ldsw + _i * 8192), 16, 0, 0); } while (0)
; #define PG8_LDA(dst, b, h) do { _Pragma("unroll") for (int m = 0; m < 4; ++m) _Pragma("unroll") for (int k = 0; k < 2; ++k) dst[m][k] = *(const LAS bf16x8*)(lds + PG8_SA(b, h) + aoff + m * 2048 + k * 1024); } while (0)
; #define PG8_LDB(dst, b, h) do { _Pragma("unroll") for (int n = 0; n < 2; ++n) _Pragma("unroll") for (int k = 0; k < 2; ++k) dst[n][k] = *(const LAS bf16x8*)(lds + PG8_SB(b, h) + boff + n * 2048 + k * 1024); } while (0)
; #define PG8_MMA(ai, bj, At, Bt) do { __builtin_amdgcn_s_setprio(1); _Pragma("unroll") for (int m = 0; m < 4; ++m) _Pragma("unroll") for (int n = 0; n < 2; ++n) _Pragma("unroll") for (int k = 0; k < 2; ++k) \
;         acc[ai][bj][m][n] = __builtin_amdgcn_mfma_f32_16x16x32_bf16(Bt[n][k], At[m][k], acc[ai][bj][m][n], 0, 0, 0); __builtin_amdgcn_s_setprio(0); } while (0)
; #define PG8_WAIT_V(n) asm volatile("s_waitcnt vmcnt(" #n ")" ::: "memory")
; #define PG8_WAIT_L(n) asm volatile("s_waitcnt lgkmcnt(" #n ")" ::: "memory")
; #define PG8_BAR __builtin_amdgcn_s_barrier()
; #define PG8_SCHED __builtin_amdgcn_sched_barrier(0)
; template <class Epi, class Sched, bool ALIGN_EPI = false, bool SP2 = false, bool TWOA = false, bool AGM = false>
; __device__ __forceinline__ void gemm_phase(LAS unsigned char* lds, const Gemm g, const Sched& S, const Epi& E, int wid) {
;     ...
;             PG8_LDB(B0, 1, 0); PG8_LDB(B1, 1, 1); PG8_SCHED; PG8_LDA(At, 1, 0); PG8_STAGE(PG8_SA(0, 1), a2 + hstepA, voffA);
;             PG8_WAIT_V(8); PG8_WAIT_L(0); PG8_BAR; PG8_MMA(0, 0, At, B0); PG8_MMA(0, 1, At, B1); PG8_BAR; PG8_SCHED;
;             PG8_LDA(At, 1, 1); PG8_STAGE(PG8_SB(1, 0), b3, voffB); PG8_STAGE(PG8_SB(1, 1), b3 + hstep, voffB); PG8_STAGE(PG8_SA(1, 0), a3, voffA);
;             PG8_WAIT_V(8); PG8_WAIT_L(0); PG8_BAR; PG8_MMA(1, 0, At, B0); PG8_MMA(1, 1, At, B1); PG8_BAR; PG8_SCHED;
;     ...
;         if constexpr (ALIGN_EPI) { if (wr == 0) PG8_BAR; }
	s_add_i32 s71, 0, 0x18000
	v_add_u32_e32 v136, s71, v153
	s_add_i32 s72, 0, 0x1c000
	ds_read_b128 v[146:149], v136
	ds_read_b128 v[160:163], v136 offset:1024
	ds_read_b128 v[164:167], v136 offset:2048
	ds_read_b128 v[168:171], v136 offset:3072
	v_add_u32_e32 v136, s72, v153
	ds_read_b128 v[172:175], v136
	ds_read_b128 v[176:179], v136 offset:1024
	ds_read_b128 v[180:183], v136 offset:2048
	ds_read_b128 v[184:187], v136 offset:3072
	s_add_u32 s34, s66, 0x100000
	s_addc_u32 s35, s67, 0
	s_mov_b32 m0, s81
	ds_read_b128 v[188:191], v157 offset:32768
	ds_read_b128 v[192:195], v157 offset:33792
	ds_read_b128 v[196:199], v157 offset:34816
	ds_read_b128 v[200:203], v157 offset:35840
	ds_read_b128 v[204:207], v157 offset:36864
	ds_read_b128 v[208:211], v157 offset:37888
	ds_read_b128 v[212:215], v157 offset:38912
	ds_read_b128 v[216:219], v157 offset:39936
	global_load_lds_dwordx4 v128, s[34:35]
	s_mov_b32 m0, s82
	s_nop 0
	global_load_lds_dwordx4 v132, s[34:35]
	s_waitcnt vmcnt(8)
	s_waitcnt lgkmcnt(0)
	s_barrier
	s_setprio 1
	s_waitcnt lgkmcnt(0)
	v_mfma_f32_16x16x32_bf16 v[124:127], v[146:149], v[188:191], v[124:127]
	v_mfma_f32_16x16x32_bf16 v[120:123], v[164:167], v[188:191], v[120:123]
	v_mfma_f32_16x16x32_bf16 v[108:111], v[146:149], v[196:199], v[108:111]
	v_mfma_f32_16x16x32_bf16 v[104:107], v[164:167], v[196:199], v[104:107]
	v_mfma_f32_16x16x32_bf16 v[92:95], v[146:149], v[204:207], v[92:95]
	v_mfma_f32_16x16x32_bf16 v[88:91], v[164:167], v[204:207], v[88:91]
	v_mfma_f32_16x16x32_bf16 v[76:79], v[146:149], v[212:215], v[76:79]
	v_mfma_f32_16x16x32_bf16 v[72:75], v[164:167], v[212:215], v[72:75]
	s_setprio 0
	s_setprio 1
	v_mfma_f32_16x16x32_bf16 v[124:127], v[160:163], v[192:195], v[124:127]
	v_mfma_f32_16x16x32_bf16 v[120:123], v[168:171], v[192:195], v[120:123]
	v_mfma_f32_16x16x32_bf16 v[108:111], v[160:163], v[200:203], v[108:111]
	v_mfma_f32_16x16x32_bf16 v[104:107], v[168:171], v[200:203], v[104:107]
	v_mfma_f32_16x16x32_bf16 v[92:95], v[160:163], v[208:211], v[92:95]
	v_mfma_f32_16x16x32_bf16 v[88:91], v[168:171], v[208:211], v[88:91]
	v_mfma_f32_16x16x32_bf16 v[76:79], v[160:163], v[216:219], v[76:79]
	v_mfma_f32_16x16x32_bf16 v[72:75], v[168:171], v[216:219], v[72:75]
	s_setprio 0
	s_setprio 1
	v_mfma_f32_16x16x32_bf16 v[116:119], v[172:175], v[188:191], v[116:119]
	v_mfma_f32_16x16x32_bf16 v[112:115], v[180:183], v[188:191], v[112:115]
	v_mfma_f32_16x16x32_bf16 v[100:103], v[172:175], v[196:199], v[100:103]
	v_mfma_f32_16x16x32_bf16 v[96:99], v[180:183], v[196:199], v[96:99]
	v_mfma_f32_16x16x32_bf16 v[84:87], v[172:175], v[204:207], v[84:87]
	v_mfma_f32_16x16x32_bf16 v[80:83], v[180:183], v[204:207], v[80:83]
	v_mfma_f32_16x16x32_bf16 v[68:71], v[172:175], v[212:215], v[68:71]
	v_mfma_f32_16x16x32_bf16 v[64:67], v[180:183], v[212:215], v[64:67]
	s_setprio 0
	s_setprio 1
	v_mfma_f32_16x16x32_bf16 v[116:119], v[176:179], v[192:195], v[116:119]
	v_mfma_f32_16x16x32_bf16 v[112:115], v[184:187], v[192:195], v[112:115]
	v_mfma_f32_16x16x32_bf16 v[100:103], v[176:179], v[200:203], v[100:103]
	v_mfma_f32_16x16x32_bf16 v[96:99], v[184:187], v[200:203], v[96:99]
	v_mfma_f32_16x16x32_bf16 v[84:87], v[176:179], v[208:211], v[84:87]
	v_mfma_f32_16x16x32_bf16 v[80:83], v[184:187], v[208:211], v[80:83]
	v_mfma_f32_16x16x32_bf16 v[68:71], v[176:179], v[216:219], v[68:71]
	v_mfma_f32_16x16x32_bf16 v[64:67], v[184:187], v[216:219], v[64:67]
	s_setprio 0
	s_barrier
	s_add_i32 s34, s71, s75
	s_add_u32 s98, s12, s46
	s_addc_u32 s99, s13, s47
	s_mov_b32 m0, s34
	ds_read_b128 v[188:191], v157 offset:49152
	ds_read_b128 v[192:195], v157 offset:50176
	ds_read_b128 v[196:199], v157 offset:51200
	ds_read_b128 v[200:203], v157 offset:52224
	ds_read_b128 v[204:207], v157 offset:53248
	ds_read_b128 v[208:211], v157 offset:54272
	ds_read_b128 v[212:215], v157 offset:55296
	ds_read_b128 v[216:219], v157 offset:56320
	global_load_lds_dwordx4 v130, s[98:99]
	s_add_i32 m0, s34, 0x2000
	s_add_u32 s12, s12, 0x100080
	s_addc_u32 s13, s13, 0
	s_add_i32 s34, s72, s75
	global_load_lds_dwordx4 v134, s[98:99]
	s_mov_b32 m0, s34
	s_nop 0
	global_load_lds_dwordx4 v130, s[12:13]
	s_add_i32 m0, s34, 0x2000
	s_nop 0
	global_load_lds_dwordx4 v134, s[12:13]
	s_add_u32 s100, s66, s46
	s_addc_u32 s101, s67, s47
	s_mov_b32 m0, s88
	s_nop 0
	global_load_lds_dwordx4 v128, s[100:101]
	s_mov_b32 m0, s89
	s_nop 0
	global_load_lds_dwordx4 v132, s[100:101]
	s_waitcnt vmcnt(8)
	s_waitcnt lgkmcnt(0)
	s_barrier
	s_setprio 1
	s_waitcnt lgkmcnt(0)
	v_mfma_f32_16x16x32_bf16 v[60:63], v[146:149], v[188:191], v[60:63]
	v_mfma_f32_16x16x32_bf16 v[56:59], v[164:167], v[188:191], v[56:59]
	v_mfma_f32_16x16x32_bf16 v[44:47], v[146:149], v[196:199], v[44:47]
	v_mfma_f32_16x16x32_bf16 v[40:43], v[164:167], v[196:199], v[40:43]
	v_mfma_f32_16x16x32_bf16 v[28:31], v[146:149], v[204:207], v[28:31]
	v_mfma_f32_16x16x32_bf16 v[24:27], v[164:167], v[204:207], v[24:27]
	v_mfma_f32_16x16x32_bf16 v[12:15], v[146:149], v[212:215], v[12:15]
	v_mfma_f32_16x16x32_bf16 v[8:11], v[164:167], v[212:215], v[8:11]
	s_setprio 0
	s_setprio 1
	v_mfma_f32_16x16x32_bf16 v[60:63], v[160:163], v[192:195], v[60:63]
	v_mfma_f32_16x16x32_bf16 v[56:59], v[168:171], v[192:195], v[56:59]
	v_mfma_f32_16x16x32_bf16 v[44:47], v[160:163], v[200:203], v[44:47]
	v_mfma_f32_16x16x32_bf16 v[40:43], v[168:171], v[200:203], v[40:43]
	v_mfma_f32_16x16x32_bf16 v[28:31], v[160:163], v[208:211], v[28:31]
	v_mfma_f32_16x16x32_bf16 v[24:27], v[168:171], v[208:211], v[24:27]
	v_mfma_f32_16x16x32_bf16 v[12:15], v[160:163], v[216:219], v[12:15]
	v_mfma_f32_16x16x32_bf16 v[8:11], v[168:171], v[216:219], v[8:11]
	s_setprio 0
	s_setprio 1
	v_mfma_f32_16x16x32_bf16 v[52:55], v[172:175], v[188:191], v[52:55]
	v_mfma_f32_16x16x32_bf16 v[48:51], v[180:183], v[188:191], v[48:51]
	v_mfma_f32_16x16x32_bf16 v[36:39], v[172:175], v[196:199], v[36:39]
	v_mfma_f32_16x16x32_bf16 v[32:35], v[180:183], v[196:199], v[32:35]
	v_mfma_f32_16x16x32_bf16 v[20:23], v[172:175], v[204:207], v[20:23]
	v_mfma_f32_16x16x32_bf16 v[16:19], v[180:183], v[204:207], v[16:19]
	v_mfma_f32_16x16x32_bf16 v[4:7], v[172:175], v[212:215], v[4:7]
	v_mfma_f32_16x16x32_bf16 v[0:3], v[180:183], v[212:215], v[0:3]
	s_setprio 0
	s_setprio 1
	v_mfma_f32_16x16x32_bf16 v[52:55], v[176:179], v[192:195], v[52:55]
	v_mfma_f32_16x16x32_bf16 v[48:51], v[184:187], v[192:195], v[48:51]
	v_mfma_f32_16x16x32_bf16 v[36:39], v[176:179], v[200:203], v[36:39]
	v_mfma_f32_16x16x32_bf16 v[32:35], v[184:187], v[200:203], v[32:35]
	v_mfma_f32_16x16x32_bf16 v[20:23], v[176:179], v[208:211], v[20:23]
	v_mfma_f32_16x16x32_bf16 v[16:19], v[184:187], v[208:211], v[16:19]
	v_mfma_f32_16x16x32_bf16 v[4:7], v[176:179], v[216:219], v[4:7]
	v_mfma_f32_16x16x32_bf16 v[0:3], v[184:187], v[216:219], v[0:3]
	s_setprio 0
	s_barrier
	s_add_i32 s70, s70, 2
	s_add_u32 s10, s10, 0x100
	s_addc_u32 s11, s11, 0
	s_add_u32 s68, s68, 0x100
	s_addc_u32 s69, s69, 0
	s_cmp_gt_u32 s70, 61
	s_cbranch_scc0 .LBB0_230
	s_and_b64 vcc, exec, s[50:51]
	s_cbranch_vccz .LBB0_233
	s_barrier

; #define PG8_STAGE(bufoff, gbase, voff) do { _Pragma("unroll") for (int _i = 0; _i < 2; ++_i) \
;         __builtin_amdgcn_global_load_lds((const unsigned*)((const char*)(gbase) + (voff)[_i]), (LAS unsigned*)(lds + (bufoff) + ldsw + _i * 8192), 16, 0, 0); } while (0)
; #define PG8_LDA(dst, b, h) do { _Pragma("unroll") for (int m = 0; m < 4; ++m) _Pragma("unroll") for (int k = 0; k < 2; ++k) dst[m][k] = *(const LAS bf16x8*)(lds + PG8_SA(b, h) + aoff + m * 2048 + k * 1024); } while (0)
; #define PG8_LDB(dst, b, h) do { _Pragma("unroll") for (int n = 0; n < 2; ++n) _Pragma("unroll") for (int k = 0; k < 2; ++k) dst[n][k] = *(const LAS bf16x8*)(lds + PG8_SB(b, h) + boff + n * 2048 + k * 1024); } while (0)
; #define PG8_MMA(ai, bj, At, Bt) do { __builtin_amdgcn_s_setprio(1); _Pragma("unroll") for (int m = 0; m < 4; ++m) _Pragma("unroll") for (int n = 0; n < 2; ++n) _Pragma("unroll") for (int k = 0; k < 2; ++k) \
;         acc[ai][bj][m][n] = __builtin_amdgcn_mfma_f32_16x16x32_bf16(Bt[n][k], At[m][k], acc[ai][bj][m][n], 0, 0, 0); __builtin_amdgcn_s_setprio(0); } while (0)
; #define PG8_WAIT_V(n) asm volatile("s_waitcnt vmcnt(" #n ")" ::: "memory")
; #define PG8_WAIT_L(n) asm volatile("s_waitcnt lgkmcnt(" #n ")" ::: "memory")
; #define PG8_BAR __builtin_amdgcn_s_barrier()
; #define PG8_SCHED __builtin_amdgcn_sched_barrier(0)
; template <class Epi, class Sched, bool ALIGN_EPI = false, bool SP2 = false, bool TWOA = false, bool AGM = false>
; __device__ __forceinline__ void gemm_phase(LAS unsigned char* lds, const Gemm g, const Sched& S, const Epi& E, int wid) {
;     ...
;     const char* cA = (const char*)g.A + (size_t)cur.pm * tstepA; const char* cB = (const char*)g.Bt + (size_t)cur.pn * tstep;
;     ...
;             if constexpr (SP2) {
;             PG8_LDB(B0, 0, 0); PG8_LDB(B1, 0, 1); PG8_SCHED; PG8_LDA(At, 0, 0); PG8_STAGE(PG8_SA(1, 1), a1 + hstepA, voffA);
;             PG8_WAIT_V(8); PG8_WAIT_L(0); PG8_BAR; PG8_MMA(0, 0, At, B0); PG8_MMA(0, 1, At, B1); PG8_BAR; PG8_SCHED;
;             PG8_LDA(At, 0, 1); PG8_STAGE(PG8_SB(0, 0), b2, voffB); PG8_STAGE(PG8_SB(0, 1), b2 + hstep, voffB); PG8_STAGE(PG8_SA(0, 0), a2, voffA);
;             PG8_WAIT_V(8); PG8_WAIT_L(0); PG8_BAR; PG8_MMA(1, 0, At, B0); PG8_MMA(1, 1, At, B1); PG8_BAR; PG8_SCHED;
.LBB0_523:
	ds_read_b128 v[0:3], v137
	ds_read_b128 v[4:7], v137 offset:1024
	ds_read_b128 v[8:11], v137 offset:2048
	ds_read_b128 v[12:15], v137 offset:3072
	ds_read_b128 v[16:19], v138
	ds_read_b128 v[20:23], v138 offset:1024
	ds_read_b128 v[24:27], v138 offset:2048
	ds_read_b128 v[28:31], v138 offset:3072
	s_ashr_i32 s27, s26, 31
	s_lshl_b64 s[30:31], s[26:27], 17
	s_add_u32 s30, s3, s30
	s_addc_u32 s31, s50, s31
	s_and_b64 s[34:35], s[36:37], exec
	s_cselect_b32 s47, s31, s41
	s_cselect_b32 s46, s30, s40
	s_ashr_i32 s25, s24, 31
	s_lshl_b64 s[34:35], s[24:25], 17
	s_add_u32 s38, s51, s34
	s_addc_u32 s39, s52, s35
	s_and_b64 s[34:35], s[36:37], exec
	s_cselect_b32 s43, s39, s45
	s_cselect_b32 s42, s38, s44
	s_add_u32 s34, s40, 0x10080
	s_addc_u32 s35, s41, 0
	s_mov_b32 m0, s66
	v_lshl_add_u64 v[64:65], s[34:35], 0, v[134:135]
	ds_read_b128 v[32:35], v139
	ds_read_b128 v[36:39], v139 offset:1024
	ds_read_b128 v[40:43], v139 offset:2048
	ds_read_b128 v[44:47], v139 offset:3072
	ds_read_b128 v[48:51], v139 offset:4096
	ds_read_b128 v[52:55], v139 offset:5120
	ds_read_b128 v[56:59], v139 offset:6144
	ds_read_b128 v[60:63], v139 offset:7168
	global_load_lds_dwordx4 v[64:65], off
	v_lshl_add_u64 v[64:65], s[34:35], 0, v[130:131]
	s_mov_b32 m0, s67
	s_nop 0
	global_load_lds_dwordx4 v[64:65], off
	s_waitcnt vmcnt(8)
	s_waitcnt lgkmcnt(0)
	s_barrier
	s_setprio 1
	s_waitcnt lgkmcnt(0)
	v_mfma_f32_16x16x32_bf16 v[64:67], v[0:3], v[32:35], 0
	v_mfma_f32_16x16x32_bf16 v[68:71], v[8:11], v[32:35], 0
	v_mfma_f32_16x16x32_bf16 v[72:75], v[0:3], v[40:43], 0
	v_mfma_f32_16x16x32_bf16 v[76:79], v[8:11], v[40:43], 0
	v_mfma_f32_16x16x32_bf16 v[80:83], v[0:3], v[48:51], 0
	v_mfma_f32_16x16x32_bf16 v[84:87], v[8:11], v[48:51], 0
	v_mfma_f32_16x16x32_bf16 v[88:91], v[0:3], v[56:59], 0
	v_mfma_f32_16x16x32_bf16 v[92:95], v[8:11], v[56:59], 0
	s_setprio 0
	s_setprio 1
	v_mfma_f32_16x16x32_bf16 v[64:67], v[4:7], v[36:39], v[64:67]
	v_mfma_f32_16x16x32_bf16 v[68:71], v[12:15], v[36:39], v[68:71]
	v_mfma_f32_16x16x32_bf16 v[72:75], v[4:7], v[44:47], v[72:75]
	v_mfma_f32_16x16x32_bf16 v[76:79], v[12:15], v[44:47], v[76:79]
	v_mfma_f32_16x16x32_bf16 v[80:83], v[4:7], v[52:55], v[80:83]
	v_mfma_f32_16x16x32_bf16 v[84:87], v[12:15], v[52:55], v[84:87]
	v_mfma_f32_16x16x32_bf16 v[88:91], v[4:7], v[60:63], v[88:91]
	v_mfma_f32_16x16x32_bf16 v[92:95], v[12:15], v[60:63], v[92:95]
	s_setprio 0
	s_setprio 1
	v_mfma_f32_16x16x32_bf16 v[96:99], v[16:19], v[32:35], 0
	v_mfma_f32_16x16x32_bf16 v[32:35], v[24:27], v[32:35], 0
	v_mfma_f32_16x16x32_bf16 v[96:99], v[20:23], v[36:39], v[96:99]
	v_mfma_f32_16x16x32_bf16 v[32:35], v[28:31], v[36:39], v[32:35]
	v_mfma_f32_16x16x32_bf16 v[36:39], v[16:19], v[40:43], 0
	v_mfma_f32_16x16x32_bf16 v[40:43], v[24:27], v[40:43], 0
	v_mfma_f32_16x16x32_bf16 v[36:39], v[20:23], v[44:47], v[36:39]
	v_mfma_f32_16x16x32_bf16 v[40:43], v[28:31], v[44:47], v[40:43]
	s_setprio 0
	s_setprio 1
	v_mfma_f32_16x16x32_bf16 v[44:47], v[16:19], v[48:51], 0
	v_mfma_f32_16x16x32_bf16 v[48:51], v[24:27], v[48:51], 0
	v_mfma_f32_16x16x32_bf16 v[44:47], v[20:23], v[52:55], v[44:47]
	v_mfma_f32_16x16x32_bf16 v[48:51], v[28:31], v[52:55], v[48:51]
	v_mfma_f32_16x16x32_bf16 v[52:55], v[16:19], v[56:59], 0
	v_mfma_f32_16x16x32_bf16 v[56:59], v[24:27], v[56:59], 0
	v_mfma_f32_16x16x32_bf16 v[52:55], v[20:23], v[60:63], v[52:55]
	v_mfma_f32_16x16x32_bf16 v[56:59], v[28:31], v[60:63], v[56:59]
	s_setprio 0
	s_barrier
	v_lshl_add_u64 v[206:207], s[44:45], 0, v[132:133]
	s_mov_b32 m0, s68
	v_lshl_add_u64 v[142:143], v[206:207], 0, s[20:21]
	v_lshl_add_u64 v[208:209], s[44:45], 0, v[128:129]
	s_add_u32 s34, s44, 0x10100
	ds_read_b128 v[60:63], v139 offset:16384
	ds_read_b128 v[100:103], v139 offset:17408
	ds_read_b128 v[104:107], v139 offset:18432
	ds_read_b128 v[108:111], v139 offset:19456
	ds_read_b128 v[112:115], v139 offset:20480
	ds_read_b128 v[116:119], v139 offset:21504
	ds_read_b128 v[120:123], v139 offset:22528
	ds_read_b128 v[124:127], v139 offset:23552
	global_load_lds_dwordx4 v[142:143], off
	v_lshl_add_u64 v[142:143], v[208:209], 0, s[20:21]
	s_mov_b32 m0, s69
	s_addc_u32 s35, s45, 0
	global_load_lds_dwordx4 v[142:143], off
	v_lshl_add_u64 v[142:143], s[34:35], 0, v[132:133]
	s_mov_b32 m0, s70
	v_lshl_add_u64 v[210:211], s[40:41], 0, v[134:135]
	global_load_lds_dwordx4 v[142:143], off
	v_lshl_add_u64 v[142:143], s[34:35], 0, v[128:129]
	s_mov_b32 m0, s71
	v_lshl_add_u64 v[212:213], s[40:41], 0, v[130:131]
	global_load_lds_dwordx4 v[142:143], off
	v_lshl_add_u64 v[142:143], v[210:211], 0, s[20:21]
	s_mov_b32 m0, s53
	s_nop 0
	global_load_lds_dwordx4 v[142:143], off
	v_lshl_add_u64 v[142:143], v[212:213], 0, s[20:21]
	s_mov_b32 m0, s54
	s_nop 0
	global_load_lds_dwordx4 v[142:143], off
	s_waitcnt vmcnt(8)
	s_waitcnt lgkmcnt(0)
	s_barrier
; #define PG8_STAGE(bufoff, gbase, voff) do { _Pragma("unroll") for (int _i = 0; _i < 2; ++_i) \
;         __builtin_amdgcn_global_load_lds((const unsigned*)((const char*)(gbase) + (voff)[_i]), (LAS unsigned*)(lds + (bufoff) + ldsw + _i * 8192), 16, 0, 0); } while (0)
; #define PG8_LDA(dst, b, h) do { _Pragma("unroll") for (int m = 0; m < 4; ++m) _Pragma("unroll") for (int k = 0; k < 2; ++k) dst[m][k] = *(const LAS bf16x8*)(lds + PG8_SA(b, h) + aoff + m * 2048 + k * 1024); } while (0)
; #define PG8_LDB(dst, b, h) do { _Pragma("unroll") for (int n = 0; n < 2; ++n) _Pragma("unroll") for (int k = 0; k < 2; ++k) dst[n][k] = *(const LAS bf16x8*)(lds + PG8_SB(b, h) + boff + n * 2048 + k * 1024); } while (0)
; #define PG8_MMA(ai, bj, At, Bt) do { __builtin_amdgcn_s_setprio(1); _Pragma("unroll") for (int m = 0; m < 4; ++m) _Pragma("unroll") for (int n = 0; n < 2; ++n) _Pragma("unroll") for (int k = 0; k < 2; ++k) \
;         acc[ai][bj][m][n] = __builtin_amdgcn_mfma_f32_16x16x32_bf16(Bt[n][k], At[m][k], acc[ai][bj][m][n], 0, 0, 0); __builtin_amdgcn_s_setprio(0); } while (0)
; #define PG8_WAIT_V(n) asm volatile("s_waitcnt vmcnt(" #n ")" ::: "memory")
; #define PG8_WAIT_L(n) asm volatile("s_waitcnt lgkmcnt(" #n ")" ::: "memory")
; #define PG8_BAR __builtin_amdgcn_s_barrier()
; #define PG8_SCHED __builtin_amdgcn_sched_barrier(0)
; template <class Epi, class Sched, bool ALIGN_EPI = false, bool SP2 = false, bool TWOA = false, bool AGM = false>
; __device__ __forceinline__ void gemm_phase(LAS unsigned char* lds, const Gemm g, const Sched& S, const Epi& E, int wid) {
;     ...
;             PG8_WAIT_V(8); PG8_WAIT_L(0); PG8_BAR; PG8_MMA(1, 0, At, B0); PG8_MMA(1, 1, At, B1); PG8_BAR; PG8_SCHED;
;             PG8_LDB(B0, 1, 0); PG8_LDB(B1, 1, 1); PG8_SCHED; PG8_LDA(At, 1, 0); PG8_STAGE(PG8_SA(0, 1), a2 + hstepA, voffA);
;             PG8_WAIT_V(8); PG8_WAIT_L(0); PG8_BAR; PG8_MMA(0, 0, At, B0); PG8_MMA(0, 1, At, B1); PG8_BAR; PG8_SCHED;
;             PG8_LDA(At, 1, 1); PG8_STAGE(PG8_SB(1, 0), b3, voffB); PG8_STAGE(PG8_SB(1, 1), b3 + hstep, voffB); PG8_STAGE(PG8_SA(1, 0), a3, voffA);
;             PG8_WAIT_V(8); PG8_WAIT_L(0); PG8_BAR; PG8_MMA(1, 0, At, B0); PG8_MMA(1, 1, At, B1); PG8_BAR; PG8_SCHED;
	s_setprio 1
	s_waitcnt lgkmcnt(0)
	v_mfma_f32_16x16x32_bf16 v[142:145], v[0:3], v[60:63], 0
	v_mfma_f32_16x16x32_bf16 v[150:153], v[0:3], v[104:107], 0
	v_mfma_f32_16x16x32_bf16 v[158:161], v[0:3], v[112:115], 0
	v_mfma_f32_16x16x32_bf16 v[0:3], v[0:3], v[120:123], 0
	v_mfma_f32_16x16x32_bf16 v[142:145], v[4:7], v[100:103], v[142:145]
	v_mfma_f32_16x16x32_bf16 v[150:153], v[4:7], v[108:111], v[150:153]
	v_mfma_f32_16x16x32_bf16 v[158:161], v[4:7], v[116:119], v[158:161]
	v_mfma_f32_16x16x32_bf16 v[0:3], v[4:7], v[124:127], v[0:3]
	s_setprio 0
	s_setprio 1
	v_mfma_f32_16x16x32_bf16 v[4:7], v[8:11], v[120:123], 0
	v_mfma_f32_16x16x32_bf16 v[146:149], v[8:11], v[60:63], 0
	v_mfma_f32_16x16x32_bf16 v[154:157], v[8:11], v[104:107], 0
	v_mfma_f32_16x16x32_bf16 v[162:165], v[8:11], v[112:115], 0
	v_mfma_f32_16x16x32_bf16 v[4:7], v[12:15], v[124:127], v[4:7]
	v_mfma_f32_16x16x32_bf16 v[146:149], v[12:15], v[100:103], v[146:149]
	v_mfma_f32_16x16x32_bf16 v[154:157], v[12:15], v[108:111], v[154:157]
	v_mfma_f32_16x16x32_bf16 v[162:165], v[12:15], v[116:119], v[162:165]
	s_setprio 0
	s_setprio 1
	v_mfma_f32_16x16x32_bf16 v[8:11], v[16:19], v[60:63], 0
	v_mfma_f32_16x16x32_bf16 v[12:15], v[24:27], v[60:63], 0
	v_mfma_f32_16x16x32_bf16 v[8:11], v[20:23], v[100:103], v[8:11]
	v_mfma_f32_16x16x32_bf16 v[12:15], v[28:31], v[100:103], v[12:15]
	v_mfma_f32_16x16x32_bf16 v[60:63], v[16:19], v[104:107], 0
	v_mfma_f32_16x16x32_bf16 v[100:103], v[24:27], v[104:107], 0
	v_mfma_f32_16x16x32_bf16 v[104:107], v[16:19], v[112:115], 0
	v_mfma_f32_16x16x32_bf16 v[16:19], v[16:19], v[120:123], 0
	s_setprio 0
	s_setprio 1
	v_mfma_f32_16x16x32_bf16 v[60:63], v[20:23], v[108:111], v[60:63]
	v_mfma_f32_16x16x32_bf16 v[100:103], v[28:31], v[108:111], v[100:103]
	v_mfma_f32_16x16x32_bf16 v[104:107], v[20:23], v[116:119], v[104:107]
	v_mfma_f32_16x16x32_bf16 v[108:111], v[24:27], v[112:115], 0
	v_mfma_f32_16x16x32_bf16 v[16:19], v[20:23], v[124:127], v[16:19]
	v_mfma_f32_16x16x32_bf16 v[20:23], v[24:27], v[120:123], 0
	v_mfma_f32_16x16x32_bf16 v[108:111], v[28:31], v[116:119], v[108:111]
	v_mfma_f32_16x16x32_bf16 v[20:23], v[28:31], v[124:127], v[20:23]
	s_setprio 0
	s_barrier
	ds_read_b128 v[24:27], v140
	ds_read_b128 v[28:31], v140 offset:1024
	ds_read_b128 v[112:115], v140 offset:2048
	ds_read_b128 v[116:119], v140 offset:3072
	ds_read_b128 v[120:123], v141
	ds_read_b128 v[124:127], v141 offset:1024
	ds_read_b128 v[166:169], v141 offset:2048
	ds_read_b128 v[170:173], v141 offset:3072
	s_add_u32 s34, s40, 0x10100
	s_addc_u32 s35, s41, 0
	s_mov_b32 m0, s55
	v_lshl_add_u64 v[214:215], s[34:35], 0, v[134:135]
	ds_read_b128 v[174:177], v139 offset:32768
	ds_read_b128 v[178:181], v139 offset:33792
	ds_read_b128 v[182:185], v139 offset:34816
	ds_read_b128 v[186:189], v139 offset:35840
	ds_read_b128 v[190:193], v139 offset:36864
	ds_read_b128 v[194:197], v139 offset:37888
	ds_read_b128 v[198:201], v139 offset:38912
	ds_read_b128 v[202:205], v139 offset:39936
	global_load_lds_dwordx4 v[214:215], off
	v_lshl_add_u64 v[214:215], s[34:35], 0, v[130:131]
	s_mov_b32 m0, s56
	s_nop 0
	global_load_lds_dwordx4 v[214:215], off
	s_waitcnt vmcnt(8)
	s_waitcnt lgkmcnt(0)
	s_barrier
	s_setprio 1
	s_waitcnt lgkmcnt(0)
	v_mfma_f32_16x16x32_bf16 v[64:67], v[24:27], v[174:177], v[64:67]
	v_mfma_f32_16x16x32_bf16 v[68:71], v[112:115], v[174:177], v[68:71]
	v_mfma_f32_16x16x32_bf16 v[72:75], v[24:27], v[182:185], v[72:75]
	v_mfma_f32_16x16x32_bf16 v[76:79], v[112:115], v[182:185], v[76:79]
	v_mfma_f32_16x16x32_bf16 v[80:83], v[24:27], v[190:193], v[80:83]
	v_mfma_f32_16x16x32_bf16 v[84:87], v[112:115], v[190:193], v[84:87]
	v_mfma_f32_16x16x32_bf16 v[88:91], v[24:27], v[198:201], v[88:91]
	v_mfma_f32_16x16x32_bf16 v[92:95], v[112:115], v[198:201], v[92:95]
	s_setprio 0
	s_setprio 1
	v_mfma_f32_16x16x32_bf16 v[64:67], v[28:31], v[178:181], v[64:67]
	v_mfma_f32_16x16x32_bf16 v[68:71], v[116:119], v[178:181], v[68:71]
	v_mfma_f32_16x16x32_bf16 v[72:75], v[28:31], v[186:189], v[72:75]
	v_mfma_f32_16x16x32_bf16 v[76:79], v[116:119], v[186:189], v[76:79]
	v_mfma_f32_16x16x32_bf16 v[80:83], v[28:31], v[194:197], v[80:83]
	v_mfma_f32_16x16x32_bf16 v[84:87], v[116:119], v[194:197], v[84:87]
	v_mfma_f32_16x16x32_bf16 v[88:91], v[28:31], v[202:205], v[88:91]
	v_mfma_f32_16x16x32_bf16 v[92:95], v[116:119], v[202:205], v[92:95]
	s_setprio 0
	s_setprio 1
	v_mfma_f32_16x16x32_bf16 v[96:99], v[120:123], v[174:177], v[96:99]
	v_mfma_f32_16x16x32_bf16 v[32:35], v[166:169], v[174:177], v[32:35]
	v_mfma_f32_16x16x32_bf16 v[36:39], v[120:123], v[182:185], v[36:39]
	v_mfma_f32_16x16x32_bf16 v[40:43], v[166:169], v[182:185], v[40:43]
	v_mfma_f32_16x16x32_bf16 v[44:47], v[120:123], v[190:193], v[44:47]
	v_mfma_f32_16x16x32_bf16 v[48:51], v[166:169], v[190:193], v[48:51]
	v_mfma_f32_16x16x32_bf16 v[52:55], v[120:123], v[198:201], v[52:55]
	v_mfma_f32_16x16x32_bf16 v[56:59], v[166:169], v[198:201], v[56:59]
	s_setprio 0
	s_setprio 1
	v_mfma_f32_16x16x32_bf16 v[96:99], v[124:127], v[178:181], v[96:99]
	v_mfma_f32_16x16x32_bf16 v[32:35], v[170:173], v[178:181], v[32:35]
	v_mfma_f32_16x16x32_bf16 v[36:39], v[124:127], v[186:189], v[36:39]
	v_mfma_f32_16x16x32_bf16 v[40:43], v[170:173], v[186:189], v[40:43]
	v_mfma_f32_16x16x32_bf16 v[44:47], v[124:127], v[194:197], v[44:47]
	v_mfma_f32_16x16x32_bf16 v[48:51], v[170:173], v[194:197], v[48:51]
	v_mfma_f32_16x16x32_bf16 v[52:55], v[124:127], v[202:205], v[52:55]
	v_mfma_f32_16x16x32_bf16 v[56:59], v[170:173], v[202:205], v[56:59]
	s_setprio 0
	s_barrier
; #define PG8_STAGE(bufoff, gbase, voff) do { _Pragma("unroll") for (int _i = 0; _i < 2; ++_i) \
;         __builtin_amdgcn_global_load_lds((const unsigned*)((const char*)(gbase) + (voff)[_i]), (LAS unsigned*)(lds + (bufoff) + ldsw + _i * 8192), 16, 0, 0); } while (0)
; #define PG8_LDA(dst, b, h) do { _Pragma("unroll") for (int m = 0; m < 4; ++m) _Pragma("unroll") for (int k = 0; k < 2; ++k) dst[m][k] = *(const LAS bf16x8*)(lds + PG8_SA(b, h) + aoff + m * 2048 + k * 1024); } while (0)
; #define PG8_LDB(dst, b, h) do { _Pragma("unroll") for (int n = 0; n < 2; ++n) _Pragma("unroll") for (int k = 0; k < 2; ++k) dst[n][k] = *(const LAS bf16x8*)(lds + PG8_SB(b, h) + boff + n * 2048 + k * 1024); } while (0)
; #define PG8_MMA(ai, bj, At, Bt) do { __builtin_amdgcn_s_setprio(1); _Pragma("unroll") for (int m = 0; m < 4; ++m) _Pragma("unroll") for (int n = 0; n < 2; ++n) _Pragma("unroll") for (int k = 0; k < 2; ++k) \
;         acc[ai][bj][m][n] = __builtin_amdgcn_mfma_f32_16x16x32_bf16(Bt[n][k], At[m][k], acc[ai][bj][m][n], 0, 0, 0); __builtin_amdgcn_s_setprio(0); } while (0)
; #define PG8_WAIT_V(n) asm volatile("s_waitcnt vmcnt(" #n ")" ::: "memory")
; #define PG8_WAIT_L(n) asm volatile("s_waitcnt lgkmcnt(" #n ")" ::: "memory")
; #define PG8_BAR __builtin_amdgcn_s_barrier()
; #define PG8_SCHED __builtin_amdgcn_sched_barrier(0)
; template <class Epi, class Sched, bool ALIGN_EPI = false, bool SP2 = false, bool TWOA = false, bool AGM = false>
; __device__ __forceinline__ void gemm_phase(LAS unsigned char* lds, const Gemm g, const Sched& S, const Epi& E, int wid) {
;     ...
;             PG8_LDB(B0, 0, 0); PG8_LDB(B1, 0, 1); PG8_SCHED; PG8_LDA(At, 0, 0); PG8_STAGE(PG8_SA(1, 1), a1 + hstepA, voffA);
;             PG8_WAIT_V(8); PG8_WAIT_L(0); PG8_BAR; PG8_MMA(0, 0, At, B0); PG8_MMA(0, 1, At, B1); PG8_BAR; PG8_SCHED;
;     ...
;             PG8_LDA(At, 1, 1); PG8_STAGE(PG8_SB(1, 0), b3, voffB); PG8_STAGE(PG8_SB(1, 1), b3 + hstep, voffB); PG8_STAGE(PG8_SA(1, 0), a3, voffA);
;             PG8_WAIT_V(8); PG8_WAIT_L(0); PG8_BAR; PG8_MMA(1, 0, At, B0); PG8_MMA(1, 1, At, B1); PG8_BAR; PG8_SCHED;
	s_mov_b32 m0, s72
	v_lshl_add_u64 v[206:207], v[206:207], 0, s[22:23]
	s_add_u32 s34, s44, 0x10180
	ds_read_b128 v[174:177], v139 offset:49152
	ds_read_b128 v[178:181], v139 offset:50176
	ds_read_b128 v[182:185], v139 offset:51200
	ds_read_b128 v[186:189], v139 offset:52224
	ds_read_b128 v[190:193], v139 offset:53248
	ds_read_b128 v[194:197], v139 offset:54272
	ds_read_b128 v[198:201], v139 offset:55296
	ds_read_b128 v[202:205], v139 offset:56320
	global_load_lds_dwordx4 v[206:207], off
	v_lshl_add_u64 v[206:207], v[208:209], 0, s[22:23]
	s_mov_b32 m0, s73
	s_addc_u32 s35, s45, 0
	global_load_lds_dwordx4 v[206:207], off
	v_lshl_add_u64 v[206:207], s[34:35], 0, v[132:133]
	s_mov_b32 m0, s74
	s_nop 0
	global_load_lds_dwordx4 v[206:207], off
	v_lshl_add_u64 v[206:207], s[34:35], 0, v[128:129]
	s_mov_b32 m0, s75
	s_nop 0
	global_load_lds_dwordx4 v[206:207], off
	v_lshl_add_u64 v[206:207], v[210:211], 0, s[22:23]
	s_mov_b32 m0, s57
	s_nop 0
	global_load_lds_dwordx4 v[206:207], off
	v_lshl_add_u64 v[206:207], v[212:213], 0, s[22:23]
	s_mov_b32 m0, s64
	s_nop 0
	global_load_lds_dwordx4 v[206:207], off
	s_waitcnt vmcnt(8)
	s_waitcnt lgkmcnt(0)
	s_barrier
	s_setprio 1
	s_waitcnt lgkmcnt(0)
	v_mfma_f32_16x16x32_bf16 v[0:3], v[24:27], v[198:201], v[0:3]
	v_mfma_f32_16x16x32_bf16 v[4:7], v[112:115], v[198:201], v[4:7]
	v_mfma_f32_16x16x32_bf16 v[142:145], v[24:27], v[174:177], v[142:145]
	v_mfma_f32_16x16x32_bf16 v[146:149], v[112:115], v[174:177], v[146:149]
	v_mfma_f32_16x16x32_bf16 v[150:153], v[24:27], v[182:185], v[150:153]
	v_mfma_f32_16x16x32_bf16 v[154:157], v[112:115], v[182:185], v[154:157]
	v_mfma_f32_16x16x32_bf16 v[158:161], v[24:27], v[190:193], v[158:161]
	v_mfma_f32_16x16x32_bf16 v[162:165], v[112:115], v[190:193], v[162:165]
	s_setprio 0
	s_setprio 1
	v_mfma_f32_16x16x32_bf16 v[0:3], v[28:31], v[202:205], v[0:3]
	v_mfma_f32_16x16x32_bf16 v[4:7], v[116:119], v[202:205], v[4:7]
	v_mfma_f32_16x16x32_bf16 v[142:145], v[28:31], v[178:181], v[142:145]
	v_mfma_f32_16x16x32_bf16 v[146:149], v[116:119], v[178:181], v[146:149]
	v_mfma_f32_16x16x32_bf16 v[150:153], v[28:31], v[186:189], v[150:153]
	v_mfma_f32_16x16x32_bf16 v[154:157], v[116:119], v[186:189], v[154:157]
	v_mfma_f32_16x16x32_bf16 v[158:161], v[28:31], v[194:197], v[158:161]
	v_mfma_f32_16x16x32_bf16 v[162:165], v[116:119], v[194:197], v[162:165]
	s_setprio 0
	s_setprio 1
	v_mfma_f32_16x16x32_bf16 v[8:11], v[120:123], v[174:177], v[8:11]
	v_mfma_f32_16x16x32_bf16 v[12:15], v[166:169], v[174:177], v[12:15]
	v_mfma_f32_16x16x32_bf16 v[24:27], v[120:123], v[182:185], v[60:63]
	v_mfma_f32_16x16x32_bf16 v[28:31], v[166:169], v[182:185], v[100:103]
	v_mfma_f32_16x16x32_bf16 v[60:63], v[120:123], v[190:193], v[104:107]
	v_mfma_f32_16x16x32_bf16 v[100:103], v[166:169], v[190:193], v[108:111]
	v_mfma_f32_16x16x32_bf16 v[16:19], v[120:123], v[198:201], v[16:19]
	v_mfma_f32_16x16x32_bf16 v[20:23], v[166:169], v[198:201], v[20:23]
	s_setprio 0
	s_setprio 1
	v_mfma_f32_16x16x32_bf16 v[8:11], v[124:127], v[178:181], v[8:11]
	v_mfma_f32_16x16x32_bf16 v[12:15], v[170:173], v[178:181], v[12:15]
	v_mfma_f32_16x16x32_bf16 v[24:27], v[124:127], v[186:189], v[24:27]
	v_mfma_f32_16x16x32_bf16 v[28:31], v[170:173], v[186:189], v[28:31]
	v_mfma_f32_16x16x32_bf16 v[60:63], v[124:127], v[194:197], v[60:63]
	v_mfma_f32_16x16x32_bf16 v[100:103], v[170:173], v[194:197], v[100:103]
	v_mfma_f32_16x16x32_bf16 v[16:19], v[124:127], v[202:205], v[16:19]
	v_mfma_f32_16x16x32_bf16 v[20:23], v[170:173], v[202:205], v[20:23]
	s_setprio 0
	s_barrier
	ds_read_b128 v[104:107], v137
	ds_read_b128 v[108:111], v137 offset:1024
	ds_read_b128 v[112:115], v137 offset:2048
	ds_read_b128 v[116:119], v137 offset:3072
	ds_read_b128 v[120:123], v138
	ds_read_b128 v[124:127], v138 offset:1024
	ds_read_b128 v[166:169], v138 offset:2048
	ds_read_b128 v[170:173], v138 offset:3072
	s_add_u32 s34, s40, 0x10180
	s_addc_u32 s35, s41, 0
	s_mov_b32 m0, s66
	v_lshl_add_u64 v[206:207], s[34:35], 0, v[134:135]
	ds_read_b128 v[174:177], v139
	ds_read_b128 v[178:181], v139 offset:1024
	ds_read_b128 v[182:185], v139 offset:2048
	ds_read_b128 v[186:189], v139 offset:3072
	ds_read_b128 v[190:193], v139 offset:4096
	ds_read_b128 v[194:197], v139 offset:5120
	ds_read_b128 v[198:201], v139 offset:6144
	ds_read_b128 v[202:205], v139 offset:7168
	global_load_lds_dwordx4 v[206:207], off
	v_lshl_add_u64 v[206:207], s[34:35], 0, v[130:131]
	s_mov_b32 m0, s67
	s_nop 0
	global_load_lds_dwordx4 v[206:207], off
	s_waitcnt vmcnt(8)
	s_waitcnt lgkmcnt(0)
	s_barrier
; #define PG8_STAGE(bufoff, gbase, voff) do { _Pragma("unroll") for (int _i = 0; _i < 2; ++_i) \
;         __builtin_amdgcn_global_load_lds((const unsigned*)((const char*)(gbase) + (voff)[_i]), (LAS unsigned*)(lds + (bufoff) + ldsw + _i * 8192), 16, 0, 0); } while (0)
; #define PG8_LDA(dst, b, h) do { _Pragma("unroll") for (int m = 0; m < 4; ++m) _Pragma("unroll") for (int k = 0; k < 2; ++k) dst[m][k] = *(const LAS bf16x8*)(lds + PG8_SA(b, h) + aoff + m * 2048 + k * 1024); } while (0)
; #define PG8_MMA(ai, bj, At, Bt) do { __builtin_amdgcn_s_setprio(1); _Pragma("unroll") for (int m = 0; m < 4; ++m) _Pragma("unroll") for (int n = 0; n < 2; ++n) _Pragma("unroll") for (int k = 0; k < 2; ++k) \
;         acc[ai][bj][m][n] = __builtin_amdgcn_mfma_f32_16x16x32_bf16(Bt[n][k], At[m][k], acc[ai][bj][m][n], 0, 0, 0); __builtin_amdgcn_s_setprio(0); } while (0)
; #define PG8_WAIT_V(n) asm volatile("s_waitcnt vmcnt(" #n ")" ::: "memory")
; #define PG8_WAIT_L(n) asm volatile("s_waitcnt lgkmcnt(" #n ")" ::: "memory")
; #define PG8_BAR __builtin_amdgcn_s_barrier()
; #define PG8_SCHED __builtin_amdgcn_sched_barrier(0)
; template <class Epi, class Sched, bool ALIGN_EPI = false, bool SP2 = false, bool TWOA = false, bool AGM = false>
; __device__ __forceinline__ void gemm_phase(LAS unsigned char* lds, const Gemm g, const Sched& S, const Epi& E, int wid) {
;     ...
;             PG8_WAIT_V(8); PG8_WAIT_L(0); PG8_BAR; PG8_MMA(0, 0, At, B0); PG8_MMA(0, 1, At, B1); PG8_BAR; PG8_SCHED;
;             PG8_LDA(At, 0, 1); PG8_STAGE(PG8_SB(0, 0), b2, voffB); PG8_STAGE(PG8_SB(0, 1), b2 + hstep, voffB); PG8_STAGE(PG8_SA(0, 0), a2, voffA);
;             PG8_WAIT_V(8); PG8_WAIT_L(0); PG8_BAR; PG8_MMA(1, 0, At, B0); PG8_MMA(1, 1, At, B1); PG8_BAR; PG8_SCHED;
	s_setprio 1
	s_waitcnt lgkmcnt(0)
	v_mfma_f32_16x16x32_bf16 v[88:91], v[104:107], v[198:201], v[88:91]
	v_mfma_f32_16x16x32_bf16 v[64:67], v[104:107], v[174:177], v[64:67]
	v_mfma_f32_16x16x32_bf16 v[68:71], v[112:115], v[174:177], v[68:71]
	v_mfma_f32_16x16x32_bf16 v[72:75], v[104:107], v[182:185], v[72:75]
	v_mfma_f32_16x16x32_bf16 v[76:79], v[112:115], v[182:185], v[76:79]
	v_mfma_f32_16x16x32_bf16 v[80:83], v[104:107], v[190:193], v[80:83]
	v_mfma_f32_16x16x32_bf16 v[84:87], v[112:115], v[190:193], v[84:87]
	v_mfma_f32_16x16x32_bf16 v[206:209], v[108:111], v[202:205], v[88:91]
	s_setprio 0
	s_setprio 1
	v_mfma_f32_16x16x32_bf16 v[88:91], v[112:115], v[198:201], v[92:95]
	v_mfma_f32_16x16x32_bf16 v[64:67], v[108:111], v[178:181], v[64:67]
	v_mfma_f32_16x16x32_bf16 v[68:71], v[116:119], v[178:181], v[68:71]
	v_mfma_f32_16x16x32_bf16 v[72:75], v[108:111], v[186:189], v[72:75]
	v_mfma_f32_16x16x32_bf16 v[76:79], v[116:119], v[186:189], v[76:79]
	v_mfma_f32_16x16x32_bf16 v[80:83], v[108:111], v[194:197], v[80:83]
	v_mfma_f32_16x16x32_bf16 v[84:87], v[116:119], v[194:197], v[84:87]
	v_mfma_f32_16x16x32_bf16 v[92:95], v[116:119], v[202:205], v[88:91]
	s_setprio 0
	s_setprio 1
	v_mfma_f32_16x16x32_bf16 v[48:51], v[166:169], v[190:193], v[48:51]
	v_mfma_f32_16x16x32_bf16 v[88:91], v[120:123], v[174:177], v[96:99]
	v_mfma_f32_16x16x32_bf16 v[32:35], v[166:169], v[174:177], v[32:35]
	v_mfma_f32_16x16x32_bf16 v[36:39], v[120:123], v[182:185], v[36:39]
	v_mfma_f32_16x16x32_bf16 v[40:43], v[166:169], v[182:185], v[40:43]
	v_mfma_f32_16x16x32_bf16 v[44:47], v[120:123], v[190:193], v[44:47]
	v_mfma_f32_16x16x32_bf16 v[174:177], v[170:173], v[194:197], v[48:51]
	v_mfma_f32_16x16x32_bf16 v[48:51], v[120:123], v[198:201], v[52:55]
	s_setprio 0
	s_setprio 1
	v_mfma_f32_16x16x32_bf16 v[32:35], v[170:173], v[178:181], v[32:35]
	v_mfma_f32_16x16x32_bf16 v[36:39], v[124:127], v[186:189], v[36:39]
	v_mfma_f32_16x16x32_bf16 v[40:43], v[170:173], v[186:189], v[40:43]
	v_mfma_f32_16x16x32_bf16 v[44:47], v[124:127], v[194:197], v[44:47]
	v_mfma_f32_16x16x32_bf16 v[52:55], v[124:127], v[202:205], v[48:51]
	v_mfma_f32_16x16x32_bf16 v[48:51], v[166:169], v[198:201], v[56:59]
	v_mfma_f32_16x16x32_bf16 v[210:213], v[124:127], v[178:181], v[88:91]
	v_mfma_f32_16x16x32_bf16 v[178:181], v[170:173], v[202:205], v[48:51]
	s_setprio 0
	s_barrier
	s_mov_b32 m0, s68
	v_lshl_add_u64 v[246:247], s[42:43], 0, v[132:133]
	s_add_u32 s34, s42, 0x10000
	s_nop 0
	ds_read_b128 v[48:51], v139 offset:16384
	ds_read_b128 v[56:59], v139 offset:17408
	ds_read_b128 v[88:91], v139 offset:18432
	ds_read_b128 v[96:99], v139 offset:19456
	ds_read_b128 v[182:185], v139 offset:20480
	ds_read_b128 v[186:189], v139 offset:21504
	ds_read_b128 v[190:193], v139 offset:22528
	ds_read_b128 v[194:197], v139 offset:23552
	global_load_lds_dwordx4 v[246:247], off
	v_lshl_add_u64 v[248:249], s[42:43], 0, v[128:129]
	s_mov_b32 m0, s69
	s_addc_u32 s35, s43, 0
	global_load_lds_dwordx4 v[248:249], off
	v_lshl_add_u64 v[198:199], s[34:35], 0, v[132:133]
	s_mov_b32 m0, s70
	v_lshl_add_u64 v[250:251], s[46:47], 0, v[134:135]
	global_load_lds_dwordx4 v[198:199], off
	v_lshl_add_u64 v[198:199], s[34:35], 0, v[128:129]
	s_mov_b32 m0, s71
	v_lshl_add_u64 v[252:253], s[46:47], 0, v[130:131]
	global_load_lds_dwordx4 v[198:199], off
	s_mov_b32 m0, s53
	s_nop 0
	global_load_lds_dwordx4 v[250:251], off
	s_mov_b32 m0, s54
	s_nop 0
	global_load_lds_dwordx4 v[252:253], off
	s_waitcnt vmcnt(8)
	s_waitcnt lgkmcnt(0)
	s_barrier
	s_setprio 1
	s_waitcnt lgkmcnt(0)
	v_mfma_f32_16x16x32_bf16 v[0:3], v[104:107], v[190:193], v[0:3]
	v_mfma_f32_16x16x32_bf16 v[4:7], v[112:115], v[190:193], v[4:7]
	v_mfma_f32_16x16x32_bf16 v[142:145], v[104:107], v[48:51], v[142:145]
	v_mfma_f32_16x16x32_bf16 v[146:149], v[112:115], v[48:51], v[146:149]
	v_mfma_f32_16x16x32_bf16 v[150:153], v[104:107], v[88:91], v[150:153]
	v_mfma_f32_16x16x32_bf16 v[154:157], v[112:115], v[88:91], v[154:157]
	v_mfma_f32_16x16x32_bf16 v[158:161], v[104:107], v[182:185], v[158:161]
	v_mfma_f32_16x16x32_bf16 v[162:165], v[112:115], v[182:185], v[162:165]
	s_setprio 0
	s_setprio 1
	v_mfma_f32_16x16x32_bf16 v[0:3], v[108:111], v[194:197], v[0:3]
	v_mfma_f32_16x16x32_bf16 v[4:7], v[116:119], v[194:197], v[4:7]
	v_mfma_f32_16x16x32_bf16 v[142:145], v[108:111], v[56:59], v[142:145]
	v_mfma_f32_16x16x32_bf16 v[146:149], v[116:119], v[56:59], v[146:149]
	v_mfma_f32_16x16x32_bf16 v[150:153], v[108:111], v[96:99], v[150:153]
	v_mfma_f32_16x16x32_bf16 v[154:157], v[116:119], v[96:99], v[154:157]
	v_mfma_f32_16x16x32_bf16 v[158:161], v[108:111], v[186:189], v[158:161]
	v_mfma_f32_16x16x32_bf16 v[162:165], v[116:119], v[186:189], v[162:165]
	s_setprio 0
	s_setprio 1
	v_mfma_f32_16x16x32_bf16 v[8:11], v[120:123], v[48:51], v[8:11]
	v_mfma_f32_16x16x32_bf16 v[198:201], v[124:127], v[56:59], v[8:11]
	v_mfma_f32_16x16x32_bf16 v[8:11], v[166:169], v[48:51], v[12:15]
	v_mfma_f32_16x16x32_bf16 v[12:15], v[170:173], v[56:59], v[8:11]
	v_mfma_f32_16x16x32_bf16 v[8:11], v[120:123], v[88:91], v[24:27]
	v_mfma_f32_16x16x32_bf16 v[202:205], v[124:127], v[96:99], v[8:11]
	v_mfma_f32_16x16x32_bf16 v[8:11], v[166:169], v[88:91], v[28:31]
	v_mfma_f32_16x16x32_bf16 v[28:31], v[170:173], v[96:99], v[8:11]
	s_setprio 0
	s_setprio 1
	v_mfma_f32_16x16x32_bf16 v[8:11], v[120:123], v[182:185], v[60:63]
	v_mfma_f32_16x16x32_bf16 v[214:217], v[124:127], v[186:189], v[8:11]
	v_mfma_f32_16x16x32_bf16 v[8:11], v[166:169], v[182:185], v[100:103]
	v_mfma_f32_16x16x32_bf16 v[182:185], v[170:173], v[186:189], v[8:11]
	v_mfma_f32_16x16x32_bf16 v[8:11], v[120:123], v[190:193], v[16:19]
	v_mfma_f32_16x16x32_bf16 v[186:189], v[124:127], v[194:197], v[8:11]
	v_mfma_f32_16x16x32_bf16 v[8:11], v[166:169], v[190:193], v[20:23]
	v_mfma_f32_16x16x32_bf16 v[166:169], v[170:173], v[194:197], v[8:11]
	s_setprio 0
	s_barrier
; #define PG8_STAGE(bufoff, gbase, voff) do { _Pragma("unroll") for (int _i = 0; _i < 2; ++_i) \
;         __builtin_amdgcn_global_load_lds((const unsigned*)((const char*)(gbase) + (voff)[_i]), (LAS unsigned*)(lds + (bufoff) + ldsw + _i * 8192), 16, 0, 0); } while (0)
; #define PG8_LDA(dst, b, h) do { _Pragma("unroll") for (int m = 0; m < 4; ++m) _Pragma("unroll") for (int k = 0; k < 2; ++k) dst[m][k] = *(const LAS bf16x8*)(lds + PG8_SA(b, h) + aoff + m * 2048 + k * 1024); } while (0)
; #define PG8_LDB(dst, b, h) do { _Pragma("unroll") for (int n = 0; n < 2; ++n) _Pragma("unroll") for (int k = 0; k < 2; ++k) dst[n][k] = *(const LAS bf16x8*)(lds + PG8_SB(b, h) + boff + n * 2048 + k * 1024); } while (0)
; #define PG8_MMA(ai, bj, At, Bt) do { __builtin_amdgcn_s_setprio(1); _Pragma("unroll") for (int m = 0; m < 4; ++m) _Pragma("unroll") for (int n = 0; n < 2; ++n) _Pragma("unroll") for (int k = 0; k < 2; ++k) \
;         acc[ai][bj][m][n] = __builtin_amdgcn_mfma_f32_16x16x32_bf16(Bt[n][k], At[m][k], acc[ai][bj][m][n], 0, 0, 0); __builtin_amdgcn_s_setprio(0); } while (0)
; #define PG8_WAIT_V(n) asm volatile("s_waitcnt vmcnt(" #n ")" ::: "memory")
; #define PG8_WAIT_L(n) asm volatile("s_waitcnt lgkmcnt(" #n ")" ::: "memory")
; #define PG8_BAR __builtin_amdgcn_s_barrier()
; #define PG8_SCHED __builtin_amdgcn_sched_barrier(0)
; template <class Epi, class Sched, bool ALIGN_EPI = false, bool SP2 = false, bool TWOA = false, bool AGM = false>
; __device__ __forceinline__ void gemm_phase(LAS unsigned char* lds, const Gemm g, const Sched& S, const Epi& E, int wid) {
;     ...
;             PG8_LDB(B0, 1, 0); PG8_LDB(B1, 1, 1); PG8_SCHED; PG8_LDA(At, 1, 0); PG8_STAGE(PG8_SA(0, 1), a2 + hstepA, voffA);
;             PG8_WAIT_V(8); PG8_WAIT_L(0); PG8_BAR; PG8_MMA(0, 0, At, B0); PG8_MMA(0, 1, At, B1); PG8_BAR; PG8_SCHED;
;             PG8_LDA(At, 1, 1); PG8_STAGE(PG8_SB(1, 0), b3, voffB); PG8_STAGE(PG8_SB(1, 1), b3 + hstep, voffB); PG8_STAGE(PG8_SA(1, 0), a3, voffA);
;             PG8_WAIT_V(8); PG8_WAIT_L(0); PG8_BAR; PG8_MMA(1, 0, At, B0); PG8_MMA(1, 1, At, B1); PG8_BAR; PG8_SCHED;
;     ...
;         if constexpr (ALIGN_EPI) { if (wr == 0) PG8_BAR; }
	s_nop 4
	ds_read_b128 v[8:11], v140
	ds_read_b128 v[20:23], v140 offset:1024
	ds_read_b128 v[170:173], v140 offset:2048
	ds_read_b128 v[190:193], v140 offset:3072
	ds_read_b128 v[194:197], v141
	ds_read_b128 v[218:221], v141 offset:1024
	ds_read_b128 v[222:225], v141 offset:2048
	ds_read_b128 v[226:229], v141 offset:3072
	s_add_u32 s34, s46, 0x10000
	s_addc_u32 s35, s47, 0
	s_mov_b32 m0, s55
	v_lshl_add_u64 v[48:49], s[34:35], 0, v[134:135]
	ds_read_b128 v[16:19], v139 offset:32768
	ds_read_b128 v[24:27], v139 offset:33792
	ds_read_b128 v[60:63], v139 offset:34816
	ds_read_b128 v[100:103], v139 offset:35840
	ds_read_b128 v[230:233], v139 offset:36864
	ds_read_b128 v[234:237], v139 offset:37888
	ds_read_b128 v[238:241], v139 offset:38912
	ds_read_b128 v[242:245], v139 offset:39936
	global_load_lds_dwordx4 v[48:49], off
	v_lshl_add_u64 v[48:49], s[34:35], 0, v[130:131]
	s_mov_b32 m0, s56
	s_nop 0
	global_load_lds_dwordx4 v[48:49], off
	s_waitcnt vmcnt(8)
	s_waitcnt lgkmcnt(0)
	s_barrier
	s_setprio 1
	s_waitcnt lgkmcnt(0)
	v_mfma_f32_16x16x32_bf16 v[48:51], v[8:11], v[16:19], v[64:67]
	v_mfma_f32_16x16x32_bf16 v[120:123], v[20:23], v[24:27], v[48:51]
	v_mfma_f32_16x16x32_bf16 v[48:51], v[170:173], v[16:19], v[68:71]
	v_mfma_f32_16x16x32_bf16 v[112:115], v[190:193], v[24:27], v[48:51]
	v_mfma_f32_16x16x32_bf16 v[48:51], v[8:11], v[60:63], v[72:75]
	v_mfma_f32_16x16x32_bf16 v[104:107], v[20:23], v[100:103], v[48:51]
	v_mfma_f32_16x16x32_bf16 v[48:51], v[170:173], v[60:63], v[76:79]
	v_mfma_f32_16x16x32_bf16 v[96:99], v[190:193], v[100:103], v[48:51]
	s_setprio 0
	s_setprio 1
	v_mfma_f32_16x16x32_bf16 v[48:51], v[8:11], v[230:233], v[80:83]
	v_mfma_f32_16x16x32_bf16 v[88:91], v[20:23], v[234:237], v[48:51]
	v_mfma_f32_16x16x32_bf16 v[48:51], v[170:173], v[230:233], v[84:87]
	v_mfma_f32_16x16x32_bf16 v[80:83], v[190:193], v[234:237], v[48:51]
	v_mfma_f32_16x16x32_bf16 v[48:51], v[8:11], v[238:241], v[206:209]
	v_mfma_f32_16x16x32_bf16 v[56:59], v[20:23], v[242:245], v[48:51]
	v_mfma_f32_16x16x32_bf16 v[48:51], v[170:173], v[238:241], v[92:95]
	v_mfma_f32_16x16x32_bf16 v[48:51], v[190:193], v[242:245], v[48:51]
	s_setprio 0
	s_setprio 1
	v_mfma_f32_16x16x32_bf16 v[64:67], v[194:197], v[16:19], v[210:213]
	v_mfma_f32_16x16x32_bf16 v[16:19], v[222:225], v[16:19], v[32:35]
	v_mfma_f32_16x16x32_bf16 v[116:119], v[226:229], v[24:27], v[16:19]
	v_mfma_f32_16x16x32_bf16 v[16:19], v[194:197], v[60:63], v[36:39]
	v_mfma_f32_16x16x32_bf16 v[108:111], v[218:221], v[100:103], v[16:19]
	v_mfma_f32_16x16x32_bf16 v[16:19], v[222:225], v[60:63], v[40:43]
	v_mfma_f32_16x16x32_bf16 v[100:103], v[226:229], v[100:103], v[16:19]
	v_mfma_f32_16x16x32_bf16 v[16:19], v[194:197], v[230:233], v[44:47]
	s_setprio 0
	s_setprio 1
	v_mfma_f32_16x16x32_bf16 v[92:95], v[218:221], v[234:237], v[16:19]
	v_mfma_f32_16x16x32_bf16 v[16:19], v[222:225], v[230:233], v[174:177]
	v_mfma_f32_16x16x32_bf16 v[84:87], v[226:229], v[234:237], v[16:19]
	v_mfma_f32_16x16x32_bf16 v[16:19], v[194:197], v[238:241], v[52:55]
	v_mfma_f32_16x16x32_bf16 v[60:63], v[218:221], v[242:245], v[16:19]
	v_mfma_f32_16x16x32_bf16 v[16:19], v[222:225], v[238:241], v[178:181]
	v_mfma_f32_16x16x32_bf16 v[124:127], v[218:221], v[24:27], v[64:67]
	v_mfma_f32_16x16x32_bf16 v[52:55], v[226:229], v[242:245], v[16:19]
	s_setprio 0
	s_barrier
	s_mov_b32 m0, s72
	s_nop 2
	v_lshl_add_u64 v[16:17], v[246:247], 0, s[12:13]
	s_add_u32 s34, s42, 0x10080
	ds_read_b128 v[36:39], v139 offset:49152
	ds_read_b128 v[44:47], v139 offset:50176
	ds_read_b128 v[174:177], v139 offset:51200
	ds_read_b128 v[178:181], v139 offset:52224
	ds_read_b128 v[206:209], v139 offset:53248
	ds_read_b128 v[210:213], v139 offset:54272
	ds_read_b128 v[230:233], v139 offset:55296
	ds_read_b128 v[234:237], v139 offset:56320
	global_load_lds_dwordx4 v[16:17], off
	v_lshl_add_u64 v[16:17], v[248:249], 0, s[12:13]
	s_mov_b32 m0, s73
	s_addc_u32 s35, s43, 0
	global_load_lds_dwordx4 v[16:17], off
	v_lshl_add_u64 v[16:17], s[34:35], 0, v[132:133]
	s_mov_b32 m0, s74
	s_nop 0
	global_load_lds_dwordx4 v[16:17], off
	v_lshl_add_u64 v[16:17], s[34:35], 0, v[128:129]
	s_mov_b32 m0, s75
	s_nop 0
	global_load_lds_dwordx4 v[16:17], off
	v_lshl_add_u64 v[16:17], v[250:251], 0, s[12:13]
	s_mov_b32 m0, s57
	s_nop 0
	global_load_lds_dwordx4 v[16:17], off
	v_lshl_add_u64 v[16:17], v[252:253], 0, s[12:13]
	s_mov_b32 m0, s64
	s_nop 0
	global_load_lds_dwordx4 v[16:17], off
	s_waitcnt vmcnt(8)
	s_waitcnt lgkmcnt(0)
	s_barrier
	s_setprio 1
	s_waitcnt lgkmcnt(0)
	v_mfma_f32_16x16x32_bf16 v[16:19], v[8:11], v[36:39], v[142:145]
	v_mfma_f32_16x16x32_bf16 v[72:75], v[20:23], v[44:47], v[16:19]
	v_mfma_f32_16x16x32_bf16 v[16:19], v[170:173], v[36:39], v[146:149]
	v_mfma_f32_16x16x32_bf16 v[64:67], v[190:193], v[44:47], v[16:19]
	v_mfma_f32_16x16x32_bf16 v[16:19], v[8:11], v[174:177], v[150:153]
	v_mfma_f32_16x16x32_bf16 v[40:43], v[20:23], v[178:181], v[16:19]
	v_mfma_f32_16x16x32_bf16 v[16:19], v[170:173], v[174:177], v[154:157]
	v_mfma_f32_16x16x32_bf16 v[32:35], v[190:193], v[178:181], v[16:19]
	s_setprio 0
	s_setprio 1
	v_mfma_f32_16x16x32_bf16 v[16:19], v[8:11], v[206:209], v[158:161]
	v_mfma_f32_16x16x32_bf16 v[0:3], v[8:11], v[230:233], v[0:3]
	v_mfma_f32_16x16x32_bf16 v[24:27], v[20:23], v[210:213], v[16:19]
	v_mfma_f32_16x16x32_bf16 v[16:19], v[170:173], v[206:209], v[162:165]
	v_mfma_f32_16x16x32_bf16 v[8:11], v[20:23], v[234:237], v[0:3]
	v_mfma_f32_16x16x32_bf16 v[0:3], v[170:173], v[230:233], v[4:7]
	v_mfma_f32_16x16x32_bf16 v[16:19], v[190:193], v[210:213], v[16:19]
	v_mfma_f32_16x16x32_bf16 v[0:3], v[190:193], v[234:237], v[0:3]
	s_setprio 0
	s_setprio 1
	v_mfma_f32_16x16x32_bf16 v[4:7], v[194:197], v[36:39], v[198:201]
	v_mfma_f32_16x16x32_bf16 v[76:79], v[218:221], v[44:47], v[4:7]
	v_mfma_f32_16x16x32_bf16 v[4:7], v[222:225], v[36:39], v[12:15]
	v_mfma_f32_16x16x32_bf16 v[68:71], v[226:229], v[44:47], v[4:7]
	v_mfma_f32_16x16x32_bf16 v[4:7], v[194:197], v[174:177], v[202:205]
	v_mfma_f32_16x16x32_bf16 v[44:47], v[218:221], v[178:181], v[4:7]
	v_mfma_f32_16x16x32_bf16 v[4:7], v[222:225], v[174:177], v[28:31]
	v_mfma_f32_16x16x32_bf16 v[36:39], v[226:229], v[178:181], v[4:7]
	s_setprio 0
	s_setprio 1
	v_mfma_f32_16x16x32_bf16 v[4:7], v[194:197], v[206:209], v[214:217]
	v_mfma_f32_16x16x32_bf16 v[28:31], v[218:221], v[210:213], v[4:7]
	v_mfma_f32_16x16x32_bf16 v[4:7], v[222:225], v[206:209], v[182:185]
	v_mfma_f32_16x16x32_bf16 v[20:23], v[226:229], v[210:213], v[4:7]
	v_mfma_f32_16x16x32_bf16 v[4:7], v[194:197], v[230:233], v[186:189]
	v_mfma_f32_16x16x32_bf16 v[12:15], v[218:221], v[234:237], v[4:7]
	v_mfma_f32_16x16x32_bf16 v[4:7], v[222:225], v[230:233], v[166:169]
	v_mfma_f32_16x16x32_bf16 v[4:7], v[226:229], v[234:237], v[4:7]
	s_setprio 0
	s_barrier
	s_and_b64 vcc, exec, s[4:5]
	s_cbranch_vccnz .LBB0_525
	s_barrier

; #define PG8_STAGE(bufoff, gbase, voff) do { _Pragma("unroll") for (int _i = 0; _i < 2; ++_i) \
;         __builtin_amdgcn_global_load_lds((const unsigned*)((const char*)(gbase) + (voff)[_i]), (LAS unsigned*)(lds + (bufoff) + ldsw + _i * 8192), 16, 0, 0); } while (0)
; #define PG8_LDA(dst, b, h) do { _Pragma("unroll") for (int m = 0; m < 4; ++m) _Pragma("unroll") for (int k = 0; k < 2; ++k) dst[m][k] = *(const LAS bf16x8*)(lds + PG8_SA(b, h) + aoff + m * 2048 + k * 1024); } while (0)
; #define PG8_WAIT_V(n) asm volatile("s_waitcnt vmcnt(" #n ")" ::: "memory")
; template <class Epi, class Sched, bool ALIGN_EPI = false, bool SP2 = false, bool TWOA = false, bool AGM = false>
; __device__ __forceinline__ void gemm_phase(LAS unsigned char* lds, const Gemm g, const Sched& S, const Epi& E, int wid) {
;     ...
;         const bool has_next = S.next(ui + 1, nxt);
;         const char* nA = has_next ? (const char*)g.A + (size_t)nxt.pm * tstepA : cA; const char* nB = has_next ? (const char*)g.Bt + (size_t)nxt.pn * tstep : cB;
;         for (int t = 0; t < nt; t += 2) {
;             const bool last = (t == nt - 2);
;             const char* cA2 = TWOA ? (const char*)g.A2 + (cA - (const char*)g.A) - (size_t)nh * kstepA : cA;
;             const char* a1_ = (TWOA && t + 1 >= nh ? cA2 : cA) + (size_t)(t + 1) * kstepA;
;             const char* a2_ = last ? nA : (TWOA && t + 2 >= nh ? cA2 : cA) + (size_t)(t + 2) * kstepA; const char* a1 = a1_; const char* a2 = a2_; const char* b2 = last ? nB : cB + (size_t)(t + 2) * kstep;
;             if constexpr (TWOA) { asm volatile("" : "+s"(a1)); asm volatile("" : "+s"(a2)); }
;             const char* a3 = a2 + kstepA; const char* b3 = b2 + kstep;
;             if (last && has_next) S.a_ready(nxt);
;             if constexpr (has_mid<Epi>::value) { if (t == nh) E.mid(acc, cur, wr, wc, fr, fq); }
;             if constexpr (SP2) {
;             PG8_LDB(B0, 0, 0); PG8_LDB(B1, 0, 1); PG8_SCHED; PG8_LDA(At, 0, 0); PG8_STAGE(PG8_SA(1, 1), a1 + hstepA, voffA);
;             PG8_WAIT_V(8); PG8_WAIT_L(0); PG8_BAR; PG8_MMA(0, 0, At, B0); PG8_MMA(0, 1, At, B1); PG8_BAR; PG8_SCHED;
;             PG8_LDA(At, 0, 1); PG8_STAGE(PG8_SB(0, 0), b2, voffB); PG8_STAGE(PG8_SB(0, 1), b2 + hstep, voffB); PG8_STAGE(PG8_SA(0, 0), a2, voffA);
;             PG8_WAIT_V(8); PG8_WAIT_L(0); PG8_BAR; PG8_MMA(1, 0, At, B0); PG8_MMA(1, 1, At, B1); PG8_BAR; PG8_SCHED;
.LBB0_682:
	s_ashr_i32 s37, s36, 31
	s_lshl_b64 s[34:35], s[36:37], 17
	s_add_u32 s38, s8, s34
	s_addc_u32 s39, s9, s35
	s_and_b64 s[34:35], s[42:43], exec
	s_cselect_b32 s37, s39, s55
	s_cselect_b32 s80, s38, s54
	s_ashr_i32 s31, s30, 31
	s_lshl_b64 s[34:35], s[30:31], 18
	s_add_u32 s40, s68, s34
	s_addc_u32 s41, s69, s35
	s_and_b64 s[34:35], s[42:43], exec
	s_cselect_b32 s31, s41, s53
	s_cselect_b32 s82, s40, s52
	s_sub_u32 s34, s54, s8
	s_subb_u32 s35, s55, s9
	s_add_u32 s50, s72, s34
	s_addc_u32 s51, s73, s35
	s_add_u32 s34, s54, 0x80
	s_addc_u32 s35, s55, 0
	s_add_u32 s56, s54, 0x100
	s_addc_u32 s57, s55, 0
	ds_read_b128 v[4:7], v157
	ds_read_b128 v[8:11], v157 offset:1024
	ds_read_b128 v[12:15], v157 offset:2048
	ds_read_b128 v[16:19], v157 offset:3072
	ds_read_b128 v[20:23], v158
	ds_read_b128 v[24:27], v158 offset:1024
	ds_read_b128 v[28:31], v158 offset:2048
	ds_read_b128 v[32:35], v158 offset:3072
	s_add_u32 s34, s34, 0x10000
	s_addc_u32 s35, s35, 0
	s_add_i32 s83, s45, 0xc000
	v_lshl_add_u64 v[64:65], s[34:35], 0, v[134:135]
	s_mov_b32 m0, s83
	s_add_i32 s84, s45, 0xe000
	ds_read_b128 v[0:3], v137
	ds_read_b128 v[36:39], v137 offset:1024
	ds_read_b128 v[40:43], v137 offset:2048
	ds_read_b128 v[44:47], v137 offset:3072
	ds_read_b128 v[48:51], v137 offset:4096
	ds_read_b128 v[52:55], v137 offset:5120
	ds_read_b128 v[56:59], v137 offset:6144
	ds_read_b128 v[60:63], v137 offset:7168
	global_load_lds_dwordx4 v[64:65], off
	v_lshl_add_u64 v[64:65], s[34:35], 0, v[130:131]
	s_mov_b32 m0, s84
	s_nop 0
	global_load_lds_dwordx4 v[64:65], off
	s_waitcnt vmcnt(8)
	s_waitcnt lgkmcnt(0)
	s_barrier
	s_setprio 1
	s_waitcnt lgkmcnt(0)
	v_mfma_f32_16x16x32_bf16 v[64:67], v[4:7], v[0:3], 0
	v_mfma_f32_16x16x32_bf16 v[68:71], v[12:15], v[0:3], 0
	v_mfma_f32_16x16x32_bf16 v[72:75], v[4:7], v[40:43], 0
	v_mfma_f32_16x16x32_bf16 v[76:79], v[12:15], v[40:43], 0
	v_mfma_f32_16x16x32_bf16 v[80:83], v[4:7], v[48:51], 0
	v_mfma_f32_16x16x32_bf16 v[84:87], v[12:15], v[48:51], 0
	v_mfma_f32_16x16x32_bf16 v[88:91], v[4:7], v[56:59], 0
	v_mfma_f32_16x16x32_bf16 v[92:95], v[12:15], v[56:59], 0
	s_setprio 0
	s_setprio 1
	v_mfma_f32_16x16x32_bf16 v[64:67], v[8:11], v[36:39], v[64:67]
	v_mfma_f32_16x16x32_bf16 v[68:71], v[16:19], v[36:39], v[68:71]
	v_mfma_f32_16x16x32_bf16 v[72:75], v[8:11], v[44:47], v[72:75]
	v_mfma_f32_16x16x32_bf16 v[76:79], v[16:19], v[44:47], v[76:79]
	v_mfma_f32_16x16x32_bf16 v[80:83], v[8:11], v[52:55], v[80:83]
	v_mfma_f32_16x16x32_bf16 v[84:87], v[16:19], v[52:55], v[84:87]
	v_mfma_f32_16x16x32_bf16 v[88:91], v[8:11], v[60:63], v[88:91]
	v_mfma_f32_16x16x32_bf16 v[92:95], v[16:19], v[60:63], v[92:95]
	s_setprio 0
	s_setprio 1
	v_mfma_f32_16x16x32_bf16 v[96:99], v[20:23], v[0:3], 0
	v_mfma_f32_16x16x32_bf16 v[0:3], v[28:31], v[0:3], 0
	v_mfma_f32_16x16x32_bf16 v[96:99], v[24:27], v[36:39], v[96:99]
	v_mfma_f32_16x16x32_bf16 v[36:39], v[32:35], v[36:39], v[0:3]
	v_mfma_f32_16x16x32_bf16 v[0:3], v[20:23], v[40:43], 0
	v_mfma_f32_16x16x32_bf16 v[100:103], v[24:27], v[44:47], v[0:3]
	v_mfma_f32_16x16x32_bf16 v[0:3], v[28:31], v[40:43], 0
	v_mfma_f32_16x16x32_bf16 v[40:43], v[32:35], v[44:47], v[0:3]
	s_setprio 0
	s_setprio 1
	v_mfma_f32_16x16x32_bf16 v[0:3], v[20:23], v[48:51], 0
	v_mfma_f32_16x16x32_bf16 v[44:47], v[24:27], v[52:55], v[0:3]
	v_mfma_f32_16x16x32_bf16 v[0:3], v[28:31], v[48:51], 0
	v_mfma_f32_16x16x32_bf16 v[48:51], v[32:35], v[52:55], v[0:3]
	v_mfma_f32_16x16x32_bf16 v[0:3], v[20:23], v[56:59], 0
	v_mfma_f32_16x16x32_bf16 v[52:55], v[24:27], v[60:63], v[0:3]
	v_mfma_f32_16x16x32_bf16 v[0:3], v[28:31], v[56:59], 0
	v_mfma_f32_16x16x32_bf16 v[56:59], v[32:35], v[60:63], v[0:3]
	s_setprio 0
	s_barrier
	s_nop 4
	v_lshl_add_u64 v[0:1], s[52:53], 0, v[132:133]
	s_add_i32 s85, s76, s3
	v_lshl_add_u64 v[2:3], v[0:1], 0, s[22:23]
	s_mov_b32 m0, s85
	s_add_i32 s86, s85, 0x2000
	ds_read_b128 v[60:63], v137 offset:16384
	ds_read_b128 v[104:107], v137 offset:17408
	ds_read_b128 v[108:111], v137 offset:18432
	ds_read_b128 v[112:115], v137 offset:19456
	ds_read_b128 v[116:119], v137 offset:20480
	ds_read_b128 v[120:123], v137 offset:21504
	ds_read_b128 v[124:127], v137 offset:22528
	ds_read_b128 v[160:163], v137 offset:23552
	global_load_lds_dwordx4 v[2:3], off
	v_lshl_add_u64 v[2:3], s[52:53], 0, v[128:129]
	s_add_u32 s34, s52, 0x20100
	v_lshl_add_u64 v[140:141], v[2:3], 0, s[22:23]
	s_mov_b32 m0, s86
	s_addc_u32 s35, s53, 0
	s_add_i32 s87, s77, s3
	global_load_lds_dwordx4 v[140:141], off
	v_lshl_add_u64 v[140:141], s[34:35], 0, v[132:133]
	s_mov_b32 m0, s87
	s_add_i32 s88, s87, 0x2000
	global_load_lds_dwordx4 v[140:141], off
	v_lshl_add_u64 v[140:141], s[34:35], 0, v[128:129]
	s_mov_b32 m0, s88
	v_lshl_add_u64 v[142:143], s[56:57], 0, v[130:131]
	global_load_lds_dwordx4 v[140:141], off
	v_lshl_add_u64 v[140:141], s[56:57], 0, v[134:135]
	s_mov_b32 m0, s45
	s_nop 0
	global_load_lds_dwordx4 v[140:141], off
	s_mov_b32 m0, s47
	s_nop 0
	global_load_lds_dwordx4 v[142:143], off
	s_waitcnt vmcnt(8)
	s_waitcnt lgkmcnt(0)
	s_barrier
; #define PG8_STAGE(bufoff, gbase, voff) do { _Pragma("unroll") for (int _i = 0; _i < 2; ++_i) \
;         __builtin_amdgcn_global_load_lds((const unsigned*)((const char*)(gbase) + (voff)[_i]), (LAS unsigned*)(lds + (bufoff) + ldsw + _i * 8192), 16, 0, 0); } while (0)
; #define PG8_LDA(dst, b, h) do { _Pragma("unroll") for (int m = 0; m < 4; ++m) _Pragma("unroll") for (int k = 0; k < 2; ++k) dst[m][k] = *(const LAS bf16x8*)(lds + PG8_SA(b, h) + aoff + m * 2048 + k * 1024); } while (0)
; #define PG8_LDB(dst, b, h) do { _Pragma("unroll") for (int n = 0; n < 2; ++n) _Pragma("unroll") for (int k = 0; k < 2; ++k) dst[n][k] = *(const LAS bf16x8*)(lds + PG8_SB(b, h) + boff + n * 2048 + k * 1024); } while (0)
; #define PG8_MMA(ai, bj, At, Bt) do { __builtin_amdgcn_s_setprio(1); _Pragma("unroll") for (int m = 0; m < 4; ++m) _Pragma("unroll") for (int n = 0; n < 2; ++n) _Pragma("unroll") for (int k = 0; k < 2; ++k) \
;         acc[ai][bj][m][n] = __builtin_amdgcn_mfma_f32_16x16x32_bf16(Bt[n][k], At[m][k], acc[ai][bj][m][n], 0, 0, 0); __builtin_amdgcn_s_setprio(0); } while (0)
; #define PG8_WAIT_V(n) asm volatile("s_waitcnt vmcnt(" #n ")" ::: "memory")
; #define PG8_WAIT_L(n) asm volatile("s_waitcnt lgkmcnt(" #n ")" ::: "memory")
; #define PG8_BAR __builtin_amdgcn_s_barrier()
; #define PG8_SCHED __builtin_amdgcn_sched_barrier(0)
; template <class Epi, class Sched, bool ALIGN_EPI = false, bool SP2 = false, bool TWOA = false, bool AGM = false>
; __device__ __forceinline__ void gemm_phase(LAS unsigned char* lds, const Gemm g, const Sched& S, const Epi& E, int wid) {
;     ...
;             PG8_WAIT_V(8); PG8_WAIT_L(0); PG8_BAR; PG8_MMA(1, 0, At, B0); PG8_MMA(1, 1, At, B1); PG8_BAR; PG8_SCHED;
;             PG8_LDB(B0, 1, 0); PG8_LDB(B1, 1, 1); PG8_SCHED; PG8_LDA(At, 1, 0); PG8_STAGE(PG8_SA(0, 1), a2 + hstepA, voffA);
;             PG8_WAIT_V(8); PG8_WAIT_L(0); PG8_BAR; PG8_MMA(0, 0, At, B0); PG8_MMA(0, 1, At, B1); PG8_BAR; PG8_SCHED;
	s_setprio 1
	s_waitcnt lgkmcnt(0)
	v_mfma_f32_16x16x32_bf16 v[164:167], v[4:7], v[60:63], 0
	v_mfma_f32_16x16x32_bf16 v[172:175], v[4:7], v[108:111], 0
	v_mfma_f32_16x16x32_bf16 v[180:183], v[4:7], v[116:119], 0
	v_mfma_f32_16x16x32_bf16 v[4:7], v[4:7], v[124:127], 0
	v_mfma_f32_16x16x32_bf16 v[164:167], v[8:11], v[104:107], v[164:167]
	v_mfma_f32_16x16x32_bf16 v[172:175], v[8:11], v[112:115], v[172:175]
	v_mfma_f32_16x16x32_bf16 v[180:183], v[8:11], v[120:123], v[180:183]
	v_mfma_f32_16x16x32_bf16 v[4:7], v[8:11], v[160:163], v[4:7]
	s_setprio 0
	s_setprio 1
	v_mfma_f32_16x16x32_bf16 v[8:11], v[12:15], v[124:127], 0
	v_mfma_f32_16x16x32_bf16 v[168:171], v[12:15], v[60:63], 0
	v_mfma_f32_16x16x32_bf16 v[176:179], v[12:15], v[108:111], 0
	v_mfma_f32_16x16x32_bf16 v[184:187], v[12:15], v[116:119], 0
	v_mfma_f32_16x16x32_bf16 v[8:11], v[16:19], v[160:163], v[8:11]
	v_mfma_f32_16x16x32_bf16 v[168:171], v[16:19], v[104:107], v[168:171]
	v_mfma_f32_16x16x32_bf16 v[176:179], v[16:19], v[112:115], v[176:179]
	v_mfma_f32_16x16x32_bf16 v[184:187], v[16:19], v[120:123], v[184:187]
	s_setprio 0
	s_setprio 1
	v_mfma_f32_16x16x32_bf16 v[12:15], v[20:23], v[60:63], 0
	v_mfma_f32_16x16x32_bf16 v[16:19], v[28:31], v[60:63], 0
	v_mfma_f32_16x16x32_bf16 v[12:15], v[24:27], v[104:107], v[12:15]
	v_mfma_f32_16x16x32_bf16 v[16:19], v[32:35], v[104:107], v[16:19]
	v_mfma_f32_16x16x32_bf16 v[60:63], v[20:23], v[108:111], 0
	v_mfma_f32_16x16x32_bf16 v[104:107], v[28:31], v[108:111], 0
	v_mfma_f32_16x16x32_bf16 v[108:111], v[20:23], v[116:119], 0
	v_mfma_f32_16x16x32_bf16 v[20:23], v[20:23], v[124:127], 0
	s_setprio 0
	s_setprio 1
	v_mfma_f32_16x16x32_bf16 v[60:63], v[24:27], v[112:115], v[60:63]
	v_mfma_f32_16x16x32_bf16 v[104:107], v[32:35], v[112:115], v[104:107]
	v_mfma_f32_16x16x32_bf16 v[108:111], v[24:27], v[120:123], v[108:111]
	v_mfma_f32_16x16x32_bf16 v[112:115], v[28:31], v[116:119], 0
	v_mfma_f32_16x16x32_bf16 v[20:23], v[24:27], v[160:163], v[20:23]
	v_mfma_f32_16x16x32_bf16 v[24:27], v[28:31], v[124:127], 0
	v_mfma_f32_16x16x32_bf16 v[112:115], v[32:35], v[120:123], v[112:115]
	v_mfma_f32_16x16x32_bf16 v[24:27], v[32:35], v[160:163], v[24:27]
	s_setprio 0
	s_barrier
	s_add_i32 s89, 0, 0x18000
	s_add_i32 s90, 0, 0x1c000
	v_add_u32_e32 v159, s89, v136
	v_add_u32_e32 v160, s90, v136
	ds_read_b128 v[28:31], v159
	ds_read_b128 v[32:35], v159 offset:1024
	ds_read_b128 v[116:119], v159 offset:2048
	ds_read_b128 v[120:123], v159 offset:3072
	ds_read_b128 v[124:127], v160
	ds_read_b128 v[188:191], v160 offset:1024
	ds_read_b128 v[192:195], v160 offset:2048
	ds_read_b128 v[196:199], v160 offset:3072
	s_add_u32 s34, s56, 0x10000
	s_addc_u32 s35, s57, 0
	s_mov_b32 m0, s70
	v_lshl_add_u64 v[144:145], s[34:35], 0, v[134:135]
	ds_read_b128 v[200:203], v137 offset:32768
	ds_read_b128 v[204:207], v137 offset:33792
	ds_read_b128 v[208:211], v137 offset:34816
	ds_read_b128 v[212:215], v137 offset:35840
	ds_read_b128 v[216:219], v137 offset:36864
	ds_read_b128 v[220:223], v137 offset:37888
	ds_read_b128 v[224:227], v137 offset:38912
	ds_read_b128 v[228:231], v137 offset:39936
	global_load_lds_dwordx4 v[144:145], off
	v_lshl_add_u64 v[144:145], s[34:35], 0, v[130:131]
	s_mov_b32 m0, s71
	s_nop 0
	global_load_lds_dwordx4 v[144:145], off
	s_waitcnt vmcnt(8)
	s_waitcnt lgkmcnt(0)
	s_barrier
	s_setprio 1
	s_waitcnt lgkmcnt(0)
	v_mfma_f32_16x16x32_bf16 v[64:67], v[28:31], v[200:203], v[64:67]
	v_mfma_f32_16x16x32_bf16 v[68:71], v[116:119], v[200:203], v[68:71]
	v_mfma_f32_16x16x32_bf16 v[72:75], v[28:31], v[208:211], v[72:75]
	v_mfma_f32_16x16x32_bf16 v[76:79], v[116:119], v[208:211], v[76:79]
	v_mfma_f32_16x16x32_bf16 v[80:83], v[28:31], v[216:219], v[80:83]
	v_mfma_f32_16x16x32_bf16 v[84:87], v[116:119], v[216:219], v[84:87]
	v_mfma_f32_16x16x32_bf16 v[88:91], v[28:31], v[224:227], v[88:91]
	v_mfma_f32_16x16x32_bf16 v[92:95], v[116:119], v[224:227], v[92:95]
	s_setprio 0
	s_setprio 1
	v_mfma_f32_16x16x32_bf16 v[64:67], v[32:35], v[204:207], v[64:67]
	v_mfma_f32_16x16x32_bf16 v[68:71], v[120:123], v[204:207], v[68:71]
	v_mfma_f32_16x16x32_bf16 v[72:75], v[32:35], v[212:215], v[72:75]
	v_mfma_f32_16x16x32_bf16 v[76:79], v[120:123], v[212:215], v[76:79]
	v_mfma_f32_16x16x32_bf16 v[80:83], v[32:35], v[220:223], v[80:83]
	v_mfma_f32_16x16x32_bf16 v[84:87], v[120:123], v[220:223], v[84:87]
	v_mfma_f32_16x16x32_bf16 v[88:91], v[32:35], v[228:231], v[88:91]
	v_mfma_f32_16x16x32_bf16 v[92:95], v[120:123], v[228:231], v[92:95]
	s_setprio 0
	s_setprio 1
	v_mfma_f32_16x16x32_bf16 v[96:99], v[124:127], v[200:203], v[96:99]
	v_mfma_f32_16x16x32_bf16 v[36:39], v[192:195], v[200:203], v[36:39]
	v_mfma_f32_16x16x32_bf16 v[100:103], v[124:127], v[208:211], v[100:103]
	v_mfma_f32_16x16x32_bf16 v[40:43], v[192:195], v[208:211], v[40:43]
	v_mfma_f32_16x16x32_bf16 v[44:47], v[124:127], v[216:219], v[44:47]
	v_mfma_f32_16x16x32_bf16 v[48:51], v[192:195], v[216:219], v[48:51]
	v_mfma_f32_16x16x32_bf16 v[52:55], v[124:127], v[224:227], v[52:55]
	v_mfma_f32_16x16x32_bf16 v[56:59], v[192:195], v[224:227], v[56:59]
	s_setprio 0
	s_setprio 1
	v_mfma_f32_16x16x32_bf16 v[96:99], v[188:191], v[204:207], v[96:99]
	v_mfma_f32_16x16x32_bf16 v[36:39], v[196:199], v[204:207], v[36:39]
	v_mfma_f32_16x16x32_bf16 v[100:103], v[188:191], v[212:215], v[100:103]
	v_mfma_f32_16x16x32_bf16 v[40:43], v[196:199], v[212:215], v[40:43]
	v_mfma_f32_16x16x32_bf16 v[44:47], v[188:191], v[220:223], v[44:47]
	v_mfma_f32_16x16x32_bf16 v[48:51], v[196:199], v[220:223], v[48:51]
	v_mfma_f32_16x16x32_bf16 v[52:55], v[188:191], v[228:231], v[52:55]
	v_mfma_f32_16x16x32_bf16 v[56:59], v[196:199], v[228:231], v[56:59]
	s_setprio 0
	s_barrier
; #define PG8_STAGE(bufoff, gbase, voff) do { _Pragma("unroll") for (int _i = 0; _i < 2; ++_i) \
;         __builtin_amdgcn_global_load_lds((const unsigned*)((const char*)(gbase) + (voff)[_i]), (LAS unsigned*)(lds + (bufoff) + ldsw + _i * 8192), 16, 0, 0); } while (0)
; #define PG8_LDA(dst, b, h) do { _Pragma("unroll") for (int m = 0; m < 4; ++m) _Pragma("unroll") for (int k = 0; k < 2; ++k) dst[m][k] = *(const LAS bf16x8*)(lds + PG8_SA(b, h) + aoff + m * 2048 + k * 1024); } while (0)
; #define PG8_LDB(dst, b, h) do { _Pragma("unroll") for (int n = 0; n < 2; ++n) _Pragma("unroll") for (int k = 0; k < 2; ++k) dst[n][k] = *(const LAS bf16x8*)(lds + PG8_SB(b, h) + boff + n * 2048 + k * 1024); } while (0)
; #define PG8_WAIT_V(n) asm volatile("s_waitcnt vmcnt(" #n ")" ::: "memory")
; #define PG8_WAIT_L(n) asm volatile("s_waitcnt lgkmcnt(" #n ")" ::: "memory")
; #define PG8_BAR __builtin_amdgcn_s_barrier()
; #define PG8_SCHED __builtin_amdgcn_sched_barrier(0)
; template <class Epi, class Sched, bool ALIGN_EPI = false, bool SP2 = false, bool TWOA = false, bool AGM = false>
; __device__ __forceinline__ void gemm_phase(LAS unsigned char* lds, const Gemm g, const Sched& S, const Epi& E, int wid) {
;     ...
;             const char* cA2 = TWOA ? (const char*)g.A2 + (cA - (const char*)g.A) - (size_t)nh * kstepA : cA;
;             const char* a1_ = (TWOA && t + 1 >= nh ? cA2 : cA) + (size_t)(t + 1) * kstepA;
;             const char* a2_ = last ? nA : (TWOA && t + 2 >= nh ? cA2 : cA) + (size_t)(t + 2) * kstepA; const char* a1 = a1_; const char* a2 = a2_; const char* b2 = last ? nB : cB + (size_t)(t + 2) * kstep;
;             if constexpr (TWOA) { asm volatile("" : "+s"(a1)); asm volatile("" : "+s"(a2)); }
;             const char* a3 = a2 + kstepA; const char* b3 = b2 + kstep;
;     ...
;             PG8_LDB(B0, 0, 0); PG8_LDB(B1, 0, 1); PG8_SCHED; PG8_LDA(At, 0, 0); PG8_STAGE(PG8_SA(1, 1), a1 + hstepA, voffA);
;             PG8_WAIT_V(8); PG8_WAIT_L(0); PG8_BAR; PG8_MMA(0, 0, At, B0); PG8_MMA(0, 1, At, B1); PG8_BAR; PG8_SCHED;
;     ...
;             PG8_LDA(At, 1, 1); PG8_STAGE(PG8_SB(1, 0), b3, voffB); PG8_STAGE(PG8_SB(1, 1), b3 + hstep, voffB); PG8_STAGE(PG8_SA(1, 0), a3, voffA);
;             PG8_WAIT_V(8); PG8_WAIT_L(0); PG8_BAR; PG8_MMA(1, 0, At, B0); PG8_MMA(1, 1, At, B1); PG8_BAR; PG8_SCHED;
	s_add_i32 s56, s89, s3
	s_add_i32 s57, s56, 0x2000
	v_lshl_add_u64 v[144:145], v[0:1], 0, s[24:25]
	s_mov_b32 m0, s56
	s_add_u32 s34, s52, 0x20180
	ds_read_b128 v[200:203], v137 offset:49152
	ds_read_b128 v[204:207], v137 offset:50176
	ds_read_b128 v[208:211], v137 offset:51200
	ds_read_b128 v[212:215], v137 offset:52224
	ds_read_b128 v[216:219], v137 offset:53248
	ds_read_b128 v[220:223], v137 offset:54272
	ds_read_b128 v[224:227], v137 offset:55296
	ds_read_b128 v[228:231], v137 offset:56320
	global_load_lds_dwordx4 v[144:145], off
	v_lshl_add_u64 v[144:145], v[2:3], 0, s[24:25]
	s_mov_b32 m0, s57
	s_addc_u32 s35, s53, 0
	s_add_i32 s89, s90, s3
	global_load_lds_dwordx4 v[144:145], off
	v_lshl_add_u64 v[144:145], s[34:35], 0, v[132:133]
	s_mov_b32 m0, s89
	s_add_i32 s90, s89, 0x2000
	global_load_lds_dwordx4 v[144:145], off
	v_lshl_add_u64 v[144:145], s[34:35], 0, v[128:129]
	s_mov_b32 m0, s90
	v_lshl_add_u64 v[140:141], v[140:141], 0, s[12:13]
	global_load_lds_dwordx4 v[144:145], off
	s_mov_b32 m0, s74
	s_nop 0
	global_load_lds_dwordx4 v[140:141], off
	v_lshl_add_u64 v[140:141], v[142:143], 0, s[12:13]
	s_mov_b32 m0, s75
	s_nop 0
	global_load_lds_dwordx4 v[140:141], off
	s_waitcnt vmcnt(8)
	s_waitcnt lgkmcnt(0)
	s_barrier
	s_setprio 1
	s_waitcnt lgkmcnt(0)
	v_mfma_f32_16x16x32_bf16 v[4:7], v[28:31], v[224:227], v[4:7]
	v_mfma_f32_16x16x32_bf16 v[8:11], v[116:119], v[224:227], v[8:11]
	v_mfma_f32_16x16x32_bf16 v[162:165], v[28:31], v[200:203], v[164:167]
	v_mfma_f32_16x16x32_bf16 v[166:169], v[116:119], v[200:203], v[168:171]
	v_mfma_f32_16x16x32_bf16 v[170:173], v[28:31], v[208:211], v[172:175]
	v_mfma_f32_16x16x32_bf16 v[174:177], v[116:119], v[208:211], v[176:179]
	v_mfma_f32_16x16x32_bf16 v[178:181], v[28:31], v[216:219], v[180:183]
	v_mfma_f32_16x16x32_bf16 v[182:185], v[116:119], v[216:219], v[184:187]
	s_setprio 0
	s_setprio 1
	v_mfma_f32_16x16x32_bf16 v[4:7], v[32:35], v[228:231], v[4:7]
	v_mfma_f32_16x16x32_bf16 v[8:11], v[120:123], v[228:231], v[8:11]
	v_mfma_f32_16x16x32_bf16 v[162:165], v[32:35], v[204:207], v[162:165]
	v_mfma_f32_16x16x32_bf16 v[166:169], v[120:123], v[204:207], v[166:169]
	v_mfma_f32_16x16x32_bf16 v[170:173], v[32:35], v[212:215], v[170:173]
	v_mfma_f32_16x16x32_bf16 v[174:177], v[120:123], v[212:215], v[174:177]
	v_mfma_f32_16x16x32_bf16 v[178:181], v[32:35], v[220:223], v[178:181]
	v_mfma_f32_16x16x32_bf16 v[182:185], v[120:123], v[220:223], v[182:185]
	s_setprio 0
	s_setprio 1
	v_mfma_f32_16x16x32_bf16 v[12:15], v[124:127], v[200:203], v[12:15]
	v_mfma_f32_16x16x32_bf16 v[16:19], v[192:195], v[200:203], v[16:19]
	v_mfma_f32_16x16x32_bf16 v[28:31], v[124:127], v[208:211], v[60:63]
	v_mfma_f32_16x16x32_bf16 v[32:35], v[192:195], v[208:211], v[104:107]
	v_mfma_f32_16x16x32_bf16 v[60:63], v[124:127], v[216:219], v[108:111]
	v_mfma_f32_16x16x32_bf16 v[104:107], v[192:195], v[216:219], v[112:115]
	v_mfma_f32_16x16x32_bf16 v[20:23], v[124:127], v[224:227], v[20:23]
	v_mfma_f32_16x16x32_bf16 v[24:27], v[192:195], v[224:227], v[24:27]
	s_setprio 0
	s_setprio 1
	v_mfma_f32_16x16x32_bf16 v[12:15], v[188:191], v[204:207], v[12:15]
	v_mfma_f32_16x16x32_bf16 v[16:19], v[196:199], v[204:207], v[16:19]
	v_mfma_f32_16x16x32_bf16 v[28:31], v[188:191], v[212:215], v[28:31]
	v_mfma_f32_16x16x32_bf16 v[32:35], v[196:199], v[212:215], v[32:35]
	v_mfma_f32_16x16x32_bf16 v[60:63], v[188:191], v[220:223], v[60:63]
	v_mfma_f32_16x16x32_bf16 v[104:107], v[196:199], v[220:223], v[104:107]
	v_mfma_f32_16x16x32_bf16 v[20:23], v[188:191], v[228:231], v[20:23]
	v_mfma_f32_16x16x32_bf16 v[24:27], v[196:199], v[228:231], v[24:27]
	s_setprio 0
	s_barrier
	s_add_u32 s34, s54, 0x180
	s_addc_u32 s35, s55, 0
	s_mov_b64 s[54:55], s[50:51]
	ds_read_b128 v[108:111], v157
	ds_read_b128 v[112:115], v157 offset:1024
	ds_read_b128 v[116:119], v157 offset:2048
	ds_read_b128 v[120:123], v157 offset:3072
	ds_read_b128 v[124:127], v158
	ds_read_b128 v[186:189], v158 offset:1024
	ds_read_b128 v[190:193], v158 offset:2048
	ds_read_b128 v[194:197], v158 offset:3072
	s_add_u32 s34, s34, 0x10000
	s_addc_u32 s35, s35, 0
	s_mov_b32 m0, s83
	v_lshl_add_u64 v[140:141], s[34:35], 0, v[134:135]
	ds_read_b128 v[198:201], v137
	ds_read_b128 v[202:205], v137 offset:1024
	ds_read_b128 v[206:209], v137 offset:2048
	ds_read_b128 v[210:213], v137 offset:3072
	ds_read_b128 v[214:217], v137 offset:4096
	ds_read_b128 v[218:221], v137 offset:5120
	ds_read_b128 v[222:225], v137 offset:6144
	ds_read_b128 v[226:229], v137 offset:7168
	global_load_lds_dwordx4 v[140:141], off
	v_lshl_add_u64 v[140:141], s[34:35], 0, v[130:131]
	s_mov_b32 m0, s84
	s_nop 0
	global_load_lds_dwordx4 v[140:141], off
	s_waitcnt vmcnt(8)
	s_waitcnt lgkmcnt(0)
	s_barrier
; #define PG8_STAGE(bufoff, gbase, voff) do { _Pragma("unroll") for (int _i = 0; _i < 2; ++_i) \
;         __builtin_amdgcn_global_load_lds((const unsigned*)((const char*)(gbase) + (voff)[_i]), (LAS unsigned*)(lds + (bufoff) + ldsw + _i * 8192), 16, 0, 0); } while (0)
; #define PG8_LDA(dst, b, h) do { _Pragma("unroll") for (int m = 0; m < 4; ++m) _Pragma("unroll") for (int k = 0; k < 2; ++k) dst[m][k] = *(const LAS bf16x8*)(lds + PG8_SA(b, h) + aoff + m * 2048 + k * 1024); } while (0)
; #define PG8_MMA(ai, bj, At, Bt) do { __builtin_amdgcn_s_setprio(1); _Pragma("unroll") for (int m = 0; m < 4; ++m) _Pragma("unroll") for (int n = 0; n < 2; ++n) _Pragma("unroll") for (int k = 0; k < 2; ++k) \
;         acc[ai][bj][m][n] = __builtin_amdgcn_mfma_f32_16x16x32_bf16(Bt[n][k], At[m][k], acc[ai][bj][m][n], 0, 0, 0); __builtin_amdgcn_s_setprio(0); } while (0)
; #define PG8_WAIT_V(n) asm volatile("s_waitcnt vmcnt(" #n ")" ::: "memory")
; #define PG8_WAIT_L(n) asm volatile("s_waitcnt lgkmcnt(" #n ")" ::: "memory")
; #define PG8_BAR __builtin_amdgcn_s_barrier()
; #define PG8_SCHED __builtin_amdgcn_sched_barrier(0)
; template <class Epi, class Sched, bool ALIGN_EPI = false, bool SP2 = false, bool TWOA = false, bool AGM = false>
; __device__ __forceinline__ void gemm_phase(LAS unsigned char* lds, const Gemm g, const Sched& S, const Epi& E, int wid) {
;     ...
;             PG8_WAIT_V(8); PG8_WAIT_L(0); PG8_BAR; PG8_MMA(0, 0, At, B0); PG8_MMA(0, 1, At, B1); PG8_BAR; PG8_SCHED;
;             PG8_LDA(At, 0, 1); PG8_STAGE(PG8_SB(0, 0), b2, voffB); PG8_STAGE(PG8_SB(0, 1), b2 + hstep, voffB); PG8_STAGE(PG8_SA(0, 0), a2, voffA);
;             PG8_WAIT_V(8); PG8_WAIT_L(0); PG8_BAR; PG8_MMA(1, 0, At, B0); PG8_MMA(1, 1, At, B1); PG8_BAR; PG8_SCHED;
	s_setprio 1
	s_waitcnt lgkmcnt(0)
	v_mfma_f32_16x16x32_bf16 v[64:67], v[108:111], v[198:201], v[64:67]
	v_mfma_f32_16x16x32_bf16 v[68:71], v[116:119], v[198:201], v[68:71]
	v_mfma_f32_16x16x32_bf16 v[72:75], v[108:111], v[206:209], v[72:75]
	v_mfma_f32_16x16x32_bf16 v[76:79], v[116:119], v[206:209], v[76:79]
	v_mfma_f32_16x16x32_bf16 v[80:83], v[108:111], v[214:217], v[80:83]
	v_mfma_f32_16x16x32_bf16 v[84:87], v[116:119], v[214:217], v[84:87]
	v_mfma_f32_16x16x32_bf16 v[88:91], v[108:111], v[222:225], v[88:91]
	v_mfma_f32_16x16x32_bf16 v[64:67], v[112:115], v[202:205], v[64:67]
	s_setprio 0
	s_setprio 1
	v_mfma_f32_16x16x32_bf16 v[68:71], v[120:123], v[202:205], v[68:71]
	v_mfma_f32_16x16x32_bf16 v[72:75], v[112:115], v[210:213], v[72:75]
	v_mfma_f32_16x16x32_bf16 v[76:79], v[120:123], v[210:213], v[76:79]
	v_mfma_f32_16x16x32_bf16 v[80:83], v[112:115], v[218:221], v[80:83]
	v_mfma_f32_16x16x32_bf16 v[84:87], v[120:123], v[218:221], v[84:87]
	v_mfma_f32_16x16x32_bf16 v[230:233], v[112:115], v[226:229], v[88:91]
	v_mfma_f32_16x16x32_bf16 v[88:91], v[116:119], v[222:225], v[92:95]
	v_mfma_f32_16x16x32_bf16 v[234:237], v[120:123], v[226:229], v[88:91]
	s_setprio 0
	s_setprio 1
	v_mfma_f32_16x16x32_bf16 v[88:91], v[124:127], v[198:201], v[96:99]
	v_mfma_f32_16x16x32_bf16 v[96:99], v[186:189], v[202:205], v[88:91]
	v_mfma_f32_16x16x32_bf16 v[36:39], v[190:193], v[198:201], v[36:39]
	v_mfma_f32_16x16x32_bf16 v[88:91], v[124:127], v[206:209], v[100:103]
	v_mfma_f32_16x16x32_bf16 v[40:43], v[190:193], v[206:209], v[40:43]
	v_mfma_f32_16x16x32_bf16 v[44:47], v[124:127], v[214:217], v[44:47]
	v_mfma_f32_16x16x32_bf16 v[48:51], v[190:193], v[214:217], v[48:51]
	v_mfma_f32_16x16x32_bf16 v[52:55], v[124:127], v[222:225], v[52:55]
	s_setprio 0
	s_setprio 1
	v_mfma_f32_16x16x32_bf16 v[56:59], v[190:193], v[222:225], v[56:59]
	v_mfma_f32_16x16x32_bf16 v[36:39], v[194:197], v[202:205], v[36:39]
	v_mfma_f32_16x16x32_bf16 v[100:103], v[186:189], v[210:213], v[88:91]
	v_mfma_f32_16x16x32_bf16 v[40:43], v[194:197], v[210:213], v[40:43]
	v_mfma_f32_16x16x32_bf16 v[44:47], v[186:189], v[218:221], v[44:47]
	v_mfma_f32_16x16x32_bf16 v[48:51], v[194:197], v[218:221], v[48:51]
	v_mfma_f32_16x16x32_bf16 v[52:55], v[186:189], v[226:229], v[52:55]
	v_mfma_f32_16x16x32_bf16 v[56:59], v[194:197], v[226:229], v[56:59]
	s_setprio 0
	s_barrier
	s_mov_b32 m0, s85
	v_lshl_add_u64 v[140:141], v[0:1], 0, s[26:27]
	s_add_u32 s34, s52, 0x20200
	ds_read_b128 v[88:91], v137 offset:16384
	ds_read_b128 v[92:95], v137 offset:17408
	ds_read_b128 v[198:201], v137 offset:18432
	ds_read_b128 v[202:205], v137 offset:19456
	ds_read_b128 v[206:209], v137 offset:20480
	ds_read_b128 v[210:213], v137 offset:21504
	ds_read_b128 v[214:217], v137 offset:22528
	ds_read_b128 v[218:221], v137 offset:23552
	global_load_lds_dwordx4 v[140:141], off
	v_lshl_add_u64 v[140:141], v[2:3], 0, s[26:27]
	s_mov_b32 m0, s86
	s_addc_u32 s35, s53, 0
	global_load_lds_dwordx4 v[140:141], off
	v_lshl_add_u64 v[140:141], s[34:35], 0, v[132:133]
	s_mov_b32 m0, s87
	v_lshl_add_u64 v[148:149], s[54:55], 0, v[134:135]
	global_load_lds_dwordx4 v[140:141], off
	v_lshl_add_u64 v[140:141], s[34:35], 0, v[128:129]
	s_mov_b32 m0, s88
	v_lshl_add_u64 v[150:151], s[54:55], 0, v[130:131]
	global_load_lds_dwordx4 v[140:141], off
	s_mov_b32 m0, s45
	s_nop 0
	global_load_lds_dwordx4 v[148:149], off
	s_mov_b32 m0, s47
	s_nop 0
	global_load_lds_dwordx4 v[150:151], off
	s_waitcnt vmcnt(8)
	s_waitcnt lgkmcnt(0)
	s_barrier
	s_setprio 1
	s_waitcnt lgkmcnt(0)
	v_mfma_f32_16x16x32_bf16 v[4:7], v[108:111], v[214:217], v[4:7]
	v_mfma_f32_16x16x32_bf16 v[8:11], v[116:119], v[214:217], v[8:11]
	v_mfma_f32_16x16x32_bf16 v[162:165], v[108:111], v[88:91], v[162:165]
	v_mfma_f32_16x16x32_bf16 v[166:169], v[116:119], v[88:91], v[166:169]
	v_mfma_f32_16x16x32_bf16 v[170:173], v[108:111], v[198:201], v[170:173]
	v_mfma_f32_16x16x32_bf16 v[174:177], v[116:119], v[198:201], v[174:177]
	v_mfma_f32_16x16x32_bf16 v[178:181], v[108:111], v[206:209], v[178:181]
	v_mfma_f32_16x16x32_bf16 v[182:185], v[116:119], v[206:209], v[182:185]
	s_setprio 0
	s_setprio 1
	v_mfma_f32_16x16x32_bf16 v[4:7], v[112:115], v[218:221], v[4:7]
	v_mfma_f32_16x16x32_bf16 v[8:11], v[120:123], v[218:221], v[8:11]
	v_mfma_f32_16x16x32_bf16 v[162:165], v[112:115], v[92:95], v[162:165]
	v_mfma_f32_16x16x32_bf16 v[166:169], v[120:123], v[92:95], v[166:169]
	v_mfma_f32_16x16x32_bf16 v[170:173], v[112:115], v[202:205], v[170:173]
	v_mfma_f32_16x16x32_bf16 v[174:177], v[120:123], v[202:205], v[174:177]
	v_mfma_f32_16x16x32_bf16 v[178:181], v[112:115], v[210:213], v[178:181]
	v_mfma_f32_16x16x32_bf16 v[182:185], v[120:123], v[210:213], v[182:185]
	s_setprio 0
	s_setprio 1
	v_mfma_f32_16x16x32_bf16 v[12:15], v[124:127], v[88:91], v[12:15]
	v_mfma_f32_16x16x32_bf16 v[222:225], v[186:189], v[92:95], v[12:15]
	v_mfma_f32_16x16x32_bf16 v[12:15], v[190:193], v[88:91], v[16:19]
	v_mfma_f32_16x16x32_bf16 v[16:19], v[194:197], v[92:95], v[12:15]
	v_mfma_f32_16x16x32_bf16 v[12:15], v[124:127], v[198:201], v[28:31]
	v_mfma_f32_16x16x32_bf16 v[226:229], v[186:189], v[202:205], v[12:15]
	v_mfma_f32_16x16x32_bf16 v[12:15], v[190:193], v[198:201], v[32:35]
	v_mfma_f32_16x16x32_bf16 v[32:35], v[194:197], v[202:205], v[12:15]
	s_setprio 0
	s_setprio 1
	v_mfma_f32_16x16x32_bf16 v[12:15], v[124:127], v[206:209], v[60:63]
	v_mfma_f32_16x16x32_bf16 v[198:201], v[186:189], v[210:213], v[12:15]
	v_mfma_f32_16x16x32_bf16 v[12:15], v[190:193], v[206:209], v[104:107]
	v_mfma_f32_16x16x32_bf16 v[202:205], v[194:197], v[210:213], v[12:15]
	v_mfma_f32_16x16x32_bf16 v[12:15], v[124:127], v[214:217], v[20:23]
	v_mfma_f32_16x16x32_bf16 v[186:189], v[186:189], v[218:221], v[12:15]
	v_mfma_f32_16x16x32_bf16 v[12:15], v[190:193], v[214:217], v[24:27]
	v_mfma_f32_16x16x32_bf16 v[190:193], v[194:197], v[218:221], v[12:15]
	s_setprio 0
	s_barrier
; #define PG8_STAGE(bufoff, gbase, voff) do { _Pragma("unroll") for (int _i = 0; _i < 2; ++_i) \
;         __builtin_amdgcn_global_load_lds((const unsigned*)((const char*)(gbase) + (voff)[_i]), (LAS unsigned*)(lds + (bufoff) + ldsw + _i * 8192), 16, 0, 0); } while (0)
; #define PG8_LDA(dst, b, h) do { _Pragma("unroll") for (int m = 0; m < 4; ++m) _Pragma("unroll") for (int k = 0; k < 2; ++k) dst[m][k] = *(const LAS bf16x8*)(lds + PG8_SA(b, h) + aoff + m * 2048 + k * 1024); } while (0)
; #define PG8_LDB(dst, b, h) do { _Pragma("unroll") for (int n = 0; n < 2; ++n) _Pragma("unroll") for (int k = 0; k < 2; ++k) dst[n][k] = *(const LAS bf16x8*)(lds + PG8_SB(b, h) + boff + n * 2048 + k * 1024); } while (0)
; #define PG8_MMA(ai, bj, At, Bt) do { __builtin_amdgcn_s_setprio(1); _Pragma("unroll") for (int m = 0; m < 4; ++m) _Pragma("unroll") for (int n = 0; n < 2; ++n) _Pragma("unroll") for (int k = 0; k < 2; ++k) \
;         acc[ai][bj][m][n] = __builtin_amdgcn_mfma_f32_16x16x32_bf16(Bt[n][k], At[m][k], acc[ai][bj][m][n], 0, 0, 0); __builtin_amdgcn_s_setprio(0); } while (0)
; #define PG8_WAIT_V(n) asm volatile("s_waitcnt vmcnt(" #n ")" ::: "memory")
; #define PG8_WAIT_L(n) asm volatile("s_waitcnt lgkmcnt(" #n ")" ::: "memory")
; #define PG8_BAR __builtin_amdgcn_s_barrier()
; #define PG8_SCHED __builtin_amdgcn_sched_barrier(0)
; template <class Epi, class Sched, bool ALIGN_EPI = false, bool SP2 = false, bool TWOA = false, bool AGM = false>
; __device__ __forceinline__ void gemm_phase(LAS unsigned char* lds, const Gemm g, const Sched& S, const Epi& E, int wid) {
;     ...
;             PG8_LDB(B0, 1, 0); PG8_LDB(B1, 1, 1); PG8_SCHED; PG8_LDA(At, 1, 0); PG8_STAGE(PG8_SA(0, 1), a2 + hstepA, voffA);
;             PG8_WAIT_V(8); PG8_WAIT_L(0); PG8_BAR; PG8_MMA(0, 0, At, B0); PG8_MMA(0, 1, At, B1); PG8_BAR; PG8_SCHED;
;             PG8_LDA(At, 1, 1); PG8_STAGE(PG8_SB(1, 0), b3, voffB); PG8_STAGE(PG8_SB(1, 1), b3 + hstep, voffB); PG8_STAGE(PG8_SA(1, 0), a3, voffA);
;             PG8_WAIT_V(8); PG8_WAIT_L(0); PG8_BAR; PG8_MMA(1, 0, At, B0); PG8_MMA(1, 1, At, B1); PG8_BAR; PG8_SCHED;
	s_nop 4
	ds_read_b128 v[12:15], v159
	ds_read_b128 v[20:23], v159 offset:1024
	ds_read_b128 v[194:197], v159 offset:2048
	ds_read_b128 v[206:209], v159 offset:3072
	ds_read_b128 v[210:213], v160
	ds_read_b128 v[214:217], v160 offset:1024
	ds_read_b128 v[218:221], v160 offset:2048
	ds_read_b128 v[238:241], v160 offset:3072
	s_add_u32 s34, s54, 0x10000
	s_addc_u32 s35, s55, 0
	s_mov_b32 m0, s70
	v_lshl_add_u64 v[88:89], s[34:35], 0, v[134:135]
	ds_read_b128 v[24:27], v137 offset:32768
	ds_read_b128 v[28:31], v137 offset:33792
	ds_read_b128 v[60:63], v137 offset:34816
	ds_read_b128 v[242:245], v137 offset:35840
	ds_read_b128 v[246:249], v137 offset:36864
	ds_read_b128 v[250:253], v137 offset:37888
	ds_read_b128 v[140:143], v137 offset:38912
	ds_read_b128 v[144:147], v137 offset:39936
	global_load_lds_dwordx4 v[88:89], off
	v_lshl_add_u64 v[88:89], s[34:35], 0, v[130:131]
	s_mov_b32 m0, s71
	s_nop 0
	global_load_lds_dwordx4 v[88:89], off
	s_waitcnt vmcnt(8)
	s_waitcnt lgkmcnt(0)
	s_barrier
	s_setprio 1
	s_waitcnt lgkmcnt(0)
	v_mfma_f32_16x16x32_bf16 v[64:67], v[12:15], v[24:27], v[64:67]
	v_mfma_f32_16x16x32_bf16 v[124:127], v[20:23], v[28:31], v[64:67]
	v_mfma_f32_16x16x32_bf16 v[64:67], v[194:197], v[24:27], v[68:71]
	v_mfma_f32_16x16x32_bf16 v[120:123], v[206:209], v[28:31], v[64:67]
	v_mfma_f32_16x16x32_bf16 v[64:67], v[12:15], v[60:63], v[72:75]
	v_mfma_f32_16x16x32_bf16 v[108:111], v[20:23], v[242:245], v[64:67]
	v_mfma_f32_16x16x32_bf16 v[64:67], v[194:197], v[60:63], v[76:79]
	v_mfma_f32_16x16x32_bf16 v[104:107], v[206:209], v[242:245], v[64:67]
	s_setprio 0
	s_setprio 1
	v_mfma_f32_16x16x32_bf16 v[64:67], v[12:15], v[246:249], v[80:83]
	v_mfma_f32_16x16x32_bf16 v[92:95], v[20:23], v[250:253], v[64:67]
	v_mfma_f32_16x16x32_bf16 v[64:67], v[194:197], v[246:249], v[84:87]
	v_mfma_f32_16x16x32_bf16 v[88:91], v[206:209], v[250:253], v[64:67]
	v_mfma_f32_16x16x32_bf16 v[64:67], v[12:15], v[140:143], v[230:233]
	v_mfma_f32_16x16x32_bf16 v[76:79], v[20:23], v[144:147], v[64:67]
	v_mfma_f32_16x16x32_bf16 v[64:67], v[194:197], v[140:143], v[234:237]
	v_mfma_f32_16x16x32_bf16 v[72:75], v[206:209], v[144:147], v[64:67]
	s_setprio 0
	s_setprio 1
	v_mfma_f32_16x16x32_bf16 v[64:67], v[210:213], v[24:27], v[96:99]
	v_mfma_f32_16x16x32_bf16 v[24:27], v[218:221], v[24:27], v[36:39]
	v_mfma_f32_16x16x32_bf16 v[112:115], v[238:241], v[28:31], v[24:27]
	v_mfma_f32_16x16x32_bf16 v[24:27], v[210:213], v[60:63], v[100:103]
	v_mfma_f32_16x16x32_bf16 v[100:103], v[214:217], v[242:245], v[24:27]
	v_mfma_f32_16x16x32_bf16 v[24:27], v[218:221], v[60:63], v[40:43]
	v_mfma_f32_16x16x32_bf16 v[96:99], v[238:241], v[242:245], v[24:27]
	v_mfma_f32_16x16x32_bf16 v[24:27], v[210:213], v[246:249], v[44:47]
	s_setprio 0
	s_setprio 1
	v_mfma_f32_16x16x32_bf16 v[84:87], v[214:217], v[250:253], v[24:27]
	v_mfma_f32_16x16x32_bf16 v[24:27], v[218:221], v[246:249], v[48:51]
	v_mfma_f32_16x16x32_bf16 v[80:83], v[238:241], v[250:253], v[24:27]
	v_mfma_f32_16x16x32_bf16 v[24:27], v[210:213], v[140:143], v[52:55]
	v_mfma_f32_16x16x32_bf16 v[68:71], v[214:217], v[144:147], v[24:27]
	v_mfma_f32_16x16x32_bf16 v[24:27], v[218:221], v[140:143], v[56:59]
	v_mfma_f32_16x16x32_bf16 v[116:119], v[214:217], v[28:31], v[64:67]
	v_mfma_f32_16x16x32_bf16 v[64:67], v[238:241], v[144:147], v[24:27]
	s_setprio 0
	s_barrier
	s_mov_b32 m0, s56
	v_lshl_add_u64 v[0:1], v[0:1], 0, s[28:29]
	s_add_u32 s34, s52, 0x20280
	ds_read_b128 v[36:39], v137 offset:49152
	ds_read_b128 v[48:51], v137 offset:50176
	ds_read_b128 v[140:143], v137 offset:51200
	ds_read_b128 v[144:147], v137 offset:52224
	ds_read_b128 v[230:233], v137 offset:53248
	ds_read_b128 v[234:237], v137 offset:54272
	ds_read_b128 v[242:245], v137 offset:55296
	ds_read_b128 v[246:249], v137 offset:56320
	global_load_lds_dwordx4 v[0:1], off
	v_lshl_add_u64 v[0:1], v[2:3], 0, s[28:29]
	s_mov_b32 m0, s57
	s_addc_u32 s35, s53, 0
	global_load_lds_dwordx4 v[0:1], off
	v_lshl_add_u64 v[0:1], s[34:35], 0, v[132:133]
	s_mov_b32 m0, s89
	s_nop 0
	global_load_lds_dwordx4 v[0:1], off
	v_lshl_add_u64 v[0:1], s[34:35], 0, v[128:129]
	s_mov_b32 m0, s90
	s_nop 0
	global_load_lds_dwordx4 v[0:1], off
	v_lshl_add_u64 v[0:1], v[148:149], 0, s[12:13]
	s_mov_b32 m0, s74
	s_nop 0
	global_load_lds_dwordx4 v[0:1], off
	v_lshl_add_u64 v[0:1], v[150:151], 0, s[12:13]
	s_mov_b32 m0, s75
	s_nop 0
	global_load_lds_dwordx4 v[0:1], off
	s_waitcnt vmcnt(8)
	s_waitcnt lgkmcnt(0)
	s_barrier
	s_setprio 1
	s_waitcnt lgkmcnt(0)
	v_mfma_f32_16x16x32_bf16 v[0:3], v[12:15], v[36:39], v[162:165]
	v_mfma_f32_16x16x32_bf16 v[60:63], v[20:23], v[48:51], v[0:3]
	v_mfma_f32_16x16x32_bf16 v[0:3], v[194:197], v[36:39], v[166:169]
	v_mfma_f32_16x16x32_bf16 v[56:59], v[206:209], v[48:51], v[0:3]
	v_mfma_f32_16x16x32_bf16 v[0:3], v[12:15], v[140:143], v[170:173]
	v_mfma_f32_16x16x32_bf16 v[44:47], v[20:23], v[144:147], v[0:3]
	v_mfma_f32_16x16x32_bf16 v[0:3], v[194:197], v[140:143], v[174:177]
	v_mfma_f32_16x16x32_bf16 v[40:43], v[206:209], v[144:147], v[0:3]
	s_setprio 0
	s_setprio 1
	v_mfma_f32_16x16x32_bf16 v[0:3], v[12:15], v[230:233], v[178:181]
	v_mfma_f32_16x16x32_bf16 v[28:31], v[20:23], v[234:237], v[0:3]
	v_mfma_f32_16x16x32_bf16 v[0:3], v[194:197], v[230:233], v[182:185]
	v_mfma_f32_16x16x32_bf16 v[24:27], v[206:209], v[234:237], v[0:3]
	v_mfma_f32_16x16x32_bf16 v[0:3], v[12:15], v[242:245], v[4:7]
	v_mfma_f32_16x16x32_bf16 v[12:15], v[20:23], v[246:249], v[0:3]
	v_mfma_f32_16x16x32_bf16 v[0:3], v[194:197], v[242:245], v[8:11]
	v_mfma_f32_16x16x32_bf16 v[8:11], v[206:209], v[246:249], v[0:3]
	s_setprio 0
	s_setprio 1
	v_mfma_f32_16x16x32_bf16 v[0:3], v[210:213], v[36:39], v[222:225]
	v_mfma_f32_16x16x32_bf16 v[52:55], v[214:217], v[48:51], v[0:3]
	v_mfma_f32_16x16x32_bf16 v[0:3], v[218:221], v[36:39], v[16:19]
	v_mfma_f32_16x16x32_bf16 v[48:51], v[238:241], v[48:51], v[0:3]
	v_mfma_f32_16x16x32_bf16 v[0:3], v[210:213], v[140:143], v[226:229]
	v_mfma_f32_16x16x32_bf16 v[36:39], v[214:217], v[144:147], v[0:3]
	v_mfma_f32_16x16x32_bf16 v[0:3], v[218:221], v[140:143], v[32:35]
	v_mfma_f32_16x16x32_bf16 v[32:35], v[238:241], v[144:147], v[0:3]
	s_setprio 0
	s_setprio 1
	v_mfma_f32_16x16x32_bf16 v[0:3], v[210:213], v[230:233], v[198:201]
	v_mfma_f32_16x16x32_bf16 v[20:23], v[214:217], v[234:237], v[0:3]
	v_mfma_f32_16x16x32_bf16 v[0:3], v[218:221], v[230:233], v[202:205]
	v_mfma_f32_16x16x32_bf16 v[16:19], v[238:241], v[234:237], v[0:3]
	v_mfma_f32_16x16x32_bf16 v[0:3], v[210:213], v[242:245], v[186:189]
	v_mfma_f32_16x16x32_bf16 v[4:7], v[214:217], v[246:249], v[0:3]
	v_mfma_f32_16x16x32_bf16 v[0:3], v[218:221], v[242:245], v[190:193]
	v_mfma_f32_16x16x32_bf16 v[0:3], v[238:241], v[246:249], v[0:3]
	s_setprio 0
	s_barrier
	s_add_u32 s91, s52, 0x300
	s_addc_u32 s92, s53, 0
	s_mov_b32 s93, 2
; #define PG8_STAGE(bufoff, gbase, voff) do { _Pragma("unroll") for (int _i = 0; _i < 2; ++_i) \
;         __builtin_amdgcn_global_load_lds((const unsigned*)((const char*)(gbase) + (voff)[_i]), (LAS unsigned*)(lds + (bufoff) + ldsw + _i * 8192), 16, 0, 0); } while (0)
; #define PG8_LDA(dst, b, h) do { _Pragma("unroll") for (int m = 0; m < 4; ++m) _Pragma("unroll") for (int k = 0; k < 2; ++k) dst[m][k] = *(const LAS bf16x8*)(lds + PG8_SA(b, h) + aoff + m * 2048 + k * 1024); } while (0)
; #define PG8_WAIT_V(n) asm volatile("s_waitcnt vmcnt(" #n ")" ::: "memory")
; #define PG8_BAR __builtin_amdgcn_s_barrier()
; template <class Epi, class Sched, bool ALIGN_EPI = false, bool SP2 = false, bool TWOA = false, bool AGM = false>
; __device__ __forceinline__ void gemm_phase(LAS unsigned char* lds, const Gemm g, const Sched& S, const Epi& E, int wid) {
;     ...
;         const char* nA = has_next ? (const char*)g.A + (size_t)nxt.pm * tstepA : cA; const char* nB = has_next ? (const char*)g.Bt + (size_t)nxt.pn * tstep : cB;
;         for (int t = 0; t < nt; t += 2) {
;             const bool last = (t == nt - 2);
;             const char* cA2 = TWOA ? (const char*)g.A2 + (cA - (const char*)g.A) - (size_t)nh * kstepA : cA;
;             const char* a1_ = (TWOA && t + 1 >= nh ? cA2 : cA) + (size_t)(t + 1) * kstepA;
;             const char* a2_ = last ? nA : (TWOA && t + 2 >= nh ? cA2 : cA) + (size_t)(t + 2) * kstepA; const char* a1 = a1_; const char* a2 = a2_; const char* b2 = last ? nB : cB + (size_t)(t + 2) * kstep;
;             if constexpr (TWOA) { asm volatile("" : "+s"(a1)); asm volatile("" : "+s"(a2)); }
;             const char* a3 = a2 + kstepA; const char* b3 = b2 + kstep;
;             if (last && has_next) S.a_ready(nxt);
;             if constexpr (has_mid<Epi>::value) { if (t == nh) E.mid(acc, cur, wr, wc, fr, fq); }
;             if constexpr (SP2) {
;             PG8_LDB(B0, 0, 0); PG8_LDB(B1, 0, 1); PG8_SCHED; PG8_LDA(At, 0, 0); PG8_STAGE(PG8_SA(1, 1), a1 + hstepA, voffA);
;             PG8_WAIT_V(8); PG8_WAIT_L(0); PG8_BAR; PG8_MMA(0, 0, At, B0); PG8_MMA(0, 1, At, B1); PG8_BAR; PG8_SCHED;
;             PG8_LDA(At, 0, 1); PG8_STAGE(PG8_SB(0, 0), b2, voffB); PG8_STAGE(PG8_SB(0, 1), b2 + hstep, voffB); PG8_STAGE(PG8_SA(0, 0), a2, voffA);
;             PG8_WAIT_V(8); PG8_WAIT_L(0); PG8_BAR; PG8_MMA(1, 0, At, B0); PG8_MMA(1, 1, At, B1); PG8_BAR; PG8_SCHED;
.LBB0_683:
	s_add_u32 s34, s50, 0x80
	s_addc_u32 s35, s51, 0
	s_add_u32 s50, s50, 0x100
	s_addc_u32 s51, s51, 0
	s_cmp_eq_u32 s93, 4
	s_cselect_b32 s55, s37, s51
	s_cselect_b32 s54, s80, s50
	ds_read_b128 v[140:143], v157
	ds_read_b128 v[144:147], v157 offset:1024
	ds_read_b128 v[162:165], v157 offset:2048
	ds_read_b128 v[166:169], v157 offset:3072
	ds_read_b128 v[170:173], v158
	ds_read_b128 v[174:177], v158 offset:1024
	ds_read_b128 v[178:181], v158 offset:2048
	ds_read_b128 v[182:185], v158 offset:3072
	s_cselect_b32 s53, s31, s92
	s_cselect_b32 s52, s82, s91
	s_add_u32 s34, s34, 0x10000
	s_addc_u32 s35, s35, 0
	s_mov_b32 m0, s83
	v_lshl_add_u64 v[148:149], s[34:35], 0, v[134:135]
	ds_read_b128 v[186:189], v137
	ds_read_b128 v[190:193], v137 offset:1024
	ds_read_b128 v[194:197], v137 offset:2048
	ds_read_b128 v[198:201], v137 offset:3072
	ds_read_b128 v[202:205], v137 offset:4096
	ds_read_b128 v[206:209], v137 offset:5120
	ds_read_b128 v[210:213], v137 offset:6144
	ds_read_b128 v[214:217], v137 offset:7168
	global_load_lds_dwordx4 v[148:149], off
	v_lshl_add_u64 v[148:149], s[34:35], 0, v[130:131]
	s_mov_b32 m0, s84
	s_nop 0
	global_load_lds_dwordx4 v[148:149], off
	s_waitcnt vmcnt(8)
	s_waitcnt lgkmcnt(0)
	s_barrier
	s_setprio 1
	s_waitcnt lgkmcnt(0)
	v_mfma_f32_16x16x32_bf16 v[124:127], v[140:143], v[186:189], v[124:127]
	v_mfma_f32_16x16x32_bf16 v[120:123], v[162:165], v[186:189], v[120:123]
	v_mfma_f32_16x16x32_bf16 v[108:111], v[140:143], v[194:197], v[108:111]
	v_mfma_f32_16x16x32_bf16 v[104:107], v[162:165], v[194:197], v[104:107]
	v_mfma_f32_16x16x32_bf16 v[92:95], v[140:143], v[202:205], v[92:95]
	v_mfma_f32_16x16x32_bf16 v[88:91], v[162:165], v[202:205], v[88:91]
	v_mfma_f32_16x16x32_bf16 v[76:79], v[140:143], v[210:213], v[76:79]
	v_mfma_f32_16x16x32_bf16 v[72:75], v[162:165], v[210:213], v[72:75]
	s_setprio 0
	s_setprio 1
	v_mfma_f32_16x16x32_bf16 v[124:127], v[144:147], v[190:193], v[124:127]
	v_mfma_f32_16x16x32_bf16 v[120:123], v[166:169], v[190:193], v[120:123]
	v_mfma_f32_16x16x32_bf16 v[108:111], v[144:147], v[198:201], v[108:111]
	v_mfma_f32_16x16x32_bf16 v[104:107], v[166:169], v[198:201], v[104:107]
	v_mfma_f32_16x16x32_bf16 v[92:95], v[144:147], v[206:209], v[92:95]
	v_mfma_f32_16x16x32_bf16 v[88:91], v[166:169], v[206:209], v[88:91]
	v_mfma_f32_16x16x32_bf16 v[76:79], v[144:147], v[214:217], v[76:79]
	v_mfma_f32_16x16x32_bf16 v[72:75], v[166:169], v[214:217], v[72:75]
	s_setprio 0
	s_setprio 1
	v_mfma_f32_16x16x32_bf16 v[116:119], v[170:173], v[186:189], v[116:119]
	v_mfma_f32_16x16x32_bf16 v[112:115], v[178:181], v[186:189], v[112:115]
	v_mfma_f32_16x16x32_bf16 v[100:103], v[170:173], v[194:197], v[100:103]
	v_mfma_f32_16x16x32_bf16 v[96:99], v[178:181], v[194:197], v[96:99]
	v_mfma_f32_16x16x32_bf16 v[84:87], v[170:173], v[202:205], v[84:87]
	v_mfma_f32_16x16x32_bf16 v[80:83], v[178:181], v[202:205], v[80:83]
	v_mfma_f32_16x16x32_bf16 v[68:71], v[170:173], v[210:213], v[68:71]
	v_mfma_f32_16x16x32_bf16 v[64:67], v[178:181], v[210:213], v[64:67]
	s_setprio 0
	s_setprio 1
	v_mfma_f32_16x16x32_bf16 v[116:119], v[174:177], v[190:193], v[116:119]
	v_mfma_f32_16x16x32_bf16 v[112:115], v[182:185], v[190:193], v[112:115]
	v_mfma_f32_16x16x32_bf16 v[100:103], v[174:177], v[198:201], v[100:103]
	v_mfma_f32_16x16x32_bf16 v[96:99], v[182:185], v[198:201], v[96:99]
	v_mfma_f32_16x16x32_bf16 v[84:87], v[174:177], v[206:209], v[84:87]
	v_mfma_f32_16x16x32_bf16 v[80:83], v[182:185], v[206:209], v[80:83]
	v_mfma_f32_16x16x32_bf16 v[68:71], v[174:177], v[214:217], v[68:71]
	v_mfma_f32_16x16x32_bf16 v[64:67], v[182:185], v[214:217], v[64:67]
	s_setprio 0
	s_barrier
	s_mov_b32 m0, s85
	v_lshl_add_u64 v[148:149], s[52:53], 0, v[132:133]
	s_add_u32 s34, s52, 0x20000
	ds_read_b128 v[186:189], v137 offset:16384
	ds_read_b128 v[190:193], v137 offset:17408
	ds_read_b128 v[194:197], v137 offset:18432
	ds_read_b128 v[198:201], v137 offset:19456
	ds_read_b128 v[202:205], v137 offset:20480
	ds_read_b128 v[206:209], v137 offset:21504
	ds_read_b128 v[210:213], v137 offset:22528
	ds_read_b128 v[214:217], v137 offset:23552
	global_load_lds_dwordx4 v[148:149], off
	v_lshl_add_u64 v[150:151], s[52:53], 0, v[128:129]
	s_mov_b32 m0, s86
	s_addc_u32 s35, s53, 0
	global_load_lds_dwordx4 v[150:151], off
	v_lshl_add_u64 v[218:219], s[34:35], 0, v[132:133]
	s_mov_b32 m0, s87
	v_lshl_add_u64 v[220:221], s[54:55], 0, v[130:131]
	global_load_lds_dwordx4 v[218:219], off
	v_lshl_add_u64 v[218:219], s[34:35], 0, v[128:129]
	s_mov_b32 m0, s88
	s_nop 0
	global_load_lds_dwordx4 v[218:219], off
	v_lshl_add_u64 v[218:219], s[54:55], 0, v[134:135]
	s_mov_b32 m0, s45
	s_nop 0
	global_load_lds_dwordx4 v[218:219], off
	s_mov_b32 m0, s47
	s_nop 0
	global_load_lds_dwordx4 v[220:221], off
	s_waitcnt vmcnt(8)
	s_waitcnt lgkmcnt(0)
	s_barrier
; #define PG8_STAGE(bufoff, gbase, voff) do { _Pragma("unroll") for (int _i = 0; _i < 2; ++_i) \
;         __builtin_amdgcn_global_load_lds((const unsigned*)((const char*)(gbase) + (voff)[_i]), (LAS unsigned*)(lds + (bufoff) + ldsw + _i * 8192), 16, 0, 0); } while (0)
; #define PG8_LDA(dst, b, h) do { _Pragma("unroll") for (int m = 0; m < 4; ++m) _Pragma("unroll") for (int k = 0; k < 2; ++k) dst[m][k] = *(const LAS bf16x8*)(lds + PG8_SA(b, h) + aoff + m * 2048 + k * 1024); } while (0)
; #define PG8_LDB(dst, b, h) do { _Pragma("unroll") for (int n = 0; n < 2; ++n) _Pragma("unroll") for (int k = 0; k < 2; ++k) dst[n][k] = *(const LAS bf16x8*)(lds + PG8_SB(b, h) + boff + n * 2048 + k * 1024); } while (0)
; #define PG8_MMA(ai, bj, At, Bt) do { __builtin_amdgcn_s_setprio(1); _Pragma("unroll") for (int m = 0; m < 4; ++m) _Pragma("unroll") for (int n = 0; n < 2; ++n) _Pragma("unroll") for (int k = 0; k < 2; ++k) \
;         acc[ai][bj][m][n] = __builtin_amdgcn_mfma_f32_16x16x32_bf16(Bt[n][k], At[m][k], acc[ai][bj][m][n], 0, 0, 0); __builtin_amdgcn_s_setprio(0); } while (0)
; #define PG8_WAIT_V(n) asm volatile("s_waitcnt vmcnt(" #n ")" ::: "memory")
; #define PG8_WAIT_L(n) asm volatile("s_waitcnt lgkmcnt(" #n ")" ::: "memory")
; template <class Epi, class Sched, bool ALIGN_EPI = false, bool SP2 = false, bool TWOA = false, bool AGM = false>
; __device__ __forceinline__ void gemm_phase(LAS unsigned char* lds, const Gemm g, const Sched& S, const Epi& E, int wid) {
;     ...
;             PG8_WAIT_V(8); PG8_WAIT_L(0); PG8_BAR; PG8_MMA(0, 0, At, B0); PG8_MMA(0, 1, At, B1); PG8_BAR; PG8_SCHED;
;             PG8_LDA(At, 0, 1); PG8_STAGE(PG8_SB(0, 0), b2, voffB); PG8_STAGE(PG8_SB(0, 1), b2 + hstep, voffB); PG8_STAGE(PG8_SA(0, 0), a2, voffA);
;             PG8_WAIT_V(8); PG8_WAIT_L(0); PG8_BAR; PG8_MMA(1, 0, At, B0); PG8_MMA(1, 1, At, B1); PG8_BAR; PG8_SCHED;
;             PG8_LDB(B0, 1, 0); PG8_LDB(B1, 1, 1); PG8_SCHED; PG8_LDA(At, 1, 0); PG8_STAGE(PG8_SA(0, 1), a2 + hstepA, voffA);
;             PG8_WAIT_V(8); PG8_WAIT_L(0); PG8_BAR; PG8_MMA(0, 0, At, B0); PG8_MMA(0, 1, At, B1); PG8_BAR; PG8_SCHED;
;             PG8_LDA(At, 1, 1); PG8_STAGE(PG8_SB(1, 0), b3, voffB); PG8_STAGE(PG8_SB(1, 1), b3 + hstep, voffB); PG8_STAGE(PG8_SA(1, 0), a3, voffA);
;             PG8_WAIT_V(8); PG8_WAIT_L(0); PG8_BAR; PG8_MMA(1, 0, At, B0); PG8_MMA(1, 1, At, B1); PG8_BAR; PG8_SCHED;
	s_setprio 1
	s_waitcnt lgkmcnt(0)
	v_mfma_f32_16x16x32_bf16 v[60:63], v[140:143], v[186:189], v[60:63]
	v_mfma_f32_16x16x32_bf16 v[56:59], v[162:165], v[186:189], v[56:59]
	v_mfma_f32_16x16x32_bf16 v[44:47], v[140:143], v[194:197], v[44:47]
	v_mfma_f32_16x16x32_bf16 v[40:43], v[162:165], v[194:197], v[40:43]
	v_mfma_f32_16x16x32_bf16 v[28:31], v[140:143], v[202:205], v[28:31]
	v_mfma_f32_16x16x32_bf16 v[24:27], v[162:165], v[202:205], v[24:27]
	v_mfma_f32_16x16x32_bf16 v[12:15], v[140:143], v[210:213], v[12:15]
	v_mfma_f32_16x16x32_bf16 v[8:11], v[162:165], v[210:213], v[8:11]
	s_setprio 0
	s_setprio 1
	v_mfma_f32_16x16x32_bf16 v[60:63], v[144:147], v[190:193], v[60:63]
	v_mfma_f32_16x16x32_bf16 v[56:59], v[166:169], v[190:193], v[56:59]
	v_mfma_f32_16x16x32_bf16 v[44:47], v[144:147], v[198:201], v[44:47]
	v_mfma_f32_16x16x32_bf16 v[40:43], v[166:169], v[198:201], v[40:43]
	v_mfma_f32_16x16x32_bf16 v[28:31], v[144:147], v[206:209], v[28:31]
	v_mfma_f32_16x16x32_bf16 v[24:27], v[166:169], v[206:209], v[24:27]
	v_mfma_f32_16x16x32_bf16 v[12:15], v[144:147], v[214:217], v[12:15]
	v_mfma_f32_16x16x32_bf16 v[8:11], v[166:169], v[214:217], v[8:11]
	s_setprio 0
	s_setprio 1
	v_mfma_f32_16x16x32_bf16 v[52:55], v[170:173], v[186:189], v[52:55]
	v_mfma_f32_16x16x32_bf16 v[48:51], v[178:181], v[186:189], v[48:51]
	v_mfma_f32_16x16x32_bf16 v[36:39], v[170:173], v[194:197], v[36:39]
	v_mfma_f32_16x16x32_bf16 v[32:35], v[178:181], v[194:197], v[32:35]
	v_mfma_f32_16x16x32_bf16 v[20:23], v[170:173], v[202:205], v[20:23]
	v_mfma_f32_16x16x32_bf16 v[16:19], v[178:181], v[202:205], v[16:19]
	v_mfma_f32_16x16x32_bf16 v[4:7], v[170:173], v[210:213], v[4:7]
	v_mfma_f32_16x16x32_bf16 v[0:3], v[178:181], v[210:213], v[0:3]
	s_setprio 0
	s_setprio 1
	v_mfma_f32_16x16x32_bf16 v[52:55], v[174:177], v[190:193], v[52:55]
	v_mfma_f32_16x16x32_bf16 v[48:51], v[182:185], v[190:193], v[48:51]
	v_mfma_f32_16x16x32_bf16 v[36:39], v[174:177], v[198:201], v[36:39]
	v_mfma_f32_16x16x32_bf16 v[32:35], v[182:185], v[198:201], v[32:35]
	v_mfma_f32_16x16x32_bf16 v[20:23], v[174:177], v[206:209], v[20:23]
	v_mfma_f32_16x16x32_bf16 v[16:19], v[182:185], v[206:209], v[16:19]
	v_mfma_f32_16x16x32_bf16 v[4:7], v[174:177], v[214:217], v[4:7]
	v_mfma_f32_16x16x32_bf16 v[0:3], v[182:185], v[214:217], v[0:3]
	s_setprio 0
	s_barrier
	ds_read_b128 v[140:143], v159
	ds_read_b128 v[144:147], v159 offset:1024
	ds_read_b128 v[162:165], v159 offset:2048
	ds_read_b128 v[166:169], v159 offset:3072
	ds_read_b128 v[170:173], v160
	ds_read_b128 v[174:177], v160 offset:1024
	ds_read_b128 v[178:181], v160 offset:2048
	ds_read_b128 v[182:185], v160 offset:3072
	s_add_u32 s34, s54, 0x10000
	s_addc_u32 s35, s55, 0
	s_mov_b32 m0, s70
	v_lshl_add_u64 v[222:223], s[34:35], 0, v[134:135]
	ds_read_b128 v[186:189], v137 offset:32768
	ds_read_b128 v[190:193], v137 offset:33792
	ds_read_b128 v[194:197], v137 offset:34816
	ds_read_b128 v[198:201], v137 offset:35840
	ds_read_b128 v[202:205], v137 offset:36864
	ds_read_b128 v[206:209], v137 offset:37888
	ds_read_b128 v[210:213], v137 offset:38912
	ds_read_b128 v[214:217], v137 offset:39936
	global_load_lds_dwordx4 v[222:223], off
	v_lshl_add_u64 v[222:223], s[34:35], 0, v[130:131]
	s_mov_b32 m0, s71
	s_nop 0
	global_load_lds_dwordx4 v[222:223], off
	s_waitcnt vmcnt(8)
	s_waitcnt lgkmcnt(0)
	s_barrier
	s_setprio 1
	s_waitcnt lgkmcnt(0)
	v_mfma_f32_16x16x32_bf16 v[124:127], v[140:143], v[186:189], v[124:127]
	v_mfma_f32_16x16x32_bf16 v[120:123], v[162:165], v[186:189], v[120:123]
	v_mfma_f32_16x16x32_bf16 v[108:111], v[140:143], v[194:197], v[108:111]
	v_mfma_f32_16x16x32_bf16 v[104:107], v[162:165], v[194:197], v[104:107]
	v_mfma_f32_16x16x32_bf16 v[92:95], v[140:143], v[202:205], v[92:95]
	v_mfma_f32_16x16x32_bf16 v[88:91], v[162:165], v[202:205], v[88:91]
	v_mfma_f32_16x16x32_bf16 v[76:79], v[140:143], v[210:213], v[76:79]
	v_mfma_f32_16x16x32_bf16 v[72:75], v[162:165], v[210:213], v[72:75]
	s_setprio 0
	s_setprio 1
	v_mfma_f32_16x16x32_bf16 v[124:127], v[144:147], v[190:193], v[124:127]
	v_mfma_f32_16x16x32_bf16 v[120:123], v[166:169], v[190:193], v[120:123]
	v_mfma_f32_16x16x32_bf16 v[108:111], v[144:147], v[198:201], v[108:111]
	v_mfma_f32_16x16x32_bf16 v[104:107], v[166:169], v[198:201], v[104:107]
	v_mfma_f32_16x16x32_bf16 v[92:95], v[144:147], v[206:209], v[92:95]
	v_mfma_f32_16x16x32_bf16 v[88:91], v[166:169], v[206:209], v[88:91]
	v_mfma_f32_16x16x32_bf16 v[76:79], v[144:147], v[214:217], v[76:79]
	v_mfma_f32_16x16x32_bf16 v[72:75], v[166:169], v[214:217], v[72:75]
	s_setprio 0
	s_setprio 1
	v_mfma_f32_16x16x32_bf16 v[116:119], v[170:173], v[186:189], v[116:119]
	v_mfma_f32_16x16x32_bf16 v[112:115], v[178:181], v[186:189], v[112:115]
	v_mfma_f32_16x16x32_bf16 v[100:103], v[170:173], v[194:197], v[100:103]
	v_mfma_f32_16x16x32_bf16 v[96:99], v[178:181], v[194:197], v[96:99]
	v_mfma_f32_16x16x32_bf16 v[84:87], v[170:173], v[202:205], v[84:87]
	v_mfma_f32_16x16x32_bf16 v[80:83], v[178:181], v[202:205], v[80:83]
	v_mfma_f32_16x16x32_bf16 v[68:71], v[170:173], v[210:213], v[68:71]
	v_mfma_f32_16x16x32_bf16 v[64:67], v[178:181], v[210:213], v[64:67]
	s_setprio 0
	s_setprio 1
	v_mfma_f32_16x16x32_bf16 v[116:119], v[174:177], v[190:193], v[116:119]
	v_mfma_f32_16x16x32_bf16 v[112:115], v[182:185], v[190:193], v[112:115]
	v_mfma_f32_16x16x32_bf16 v[100:103], v[174:177], v[198:201], v[100:103]
	v_mfma_f32_16x16x32_bf16 v[96:99], v[182:185], v[198:201], v[96:99]
	v_mfma_f32_16x16x32_bf16 v[84:87], v[174:177], v[206:209], v[84:87]
	v_mfma_f32_16x16x32_bf16 v[80:83], v[182:185], v[206:209], v[80:83]
	v_mfma_f32_16x16x32_bf16 v[68:71], v[174:177], v[214:217], v[68:71]
	v_mfma_f32_16x16x32_bf16 v[64:67], v[182:185], v[214:217], v[64:67]
	s_setprio 0
	s_barrier
; #define PG8_STAGE(bufoff, gbase, voff) do { _Pragma("unroll") for (int _i = 0; _i < 2; ++_i) \
;         __builtin_amdgcn_global_load_lds((const unsigned*)((const char*)(gbase) + (voff)[_i]), (LAS unsigned*)(lds + (bufoff) + ldsw + _i * 8192), 16, 0, 0); } while (0)
; #define PG8_LDA(dst, b, h) do { _Pragma("unroll") for (int m = 0; m < 4; ++m) _Pragma("unroll") for (int k = 0; k < 2; ++k) dst[m][k] = *(const LAS bf16x8*)(lds + PG8_SA(b, h) + aoff + m * 2048 + k * 1024); } while (0)
; #define PG8_MMA(ai, bj, At, Bt) do { __builtin_amdgcn_s_setprio(1); _Pragma("unroll") for (int m = 0; m < 4; ++m) _Pragma("unroll") for (int n = 0; n < 2; ++n) _Pragma("unroll") for (int k = 0; k < 2; ++k) \
;         acc[ai][bj][m][n] = __builtin_amdgcn_mfma_f32_16x16x32_bf16(Bt[n][k], At[m][k], acc[ai][bj][m][n], 0, 0, 0); __builtin_amdgcn_s_setprio(0); } while (0)
; #define PG8_WAIT_V(n) asm volatile("s_waitcnt vmcnt(" #n ")" ::: "memory")
; #define PG8_WAIT_L(n) asm volatile("s_waitcnt lgkmcnt(" #n ")" ::: "memory")
; #define PG8_BAR __builtin_amdgcn_s_barrier()
; #define PG8_SCHED __builtin_amdgcn_sched_barrier(0)
; template <class Epi, class Sched, bool ALIGN_EPI = false, bool SP2 = false, bool TWOA = false, bool AGM = false>
; __device__ __forceinline__ void gemm_phase(LAS unsigned char* lds, const Gemm g, const Sched& S, const Epi& E, int wid) {
;     ...
;             PG8_LDA(At, 1, 1); PG8_STAGE(PG8_SB(1, 0), b3, voffB); PG8_STAGE(PG8_SB(1, 1), b3 + hstep, voffB); PG8_STAGE(PG8_SA(1, 0), a3, voffA);
;             PG8_WAIT_V(8); PG8_WAIT_L(0); PG8_BAR; PG8_MMA(1, 0, At, B0); PG8_MMA(1, 1, At, B1); PG8_BAR; PG8_SCHED;
;     ...
;         }
;         if constexpr (ALIGN_EPI) { if (wr == 0) PG8_BAR; }
	s_mov_b32 m0, s56
	v_lshl_add_u64 v[148:149], v[148:149], 0, s[12:13]
	s_add_u32 s34, s52, 0x20080
	ds_read_b128 v[186:189], v137 offset:49152
	ds_read_b128 v[190:193], v137 offset:50176
	ds_read_b128 v[194:197], v137 offset:51200
	ds_read_b128 v[198:201], v137 offset:52224
	ds_read_b128 v[202:205], v137 offset:53248
	ds_read_b128 v[206:209], v137 offset:54272
	ds_read_b128 v[210:213], v137 offset:55296
	ds_read_b128 v[214:217], v137 offset:56320
	global_load_lds_dwordx4 v[148:149], off
	v_lshl_add_u64 v[148:149], v[150:151], 0, s[12:13]
	s_mov_b32 m0, s57
	s_addc_u32 s35, s53, 0
	global_load_lds_dwordx4 v[148:149], off
	v_lshl_add_u64 v[148:149], s[34:35], 0, v[132:133]
	s_mov_b32 m0, s89
	s_nop 0
	global_load_lds_dwordx4 v[148:149], off
	v_lshl_add_u64 v[148:149], s[34:35], 0, v[128:129]
	s_mov_b32 m0, s90
	s_nop 0
	global_load_lds_dwordx4 v[148:149], off
	v_lshl_add_u64 v[148:149], v[218:219], 0, s[12:13]
	s_mov_b32 m0, s74
	s_nop 0
	global_load_lds_dwordx4 v[148:149], off
	v_lshl_add_u64 v[148:149], v[220:221], 0, s[12:13]
	s_mov_b32 m0, s75
	s_nop 0
	global_load_lds_dwordx4 v[148:149], off
	s_waitcnt vmcnt(8)
	s_waitcnt lgkmcnt(0)
	s_barrier
	s_setprio 1
	s_waitcnt lgkmcnt(0)
	v_mfma_f32_16x16x32_bf16 v[60:63], v[140:143], v[186:189], v[60:63]
	v_mfma_f32_16x16x32_bf16 v[56:59], v[162:165], v[186:189], v[56:59]
	v_mfma_f32_16x16x32_bf16 v[44:47], v[140:143], v[194:197], v[44:47]
	v_mfma_f32_16x16x32_bf16 v[40:43], v[162:165], v[194:197], v[40:43]
	v_mfma_f32_16x16x32_bf16 v[28:31], v[140:143], v[202:205], v[28:31]
	v_mfma_f32_16x16x32_bf16 v[24:27], v[162:165], v[202:205], v[24:27]
	v_mfma_f32_16x16x32_bf16 v[12:15], v[140:143], v[210:213], v[12:15]
	v_mfma_f32_16x16x32_bf16 v[8:11], v[162:165], v[210:213], v[8:11]
	s_setprio 0
	s_setprio 1
	v_mfma_f32_16x16x32_bf16 v[60:63], v[144:147], v[190:193], v[60:63]
	v_mfma_f32_16x16x32_bf16 v[56:59], v[166:169], v[190:193], v[56:59]
	v_mfma_f32_16x16x32_bf16 v[44:47], v[144:147], v[198:201], v[44:47]
	v_mfma_f32_16x16x32_bf16 v[40:43], v[166:169], v[198:201], v[40:43]
	v_mfma_f32_16x16x32_bf16 v[28:31], v[144:147], v[206:209], v[28:31]
	v_mfma_f32_16x16x32_bf16 v[24:27], v[166:169], v[206:209], v[24:27]
	v_mfma_f32_16x16x32_bf16 v[12:15], v[144:147], v[214:217], v[12:15]
	v_mfma_f32_16x16x32_bf16 v[8:11], v[166:169], v[214:217], v[8:11]
	s_setprio 0
	s_setprio 1
	v_mfma_f32_16x16x32_bf16 v[52:55], v[170:173], v[186:189], v[52:55]
	v_mfma_f32_16x16x32_bf16 v[48:51], v[178:181], v[186:189], v[48:51]
	v_mfma_f32_16x16x32_bf16 v[36:39], v[170:173], v[194:197], v[36:39]
	v_mfma_f32_16x16x32_bf16 v[32:35], v[178:181], v[194:197], v[32:35]
	v_mfma_f32_16x16x32_bf16 v[20:23], v[170:173], v[202:205], v[20:23]
	v_mfma_f32_16x16x32_bf16 v[16:19], v[178:181], v[202:205], v[16:19]
	v_mfma_f32_16x16x32_bf16 v[4:7], v[170:173], v[210:213], v[4:7]
	v_mfma_f32_16x16x32_bf16 v[0:3], v[178:181], v[210:213], v[0:3]
	s_setprio 0
	s_setprio 1
	v_mfma_f32_16x16x32_bf16 v[52:55], v[174:177], v[190:193], v[52:55]
	v_mfma_f32_16x16x32_bf16 v[48:51], v[182:185], v[190:193], v[48:51]
	v_mfma_f32_16x16x32_bf16 v[36:39], v[174:177], v[198:201], v[36:39]
	v_mfma_f32_16x16x32_bf16 v[32:35], v[182:185], v[198:201], v[32:35]
	v_mfma_f32_16x16x32_bf16 v[20:23], v[174:177], v[206:209], v[20:23]
	v_mfma_f32_16x16x32_bf16 v[16:19], v[182:185], v[206:209], v[16:19]
	v_mfma_f32_16x16x32_bf16 v[4:7], v[174:177], v[214:217], v[4:7]
	v_mfma_f32_16x16x32_bf16 v[0:3], v[182:185], v[214:217], v[0:3]
	s_setprio 0
	s_barrier
	s_add_i32 s93, s93, 2
	s_add_u32 s91, s91, 0x100
	s_addc_u32 s92, s92, 0
	s_cmp_gt_u32 s93, 5
	s_cbranch_scc0 .LBB0_683
	s_and_b64 vcc, exec, s[20:21]
	s_cbranch_vccz .LBB0_686
	s_barrier

; #define PG8_STAGE(bufoff, gbase, voff) do { _Pragma("unroll") for (int _i = 0; _i < 2; ++_i) \
;         __builtin_amdgcn_global_load_lds((const unsigned*)((const char*)(gbase) + (voff)[_i]), (LAS unsigned*)(lds + (bufoff) + ldsw + _i * 8192), 16, 0, 0); } while (0)
; #define PG8_LDA(dst, b, h) do { _Pragma("unroll") for (int m = 0; m < 4; ++m) _Pragma("unroll") for (int k = 0; k < 2; ++k) dst[m][k] = *(const LAS bf16x8*)(lds + PG8_SA(b, h) + aoff + m * 2048 + k * 1024); } while (0)
; #define PG8_LDB(dst, b, h) do { _Pragma("unroll") for (int n = 0; n < 2; ++n) _Pragma("unroll") for (int k = 0; k < 2; ++k) dst[n][k] = *(const LAS bf16x8*)(lds + PG8_SB(b, h) + boff + n * 2048 + k * 1024); } while (0)
; #define PG8_WAIT_V(n) asm volatile("s_waitcnt vmcnt(" #n ")" ::: "memory")
; template <class Epi, class Sched, bool ALIGN_EPI = false, bool SP2 = false, bool TWOA = false, bool AGM = false>
; __device__ __forceinline__ void gemm_phase(LAS unsigned char* lds, const Gemm g, const Sched& S, const Epi& E, int wid) {
;     ...
;             const bool last = (t == nt - 2);
;             const char* cA2 = TWOA ? (const char*)g.A2 + (cA - (const char*)g.A) - (size_t)nh * kstepA : cA;
;             const char* a1_ = (TWOA && t + 1 >= nh ? cA2 : cA) + (size_t)(t + 1) * kstepA;
;             const char* a2_ = last ? nA : (TWOA && t + 2 >= nh ? cA2 : cA) + (size_t)(t + 2) * kstepA; const char* a1 = a1_; const char* a2 = a2_; const char* b2 = last ? nB : cB + (size_t)(t + 2) * kstep;
;             if constexpr (TWOA) { asm volatile("" : "+s"(a1)); asm volatile("" : "+s"(a2)); }
;             const char* a3 = a2 + kstepA; const char* b3 = b2 + kstep;
;             if (last && has_next) S.a_ready(nxt);
;             if constexpr (has_mid<Epi>::value) { if (t == nh) E.mid(acc, cur, wr, wc, fr, fq); }
;             if constexpr (SP2) {
;             PG8_LDB(B0, 0, 0); PG8_LDB(B1, 0, 1); PG8_SCHED; PG8_LDA(At, 0, 0); PG8_STAGE(PG8_SA(1, 1), a1 + hstepA, voffA);
;             PG8_WAIT_V(8); PG8_WAIT_L(0); PG8_BAR; PG8_MMA(0, 0, At, B0); PG8_MMA(0, 1, At, B1); PG8_BAR; PG8_SCHED;
;             PG8_LDA(At, 0, 1); PG8_STAGE(PG8_SB(0, 0), b2, voffB); PG8_STAGE(PG8_SB(0, 1), b2 + hstep, voffB); PG8_STAGE(PG8_SA(0, 0), a2, voffA);
;             PG8_WAIT_V(8); PG8_WAIT_L(0); PG8_BAR; PG8_MMA(1, 0, At, B0); PG8_MMA(1, 1, At, B1); PG8_BAR; PG8_SCHED;
.LBB0_753:
	ds_read_b128 v[146:149], v152
	ds_read_b128 v[156:159], v152 offset:1024
	ds_read_b128 v[160:163], v152 offset:2048
	ds_read_b128 v[164:167], v152 offset:3072
	ds_read_b128 v[168:171], v153
	ds_read_b128 v[172:175], v153 offset:1024
	ds_read_b128 v[176:179], v153 offset:2048
	ds_read_b128 v[180:183], v153 offset:3072
	s_add_u32 s38, s36, 0x600000
	s_addc_u32 s39, s37, 0
	s_cmp_eq_u32 s75, 28
	s_cselect_b32 s44, s71, s38
	s_cselect_b32 s45, s25, s39
	s_cselect_b32 s42, s72, s73
	s_cselect_b32 s43, s23, s74
	s_add_u32 s40, s44, 0x300000
	s_addc_u32 s41, s45, 0
	v_lshl_add_u64 v[216:217], s[36:37], 0, v[136:137]
	s_add_i32 m0, s50, 0xc000
	ds_read_b128 v[184:187], v154
	ds_read_b128 v[188:191], v154 offset:1024
	ds_read_b128 v[192:195], v154 offset:2048
	ds_read_b128 v[196:199], v154 offset:3072
	ds_read_b128 v[200:203], v154 offset:4096
	ds_read_b128 v[204:207], v154 offset:5120
	ds_read_b128 v[208:211], v154 offset:6144
	ds_read_b128 v[212:215], v154 offset:7168
	global_load_lds_dwordx4 v[216:217], off
	v_lshl_add_u64 v[216:217], s[36:37], 0, v[138:139]
	s_add_i32 m0, s50, 0xe000
	s_nop 0
	global_load_lds_dwordx4 v[216:217], off
	s_waitcnt vmcnt(8)
	s_waitcnt lgkmcnt(0)
	s_barrier
	s_setprio 1
	s_waitcnt lgkmcnt(0)
	v_mfma_f32_16x16x32_bf16 v[116:119], v[146:149], v[184:187], v[116:119]
	v_mfma_f32_16x16x32_bf16 v[112:115], v[160:163], v[184:187], v[112:115]
	v_mfma_f32_16x16x32_bf16 v[100:103], v[146:149], v[192:195], v[100:103]
	v_mfma_f32_16x16x32_bf16 v[96:99], v[160:163], v[192:195], v[96:99]
	v_mfma_f32_16x16x32_bf16 v[84:87], v[146:149], v[200:203], v[84:87]
	v_mfma_f32_16x16x32_bf16 v[80:83], v[160:163], v[200:203], v[80:83]
	v_mfma_f32_16x16x32_bf16 v[68:71], v[146:149], v[208:211], v[68:71]
	v_mfma_f32_16x16x32_bf16 v[64:67], v[160:163], v[208:211], v[64:67]
	s_setprio 0
	s_setprio 1
	v_mfma_f32_16x16x32_bf16 v[116:119], v[156:159], v[188:191], v[116:119]
	v_mfma_f32_16x16x32_bf16 v[112:115], v[164:167], v[188:191], v[112:115]
	v_mfma_f32_16x16x32_bf16 v[100:103], v[156:159], v[196:199], v[100:103]
	v_mfma_f32_16x16x32_bf16 v[96:99], v[164:167], v[196:199], v[96:99]
	v_mfma_f32_16x16x32_bf16 v[84:87], v[156:159], v[204:207], v[84:87]
	v_mfma_f32_16x16x32_bf16 v[80:83], v[164:167], v[204:207], v[80:83]
	v_mfma_f32_16x16x32_bf16 v[68:71], v[156:159], v[212:215], v[68:71]
	v_mfma_f32_16x16x32_bf16 v[64:67], v[164:167], v[212:215], v[64:67]
	s_setprio 0
	s_setprio 1
	v_mfma_f32_16x16x32_bf16 v[124:127], v[168:171], v[184:187], v[124:127]
	v_mfma_f32_16x16x32_bf16 v[120:123], v[176:179], v[184:187], v[120:123]
	v_mfma_f32_16x16x32_bf16 v[108:111], v[168:171], v[192:195], v[108:111]
	v_mfma_f32_16x16x32_bf16 v[104:107], v[176:179], v[192:195], v[104:107]
	v_mfma_f32_16x16x32_bf16 v[92:95], v[168:171], v[200:203], v[92:95]
	v_mfma_f32_16x16x32_bf16 v[88:91], v[176:179], v[200:203], v[88:91]
	v_mfma_f32_16x16x32_bf16 v[76:79], v[168:171], v[208:211], v[76:79]
	v_mfma_f32_16x16x32_bf16 v[72:75], v[176:179], v[208:211], v[72:75]
	s_setprio 0
	s_setprio 1
	v_mfma_f32_16x16x32_bf16 v[124:127], v[172:175], v[188:191], v[124:127]
	v_mfma_f32_16x16x32_bf16 v[120:123], v[180:183], v[188:191], v[120:123]
	v_mfma_f32_16x16x32_bf16 v[108:111], v[172:175], v[196:199], v[108:111]
	v_mfma_f32_16x16x32_bf16 v[104:107], v[180:183], v[196:199], v[104:107]
	v_mfma_f32_16x16x32_bf16 v[92:95], v[172:175], v[204:207], v[92:95]
	v_mfma_f32_16x16x32_bf16 v[88:91], v[180:183], v[204:207], v[88:91]
	v_mfma_f32_16x16x32_bf16 v[76:79], v[172:175], v[212:215], v[76:79]
	v_mfma_f32_16x16x32_bf16 v[72:75], v[180:183], v[212:215], v[72:75]
	s_setprio 0
	s_barrier
	s_add_i32 s34, s65, s3
	v_lshl_add_u64 v[216:217], s[42:43], 0, v[132:133]
	s_mov_b32 m0, s34
	ds_read_b128 v[184:187], v154 offset:16384
	ds_read_b128 v[188:191], v154 offset:17408
	ds_read_b128 v[192:195], v154 offset:18432
	ds_read_b128 v[196:199], v154 offset:19456
	ds_read_b128 v[200:203], v154 offset:20480
	ds_read_b128 v[204:207], v154 offset:21504
	ds_read_b128 v[208:211], v154 offset:22528
	ds_read_b128 v[212:215], v154 offset:23552
	global_load_lds_dwordx4 v[216:217], off
	s_add_i32 m0, s34, 0x2000
	s_add_u32 s34, s42, 0x80000
	v_lshl_add_u64 v[218:219], s[42:43], 0, v[128:129]
	s_addc_u32 s35, s43, 0
	s_add_i32 s36, s66, s3
	global_load_lds_dwordx4 v[218:219], off
	v_lshl_add_u64 v[220:221], s[34:35], 0, v[132:133]
	s_mov_b32 m0, s36
	s_nop 0
	global_load_lds_dwordx4 v[220:221], off
	v_lshl_add_u64 v[220:221], s[34:35], 0, v[128:129]
	s_add_i32 m0, s36, 0x2000
	s_nop 0
	global_load_lds_dwordx4 v[220:221], off
	v_lshl_add_u64 v[220:221], s[44:45], 0, v[134:135]
	s_mov_b32 m0, s50
	s_nop 0
	global_load_lds_dwordx4 v[220:221], off
	v_lshl_add_u64 v[220:221], s[44:45], 0, v[130:131]
	s_mov_b32 m0, s51
	s_nop 0
	global_load_lds_dwordx4 v[220:221], off
	s_waitcnt vmcnt(8)
	s_waitcnt lgkmcnt(0)
	s_barrier
; #define PG8_STAGE(bufoff, gbase, voff) do { _Pragma("unroll") for (int _i = 0; _i < 2; ++_i) \
;         __builtin_amdgcn_global_load_lds((const unsigned*)((const char*)(gbase) + (voff)[_i]), (LAS unsigned*)(lds + (bufoff) + ldsw + _i * 8192), 16, 0, 0); } while (0)
; #define PG8_LDA(dst, b, h) do { _Pragma("unroll") for (int m = 0; m < 4; ++m) _Pragma("unroll") for (int k = 0; k < 2; ++k) dst[m][k] = *(const LAS bf16x8*)(lds + PG8_SA(b, h) + aoff + m * 2048 + k * 1024); } while (0)
; #define PG8_LDB(dst, b, h) do { _Pragma("unroll") for (int n = 0; n < 2; ++n) _Pragma("unroll") for (int k = 0; k < 2; ++k) dst[n][k] = *(const LAS bf16x8*)(lds + PG8_SB(b, h) + boff + n * 2048 + k * 1024); } while (0)
; #define PG8_MMA(ai, bj, At, Bt) do { __builtin_amdgcn_s_setprio(1); _Pragma("unroll") for (int m = 0; m < 4; ++m) _Pragma("unroll") for (int n = 0; n < 2; ++n) _Pragma("unroll") for (int k = 0; k < 2; ++k) \
;         acc[ai][bj][m][n] = __builtin_amdgcn_mfma_f32_16x16x32_bf16(Bt[n][k], At[m][k], acc[ai][bj][m][n], 0, 0, 0); __builtin_amdgcn_s_setprio(0); } while (0)
; #define PG8_WAIT_V(n) asm volatile("s_waitcnt vmcnt(" #n ")" ::: "memory")
; #define PG8_WAIT_L(n) asm volatile("s_waitcnt lgkmcnt(" #n ")" ::: "memory")
; #define PG8_BAR __builtin_amdgcn_s_barrier()
; #define PG8_SCHED __builtin_amdgcn_sched_barrier(0)
; template <class Epi, class Sched, bool ALIGN_EPI = false, bool SP2 = false, bool TWOA = false, bool AGM = false>
; __device__ __forceinline__ void gemm_phase(LAS unsigned char* lds, const Gemm g, const Sched& S, const Epi& E, int wid) {
;     ...
;             PG8_WAIT_V(8); PG8_WAIT_L(0); PG8_BAR; PG8_MMA(1, 0, At, B0); PG8_MMA(1, 1, At, B1); PG8_BAR; PG8_SCHED;
;             PG8_LDB(B0, 1, 0); PG8_LDB(B1, 1, 1); PG8_SCHED; PG8_LDA(At, 1, 0); PG8_STAGE(PG8_SA(0, 1), a2 + hstepA, voffA);
;             PG8_WAIT_V(8); PG8_WAIT_L(0); PG8_BAR; PG8_MMA(0, 0, At, B0); PG8_MMA(0, 1, At, B1); PG8_BAR; PG8_SCHED;
;             PG8_LDA(At, 1, 1); PG8_STAGE(PG8_SB(1, 0), b3, voffB); PG8_STAGE(PG8_SB(1, 1), b3 + hstep, voffB); PG8_STAGE(PG8_SA(1, 0), a3, voffA);
	s_setprio 1
	s_waitcnt lgkmcnt(0)
	v_mfma_f32_16x16x32_bf16 v[52:55], v[146:149], v[184:187], v[52:55]
	v_mfma_f32_16x16x32_bf16 v[48:51], v[160:163], v[184:187], v[48:51]
	v_mfma_f32_16x16x32_bf16 v[36:39], v[146:149], v[192:195], v[36:39]
	v_mfma_f32_16x16x32_bf16 v[32:35], v[160:163], v[192:195], v[32:35]
	v_mfma_f32_16x16x32_bf16 v[20:23], v[146:149], v[200:203], v[20:23]
	v_mfma_f32_16x16x32_bf16 v[16:19], v[160:163], v[200:203], v[16:19]
	v_mfma_f32_16x16x32_bf16 v[4:7], v[146:149], v[208:211], v[4:7]
	v_mfma_f32_16x16x32_bf16 v[0:3], v[160:163], v[208:211], v[0:3]
	s_setprio 0
	s_setprio 1
	v_mfma_f32_16x16x32_bf16 v[52:55], v[156:159], v[188:191], v[52:55]
	v_mfma_f32_16x16x32_bf16 v[48:51], v[164:167], v[188:191], v[48:51]
	v_mfma_f32_16x16x32_bf16 v[36:39], v[156:159], v[196:199], v[36:39]
	v_mfma_f32_16x16x32_bf16 v[32:35], v[164:167], v[196:199], v[32:35]
	v_mfma_f32_16x16x32_bf16 v[20:23], v[156:159], v[204:207], v[20:23]
	v_mfma_f32_16x16x32_bf16 v[16:19], v[164:167], v[204:207], v[16:19]
	v_mfma_f32_16x16x32_bf16 v[4:7], v[156:159], v[212:215], v[4:7]
	v_mfma_f32_16x16x32_bf16 v[0:3], v[164:167], v[212:215], v[0:3]
	s_setprio 0
	s_setprio 1
	v_mfma_f32_16x16x32_bf16 v[60:63], v[168:171], v[184:187], v[60:63]
	v_mfma_f32_16x16x32_bf16 v[56:59], v[176:179], v[184:187], v[56:59]
	v_mfma_f32_16x16x32_bf16 v[44:47], v[168:171], v[192:195], v[44:47]
	v_mfma_f32_16x16x32_bf16 v[40:43], v[176:179], v[192:195], v[40:43]
	v_mfma_f32_16x16x32_bf16 v[28:31], v[168:171], v[200:203], v[28:31]
	v_mfma_f32_16x16x32_bf16 v[24:27], v[176:179], v[200:203], v[24:27]
	v_mfma_f32_16x16x32_bf16 v[12:15], v[168:171], v[208:211], v[12:15]
	v_mfma_f32_16x16x32_bf16 v[8:11], v[176:179], v[208:211], v[8:11]
	s_setprio 0
	s_setprio 1
	v_mfma_f32_16x16x32_bf16 v[60:63], v[172:175], v[188:191], v[60:63]
	v_mfma_f32_16x16x32_bf16 v[56:59], v[180:183], v[188:191], v[56:59]
	v_mfma_f32_16x16x32_bf16 v[44:47], v[172:175], v[196:199], v[44:47]
	v_mfma_f32_16x16x32_bf16 v[40:43], v[180:183], v[196:199], v[40:43]
	v_mfma_f32_16x16x32_bf16 v[28:31], v[172:175], v[204:207], v[28:31]
	v_mfma_f32_16x16x32_bf16 v[24:27], v[180:183], v[204:207], v[24:27]
	v_mfma_f32_16x16x32_bf16 v[12:15], v[172:175], v[212:215], v[12:15]
	v_mfma_f32_16x16x32_bf16 v[8:11], v[180:183], v[212:215], v[8:11]
	s_setprio 0
	s_barrier
	s_add_i32 s36, 0, 0x18000
	v_add_u32_e32 v155, s36, v151
	s_add_i32 s37, 0, 0x1c000
	ds_read_b128 v[146:149], v155
	ds_read_b128 v[156:159], v155 offset:1024
	ds_read_b128 v[160:163], v155 offset:2048
	ds_read_b128 v[164:167], v155 offset:3072
	v_add_u32_e32 v155, s37, v151
	ds_read_b128 v[168:171], v155
	ds_read_b128 v[172:175], v155 offset:1024
	ds_read_b128 v[176:179], v155 offset:2048
	ds_read_b128 v[180:183], v155 offset:3072
	s_add_u32 s34, s44, 0x1000
	s_addc_u32 s35, s45, 0
	s_mov_b32 m0, s52
	v_lshl_add_u64 v[220:221], s[34:35], 0, v[134:135]
	ds_read_b128 v[184:187], v154 offset:32768
	ds_read_b128 v[188:191], v154 offset:33792
	ds_read_b128 v[192:195], v154 offset:34816
	ds_read_b128 v[196:199], v154 offset:35840
	ds_read_b128 v[200:203], v154 offset:36864
	ds_read_b128 v[204:207], v154 offset:37888
	ds_read_b128 v[208:211], v154 offset:38912
	ds_read_b128 v[212:215], v154 offset:39936
	global_load_lds_dwordx4 v[220:221], off
	v_lshl_add_u64 v[220:221], s[34:35], 0, v[130:131]
	s_mov_b32 m0, s53
	s_nop 0
	global_load_lds_dwordx4 v[220:221], off
	s_waitcnt vmcnt(8)
	s_waitcnt lgkmcnt(0)
	s_barrier
	s_setprio 1
	s_waitcnt lgkmcnt(0)
	v_mfma_f32_16x16x32_bf16 v[116:119], v[146:149], v[184:187], v[116:119]
	v_mfma_f32_16x16x32_bf16 v[112:115], v[160:163], v[184:187], v[112:115]
	v_mfma_f32_16x16x32_bf16 v[100:103], v[146:149], v[192:195], v[100:103]
	v_mfma_f32_16x16x32_bf16 v[96:99], v[160:163], v[192:195], v[96:99]
	v_mfma_f32_16x16x32_bf16 v[84:87], v[146:149], v[200:203], v[84:87]
	v_mfma_f32_16x16x32_bf16 v[80:83], v[160:163], v[200:203], v[80:83]
	v_mfma_f32_16x16x32_bf16 v[68:71], v[146:149], v[208:211], v[68:71]
	v_mfma_f32_16x16x32_bf16 v[64:67], v[160:163], v[208:211], v[64:67]
	s_setprio 0
	s_setprio 1
	v_mfma_f32_16x16x32_bf16 v[116:119], v[156:159], v[188:191], v[116:119]
	v_mfma_f32_16x16x32_bf16 v[112:115], v[164:167], v[188:191], v[112:115]
	v_mfma_f32_16x16x32_bf16 v[100:103], v[156:159], v[196:199], v[100:103]
	v_mfma_f32_16x16x32_bf16 v[96:99], v[164:167], v[196:199], v[96:99]
	v_mfma_f32_16x16x32_bf16 v[84:87], v[156:159], v[204:207], v[84:87]
	v_mfma_f32_16x16x32_bf16 v[80:83], v[164:167], v[204:207], v[80:83]
	v_mfma_f32_16x16x32_bf16 v[68:71], v[156:159], v[212:215], v[68:71]
	v_mfma_f32_16x16x32_bf16 v[64:67], v[164:167], v[212:215], v[64:67]
	s_setprio 0
	s_setprio 1
	v_mfma_f32_16x16x32_bf16 v[124:127], v[168:171], v[184:187], v[124:127]
	v_mfma_f32_16x16x32_bf16 v[120:123], v[176:179], v[184:187], v[120:123]
	v_mfma_f32_16x16x32_bf16 v[108:111], v[168:171], v[192:195], v[108:111]
	v_mfma_f32_16x16x32_bf16 v[104:107], v[176:179], v[192:195], v[104:107]
	v_mfma_f32_16x16x32_bf16 v[92:95], v[168:171], v[200:203], v[92:95]
	v_mfma_f32_16x16x32_bf16 v[88:91], v[176:179], v[200:203], v[88:91]
	v_mfma_f32_16x16x32_bf16 v[76:79], v[168:171], v[208:211], v[76:79]
	v_mfma_f32_16x16x32_bf16 v[72:75], v[176:179], v[208:211], v[72:75]
	s_setprio 0
	s_setprio 1
	v_mfma_f32_16x16x32_bf16 v[124:127], v[172:175], v[188:191], v[124:127]
	v_mfma_f32_16x16x32_bf16 v[120:123], v[180:183], v[188:191], v[120:123]
	v_mfma_f32_16x16x32_bf16 v[108:111], v[172:175], v[196:199], v[108:111]
	v_mfma_f32_16x16x32_bf16 v[104:107], v[180:183], v[196:199], v[104:107]
	v_mfma_f32_16x16x32_bf16 v[92:95], v[172:175], v[204:207], v[92:95]
	v_mfma_f32_16x16x32_bf16 v[88:91], v[180:183], v[204:207], v[88:91]
	v_mfma_f32_16x16x32_bf16 v[76:79], v[172:175], v[212:215], v[76:79]
	v_mfma_f32_16x16x32_bf16 v[72:75], v[180:183], v[212:215], v[72:75]
	s_setprio 0
	s_barrier
; #define PG8_STAGE(bufoff, gbase, voff) do { _Pragma("unroll") for (int _i = 0; _i < 2; ++_i) \
;         __builtin_amdgcn_global_load_lds((const unsigned*)((const char*)(gbase) + (voff)[_i]), (LAS unsigned*)(lds + (bufoff) + ldsw + _i * 8192), 16, 0, 0); } while (0)
; #define PG8_LDA(dst, b, h) do { _Pragma("unroll") for (int m = 0; m < 4; ++m) _Pragma("unroll") for (int k = 0; k < 2; ++k) dst[m][k] = *(const LAS bf16x8*)(lds + PG8_SA(b, h) + aoff + m * 2048 + k * 1024); } while (0)
; #define PG8_MMA(ai, bj, At, Bt) do { __builtin_amdgcn_s_setprio(1); _Pragma("unroll") for (int m = 0; m < 4; ++m) _Pragma("unroll") for (int n = 0; n < 2; ++n) _Pragma("unroll") for (int k = 0; k < 2; ++k) \
;         acc[ai][bj][m][n] = __builtin_amdgcn_mfma_f32_16x16x32_bf16(Bt[n][k], At[m][k], acc[ai][bj][m][n], 0, 0, 0); __builtin_amdgcn_s_setprio(0); } while (0)
; #define PG8_WAIT_V(n) asm volatile("s_waitcnt vmcnt(" #n ")" ::: "memory")
; #define PG8_WAIT_L(n) asm volatile("s_waitcnt lgkmcnt(" #n ")" ::: "memory")
; #define PG8_BAR __builtin_amdgcn_s_barrier()
; #define PG8_SCHED __builtin_amdgcn_sched_barrier(0)
; template <class Epi, class Sched, bool ALIGN_EPI = false, bool SP2 = false, bool TWOA = false, bool AGM = false>
; __device__ __forceinline__ void gemm_phase(LAS unsigned char* lds, const Gemm g, const Sched& S, const Epi& E, int wid) {
;     ...
;             PG8_LDA(At, 1, 1); PG8_STAGE(PG8_SB(1, 0), b3, voffB); PG8_STAGE(PG8_SB(1, 1), b3 + hstep, voffB); PG8_STAGE(PG8_SA(1, 0), a3, voffA);
;             PG8_WAIT_V(8); PG8_WAIT_L(0); PG8_BAR; PG8_MMA(1, 0, At, B0); PG8_MMA(1, 1, At, B1); PG8_BAR; PG8_SCHED;
;     ...
;         }
;         if constexpr (ALIGN_EPI) { if (wr == 0) PG8_BAR; }
	s_add_i32 s34, s36, s3
	v_lshl_add_u64 v[216:217], v[216:217], 0, s[12:13]
	s_mov_b32 m0, s34
	ds_read_b128 v[184:187], v154 offset:49152
	ds_read_b128 v[188:191], v154 offset:50176
	ds_read_b128 v[192:195], v154 offset:51200
	ds_read_b128 v[196:199], v154 offset:52224
	ds_read_b128 v[200:203], v154 offset:53248
	ds_read_b128 v[204:207], v154 offset:54272
	ds_read_b128 v[208:211], v154 offset:55296
	ds_read_b128 v[212:215], v154 offset:56320
	global_load_lds_dwordx4 v[216:217], off
	s_add_i32 m0, s34, 0x2000
	s_add_u32 s34, s42, 0x80080
	v_lshl_add_u64 v[216:217], v[218:219], 0, s[12:13]
	s_addc_u32 s35, s43, 0
	s_add_i32 s36, s37, s3
	global_load_lds_dwordx4 v[216:217], off
	v_lshl_add_u64 v[216:217], s[34:35], 0, v[132:133]
	s_mov_b32 m0, s36
	s_nop 0
	global_load_lds_dwordx4 v[216:217], off
	v_lshl_add_u64 v[216:217], s[34:35], 0, v[128:129]
	s_add_i32 m0, s36, 0x2000
	s_nop 0
	global_load_lds_dwordx4 v[216:217], off
	v_lshl_add_u64 v[216:217], s[40:41], 0, v[134:135]
	s_mov_b32 m0, s55
	s_nop 0
	global_load_lds_dwordx4 v[216:217], off
	v_lshl_add_u64 v[216:217], s[40:41], 0, v[130:131]
	s_mov_b32 m0, s56
	s_nop 0
	global_load_lds_dwordx4 v[216:217], off
	s_waitcnt vmcnt(8)
	s_waitcnt lgkmcnt(0)
	s_barrier
	s_setprio 1
	s_waitcnt lgkmcnt(0)
	v_mfma_f32_16x16x32_bf16 v[52:55], v[146:149], v[184:187], v[52:55]
	v_mfma_f32_16x16x32_bf16 v[48:51], v[160:163], v[184:187], v[48:51]
	v_mfma_f32_16x16x32_bf16 v[36:39], v[146:149], v[192:195], v[36:39]
	v_mfma_f32_16x16x32_bf16 v[32:35], v[160:163], v[192:195], v[32:35]
	v_mfma_f32_16x16x32_bf16 v[20:23], v[146:149], v[200:203], v[20:23]
	v_mfma_f32_16x16x32_bf16 v[16:19], v[160:163], v[200:203], v[16:19]
	v_mfma_f32_16x16x32_bf16 v[4:7], v[146:149], v[208:211], v[4:7]
	v_mfma_f32_16x16x32_bf16 v[0:3], v[160:163], v[208:211], v[0:3]
	s_setprio 0
	s_setprio 1
	v_mfma_f32_16x16x32_bf16 v[52:55], v[156:159], v[188:191], v[52:55]
	v_mfma_f32_16x16x32_bf16 v[48:51], v[164:167], v[188:191], v[48:51]
	v_mfma_f32_16x16x32_bf16 v[36:39], v[156:159], v[196:199], v[36:39]
	v_mfma_f32_16x16x32_bf16 v[32:35], v[164:167], v[196:199], v[32:35]
	v_mfma_f32_16x16x32_bf16 v[20:23], v[156:159], v[204:207], v[20:23]
	v_mfma_f32_16x16x32_bf16 v[16:19], v[164:167], v[204:207], v[16:19]
	v_mfma_f32_16x16x32_bf16 v[4:7], v[156:159], v[212:215], v[4:7]
	v_mfma_f32_16x16x32_bf16 v[0:3], v[164:167], v[212:215], v[0:3]
	s_setprio 0
	s_setprio 1
	v_mfma_f32_16x16x32_bf16 v[60:63], v[168:171], v[184:187], v[60:63]
	v_mfma_f32_16x16x32_bf16 v[56:59], v[176:179], v[184:187], v[56:59]
	v_mfma_f32_16x16x32_bf16 v[44:47], v[168:171], v[192:195], v[44:47]
	v_mfma_f32_16x16x32_bf16 v[40:43], v[176:179], v[192:195], v[40:43]
	v_mfma_f32_16x16x32_bf16 v[28:31], v[168:171], v[200:203], v[28:31]
	v_mfma_f32_16x16x32_bf16 v[24:27], v[176:179], v[200:203], v[24:27]
	v_mfma_f32_16x16x32_bf16 v[12:15], v[168:171], v[208:211], v[12:15]
	v_mfma_f32_16x16x32_bf16 v[8:11], v[176:179], v[208:211], v[8:11]
	s_setprio 0
	s_setprio 1
	v_mfma_f32_16x16x32_bf16 v[60:63], v[172:175], v[188:191], v[60:63]
	v_mfma_f32_16x16x32_bf16 v[56:59], v[180:183], v[188:191], v[56:59]
	v_mfma_f32_16x16x32_bf16 v[44:47], v[172:175], v[196:199], v[44:47]
	v_mfma_f32_16x16x32_bf16 v[40:43], v[180:183], v[196:199], v[40:43]
	v_mfma_f32_16x16x32_bf16 v[28:31], v[172:175], v[204:207], v[28:31]
	v_mfma_f32_16x16x32_bf16 v[24:27], v[180:183], v[204:207], v[24:27]
	v_mfma_f32_16x16x32_bf16 v[12:15], v[172:175], v[212:215], v[12:15]
	v_mfma_f32_16x16x32_bf16 v[8:11], v[180:183], v[212:215], v[8:11]
	s_setprio 0
	s_barrier
	s_add_i32 s75, s75, 2
	s_add_u32 s73, s73, 0x100
	s_addc_u32 s74, s74, 0
	s_cmp_gt_u32 s75, 29
	s_mov_b64 s[36:37], s[38:39]
	s_cbranch_scc0 .LBB0_753
	s_and_b64 vcc, exec, s[20:21]
	s_cbranch_vccz .LBB0_756
	s_barrier

; #define PG8_STAGE(bufoff, gbase, voff) do { _Pragma("unroll") for (int _i = 0; _i < 2; ++_i) \
;         __builtin_amdgcn_global_load_lds((const unsigned*)((const char*)(gbase) + (voff)[_i]), (LAS unsigned*)(lds + (bufoff) + ldsw + _i * 8192), 16, 0, 0); } while (0)
; #define PG8_LDA(dst, b, h) do { _Pragma("unroll") for (int m = 0; m < 4; ++m) _Pragma("unroll") for (int k = 0; k < 2; ++k) dst[m][k] = *(const LAS bf16x8*)(lds + PG8_SA(b, h) + aoff + m * 2048 + k * 1024); } while (0)
; #define PG8_LDB(dst, b, h) do { _Pragma("unroll") for (int n = 0; n < 2; ++n) _Pragma("unroll") for (int k = 0; k < 2; ++k) dst[n][k] = *(const LAS bf16x8*)(lds + PG8_SB(b, h) + boff + n * 2048 + k * 1024); } while (0)
; #define PG8_WAIT_V(n) asm volatile("s_waitcnt vmcnt(" #n ")" ::: "memory")
; template <class Epi, class Sched, bool ALIGN_EPI = false, bool SP2 = false, bool TWOA = false, bool AGM = false>
; __device__ __forceinline__ void gemm_phase(LAS unsigned char* lds, const Gemm g, const Sched& S, const Epi& E, int wid) {
;     ...
;             const bool last = (t == nt - 2);
;             const char* cA2 = TWOA ? (const char*)g.A2 + (cA - (const char*)g.A) - (size_t)nh * kstepA : cA;
;             const char* a1_ = (TWOA && t + 1 >= nh ? cA2 : cA) + (size_t)(t + 1) * kstepA;
;             const char* a2_ = last ? nA : (TWOA && t + 2 >= nh ? cA2 : cA) + (size_t)(t + 2) * kstepA; const char* a1 = a1_; const char* a2 = a2_; const char* b2 = last ? nB : cB + (size_t)(t + 2) * kstep;
;             if constexpr (TWOA) { asm volatile("" : "+s"(a1)); asm volatile("" : "+s"(a2)); }
;             const char* a3 = a2 + kstepA; const char* b3 = b2 + kstep;
;             if (last && has_next) S.a_ready(nxt);
;             if constexpr (has_mid<Epi>::value) { if (t == nh) E.mid(acc, cur, wr, wc, fr, fq); }
;             if constexpr (SP2) {
;             PG8_LDB(B0, 0, 0); PG8_LDB(B1, 0, 1); PG8_SCHED; PG8_LDA(At, 0, 0); PG8_STAGE(PG8_SA(1, 1), a1 + hstepA, voffA);
;             PG8_WAIT_V(8); PG8_WAIT_L(0); PG8_BAR; PG8_MMA(0, 0, At, B0); PG8_MMA(0, 1, At, B1); PG8_BAR; PG8_SCHED;
;             PG8_LDA(At, 0, 1); PG8_STAGE(PG8_SB(0, 0), b2, voffB); PG8_STAGE(PG8_SB(0, 1), b2 + hstep, voffB); PG8_STAGE(PG8_SA(0, 0), a2, voffA);
;             PG8_WAIT_V(8); PG8_WAIT_L(0); PG8_BAR; PG8_MMA(1, 0, At, B0); PG8_MMA(1, 1, At, B1); PG8_BAR; PG8_SCHED;
.LBB0_826:
	v_add_u32_e32 v1, s65, v153
	ds_read_b128 v[132:135], v1
	ds_read_b128 v[136:139], v1 offset:1024
	ds_read_b128 v[158:161], v1 offset:2048
	ds_read_b128 v[162:165], v1 offset:3072
	v_add_u32_e32 v1, s66, v153
	ds_read_b128 v[166:169], v1
	ds_read_b128 v[170:173], v1 offset:1024
	ds_read_b128 v[174:177], v1 offset:2048
	ds_read_b128 v[178:181], v1 offset:3072
	s_add_u32 s74, s71, s36
	s_addc_u32 s75, s72, s37
	s_and_b64 s[34:35], s[42:43], exec
	s_cselect_b32 s43, s23, s75
	s_cselect_b32 s42, s68, s74
	s_add_u32 s34, s40, 0x80000
	s_addc_u32 s35, s41, 0
	v_lshl_add_u64 v[2:3], s[34:35], 0, v[146:147]
	s_add_i32 m0, s50, 0xc000
	ds_read_b128 v[182:185], v156
	ds_read_b128 v[186:189], v156 offset:1024
	ds_read_b128 v[190:193], v156 offset:2048
	ds_read_b128 v[194:197], v156 offset:3072
	ds_read_b128 v[198:201], v156 offset:4096
	ds_read_b128 v[202:205], v156 offset:5120
	ds_read_b128 v[206:209], v156 offset:6144
	ds_read_b128 v[210:213], v156 offset:7168
	global_load_lds_dwordx4 v[2:3], off
	v_lshl_add_u64 v[2:3], s[34:35], 0, v[142:143]
	s_add_i32 m0, s50, 0xe000
	s_nop 0
	global_load_lds_dwordx4 v[2:3], off
	s_waitcnt vmcnt(8)
	s_waitcnt lgkmcnt(0)
	s_barrier
	s_setprio 1
	s_waitcnt lgkmcnt(0)
	v_mfma_f32_16x16x32_bf16 v[128:131], v[132:135], v[182:185], v[128:131]
	v_mfma_f32_16x16x32_bf16 v[124:127], v[158:161], v[182:185], v[124:127]
	v_mfma_f32_16x16x32_bf16 v[112:115], v[132:135], v[190:193], v[112:115]
	v_mfma_f32_16x16x32_bf16 v[108:111], v[158:161], v[190:193], v[108:111]
	v_mfma_f32_16x16x32_bf16 v[96:99], v[132:135], v[198:201], v[96:99]
	v_mfma_f32_16x16x32_bf16 v[92:95], v[158:161], v[198:201], v[92:95]
	v_mfma_f32_16x16x32_bf16 v[80:83], v[132:135], v[206:209], v[80:83]
	v_mfma_f32_16x16x32_bf16 v[76:79], v[158:161], v[206:209], v[76:79]
	s_setprio 0
	s_setprio 1
	v_mfma_f32_16x16x32_bf16 v[128:131], v[136:139], v[186:189], v[128:131]
	v_mfma_f32_16x16x32_bf16 v[124:127], v[162:165], v[186:189], v[124:127]
	v_mfma_f32_16x16x32_bf16 v[112:115], v[136:139], v[194:197], v[112:115]
	v_mfma_f32_16x16x32_bf16 v[108:111], v[162:165], v[194:197], v[108:111]
	v_mfma_f32_16x16x32_bf16 v[96:99], v[136:139], v[202:205], v[96:99]
	v_mfma_f32_16x16x32_bf16 v[92:95], v[162:165], v[202:205], v[92:95]
	v_mfma_f32_16x16x32_bf16 v[80:83], v[136:139], v[210:213], v[80:83]
	v_mfma_f32_16x16x32_bf16 v[76:79], v[162:165], v[210:213], v[76:79]
	s_setprio 0
	s_setprio 1
	v_mfma_f32_16x16x32_bf16 v[120:123], v[166:169], v[182:185], v[120:123]
	v_mfma_f32_16x16x32_bf16 v[116:119], v[174:177], v[182:185], v[116:119]
	v_mfma_f32_16x16x32_bf16 v[104:107], v[166:169], v[190:193], v[104:107]
	v_mfma_f32_16x16x32_bf16 v[100:103], v[174:177], v[190:193], v[100:103]
	v_mfma_f32_16x16x32_bf16 v[88:91], v[166:169], v[198:201], v[88:91]
	v_mfma_f32_16x16x32_bf16 v[84:87], v[174:177], v[198:201], v[84:87]
	v_mfma_f32_16x16x32_bf16 v[72:75], v[166:169], v[206:209], v[72:75]
	v_mfma_f32_16x16x32_bf16 v[68:71], v[174:177], v[206:209], v[68:71]
	s_setprio 0
	s_setprio 1
	v_mfma_f32_16x16x32_bf16 v[120:123], v[170:173], v[186:189], v[120:123]
	v_mfma_f32_16x16x32_bf16 v[116:119], v[178:181], v[186:189], v[116:119]
	v_mfma_f32_16x16x32_bf16 v[104:107], v[170:173], v[194:197], v[104:107]
	v_mfma_f32_16x16x32_bf16 v[100:103], v[178:181], v[194:197], v[100:103]
	v_mfma_f32_16x16x32_bf16 v[88:91], v[170:173], v[202:205], v[88:91]
	v_mfma_f32_16x16x32_bf16 v[84:87], v[178:181], v[202:205], v[84:87]
	v_mfma_f32_16x16x32_bf16 v[72:75], v[170:173], v[210:213], v[72:75]
	v_mfma_f32_16x16x32_bf16 v[68:71], v[178:181], v[210:213], v[68:71]
	s_setprio 0
	s_barrier
	s_add_i32 s34, s65, s47
	v_lshl_add_u64 v[214:215], s[42:43], 0, v[144:145]
	s_mov_b32 m0, s34
	ds_read_b128 v[182:185], v156 offset:16384
	ds_read_b128 v[186:189], v156 offset:17408
	ds_read_b128 v[190:193], v156 offset:18432
	ds_read_b128 v[194:197], v156 offset:19456
	ds_read_b128 v[198:201], v156 offset:20480
	ds_read_b128 v[202:205], v156 offset:21504
	ds_read_b128 v[206:209], v156 offset:22528
	ds_read_b128 v[210:213], v156 offset:23552
	global_load_lds_dwordx4 v[214:215], off
	s_add_i32 m0, s34, 0x2000
	s_add_u32 s34, s42, 0x100000
	v_lshl_add_u64 v[216:217], s[42:43], 0, v[140:141]
	s_addc_u32 s35, s43, 0
	s_add_i32 s40, s66, s47
	global_load_lds_dwordx4 v[216:217], off
	v_lshl_add_u64 v[2:3], s[34:35], 0, v[144:145]
	s_mov_b32 m0, s40
	v_lshl_add_u64 v[218:219], s[38:39], 0, v[146:147]
	global_load_lds_dwordx4 v[2:3], off
	v_lshl_add_u64 v[2:3], s[34:35], 0, v[140:141]
	s_add_i32 m0, s40, 0x2000
	v_lshl_add_u64 v[220:221], s[38:39], 0, v[142:143]
	global_load_lds_dwordx4 v[2:3], off
	s_mov_b32 m0, s50
	s_nop 0
	global_load_lds_dwordx4 v[218:219], off
	s_mov_b32 m0, s51
	s_nop 0
	global_load_lds_dwordx4 v[220:221], off
	s_waitcnt vmcnt(8)
	s_waitcnt lgkmcnt(0)
	s_barrier
; #define PG8_STAGE(bufoff, gbase, voff) do { _Pragma("unroll") for (int _i = 0; _i < 2; ++_i) \
;         __builtin_amdgcn_global_load_lds((const unsigned*)((const char*)(gbase) + (voff)[_i]), (LAS unsigned*)(lds + (bufoff) + ldsw + _i * 8192), 16, 0, 0); } while (0)
; #define PG8_LDA(dst, b, h) do { _Pragma("unroll") for (int m = 0; m < 4; ++m) _Pragma("unroll") for (int k = 0; k < 2; ++k) dst[m][k] = *(const LAS bf16x8*)(lds + PG8_SA(b, h) + aoff + m * 2048 + k * 1024); } while (0)
; #define PG8_LDB(dst, b, h) do { _Pragma("unroll") for (int n = 0; n < 2; ++n) _Pragma("unroll") for (int k = 0; k < 2; ++k) dst[n][k] = *(const LAS bf16x8*)(lds + PG8_SB(b, h) + boff + n * 2048 + k * 1024); } while (0)
; #define PG8_MMA(ai, bj, At, Bt) do { __builtin_amdgcn_s_setprio(1); _Pragma("unroll") for (int m = 0; m < 4; ++m) _Pragma("unroll") for (int n = 0; n < 2; ++n) _Pragma("unroll") for (int k = 0; k < 2; ++k) \
;         acc[ai][bj][m][n] = __builtin_amdgcn_mfma_f32_16x16x32_bf16(Bt[n][k], At[m][k], acc[ai][bj][m][n], 0, 0, 0); __builtin_amdgcn_s_setprio(0); } while (0)
; #define PG8_WAIT_V(n) asm volatile("s_waitcnt vmcnt(" #n ")" ::: "memory")
; #define PG8_WAIT_L(n) asm volatile("s_waitcnt lgkmcnt(" #n ")" ::: "memory")
; #define PG8_BAR __builtin_amdgcn_s_barrier()
; #define PG8_SCHED __builtin_amdgcn_sched_barrier(0)
; template <class Epi, class Sched, bool ALIGN_EPI = false, bool SP2 = false, bool TWOA = false, bool AGM = false>
; __device__ __forceinline__ void gemm_phase(LAS unsigned char* lds, const Gemm g, const Sched& S, const Epi& E, int wid) {
;     ...
;             PG8_WAIT_V(8); PG8_WAIT_L(0); PG8_BAR; PG8_MMA(1, 0, At, B0); PG8_MMA(1, 1, At, B1); PG8_BAR; PG8_SCHED;
;             PG8_LDB(B0, 1, 0); PG8_LDB(B1, 1, 1); PG8_SCHED; PG8_LDA(At, 1, 0); PG8_STAGE(PG8_SA(0, 1), a2 + hstepA, voffA);
;             PG8_WAIT_V(8); PG8_WAIT_L(0); PG8_BAR; PG8_MMA(0, 0, At, B0); PG8_MMA(0, 1, At, B1); PG8_BAR; PG8_SCHED;
;             PG8_LDA(At, 1, 1); PG8_STAGE(PG8_SB(1, 0), b3, voffB); PG8_STAGE(PG8_SB(1, 1), b3 + hstep, voffB); PG8_STAGE(PG8_SA(1, 0), a3, voffA);
	s_setprio 1
	s_waitcnt lgkmcnt(0)
	v_mfma_f32_16x16x32_bf16 v[64:67], v[132:135], v[182:185], v[64:67]
	v_mfma_f32_16x16x32_bf16 v[60:63], v[158:161], v[182:185], v[60:63]
	v_mfma_f32_16x16x32_bf16 v[48:51], v[132:135], v[190:193], v[48:51]
	v_mfma_f32_16x16x32_bf16 v[44:47], v[158:161], v[190:193], v[44:47]
	v_mfma_f32_16x16x32_bf16 v[32:35], v[132:135], v[198:201], v[32:35]
	v_mfma_f32_16x16x32_bf16 v[28:31], v[158:161], v[198:201], v[28:31]
	v_mfma_f32_16x16x32_bf16 v[16:19], v[132:135], v[206:209], v[16:19]
	v_mfma_f32_16x16x32_bf16 v[12:15], v[158:161], v[206:209], v[12:15]
	s_setprio 0
	s_setprio 1
	v_mfma_f32_16x16x32_bf16 v[64:67], v[136:139], v[186:189], v[64:67]
	v_mfma_f32_16x16x32_bf16 v[60:63], v[162:165], v[186:189], v[60:63]
	v_mfma_f32_16x16x32_bf16 v[48:51], v[136:139], v[194:197], v[48:51]
	v_mfma_f32_16x16x32_bf16 v[44:47], v[162:165], v[194:197], v[44:47]
	v_mfma_f32_16x16x32_bf16 v[32:35], v[136:139], v[202:205], v[32:35]
	v_mfma_f32_16x16x32_bf16 v[28:31], v[162:165], v[202:205], v[28:31]
	v_mfma_f32_16x16x32_bf16 v[16:19], v[136:139], v[210:213], v[16:19]
	v_mfma_f32_16x16x32_bf16 v[12:15], v[162:165], v[210:213], v[12:15]
	s_setprio 0
	s_setprio 1
	v_mfma_f32_16x16x32_bf16 v[56:59], v[166:169], v[182:185], v[56:59]
	v_mfma_f32_16x16x32_bf16 v[52:55], v[174:177], v[182:185], v[52:55]
	v_mfma_f32_16x16x32_bf16 v[40:43], v[166:169], v[190:193], v[40:43]
	v_mfma_f32_16x16x32_bf16 v[36:39], v[174:177], v[190:193], v[36:39]
	v_mfma_f32_16x16x32_bf16 v[24:27], v[166:169], v[198:201], v[24:27]
	v_mfma_f32_16x16x32_bf16 v[20:23], v[174:177], v[198:201], v[20:23]
	v_mfma_f32_16x16x32_bf16 v[8:11], v[166:169], v[206:209], v[8:11]
	v_mfma_f32_16x16x32_bf16 v[2:5], v[174:177], v[206:209], v[4:7]
	s_setprio 0
	s_setprio 1
	v_mfma_f32_16x16x32_bf16 v[56:59], v[170:173], v[186:189], v[56:59]
	v_mfma_f32_16x16x32_bf16 v[52:55], v[178:181], v[186:189], v[52:55]
	v_mfma_f32_16x16x32_bf16 v[40:43], v[170:173], v[194:197], v[40:43]
	v_mfma_f32_16x16x32_bf16 v[36:39], v[178:181], v[194:197], v[36:39]
	v_mfma_f32_16x16x32_bf16 v[24:27], v[170:173], v[202:205], v[24:27]
	v_mfma_f32_16x16x32_bf16 v[20:23], v[178:181], v[202:205], v[20:23]
	v_mfma_f32_16x16x32_bf16 v[8:11], v[170:173], v[210:213], v[8:11]
	v_mfma_f32_16x16x32_bf16 v[2:5], v[178:181], v[210:213], v[2:5]
	s_setprio 0
	s_barrier
	s_add_i32 s40, 0, 0x18000
	v_add_u32_e32 v1, s40, v153
	s_add_i32 s41, 0, 0x1c000
	ds_read_b128 v[132:135], v1
	ds_read_b128 v[136:139], v1 offset:1024
	ds_read_b128 v[158:161], v1 offset:2048
	ds_read_b128 v[162:165], v1 offset:3072
	v_add_u32_e32 v1, s41, v153
	ds_read_b128 v[166:169], v1
	ds_read_b128 v[170:173], v1 offset:1024
	ds_read_b128 v[174:177], v1 offset:2048
	ds_read_b128 v[178:181], v1 offset:3072
	s_add_u32 s34, s38, 0x80000
	s_addc_u32 s35, s39, 0
	s_mov_b32 m0, s52
	v_lshl_add_u64 v[6:7], s[34:35], 0, v[146:147]
	ds_read_b128 v[182:185], v156 offset:32768
	ds_read_b128 v[186:189], v156 offset:33792
	ds_read_b128 v[190:193], v156 offset:34816
	ds_read_b128 v[194:197], v156 offset:35840
	ds_read_b128 v[198:201], v156 offset:36864
	ds_read_b128 v[202:205], v156 offset:37888
	ds_read_b128 v[206:209], v156 offset:38912
	ds_read_b128 v[210:213], v156 offset:39936
	global_load_lds_dwordx4 v[6:7], off
	v_lshl_add_u64 v[6:7], s[34:35], 0, v[142:143]
	s_mov_b32 m0, s53
	s_nop 0
	global_load_lds_dwordx4 v[6:7], off
	s_waitcnt vmcnt(8)
	s_waitcnt lgkmcnt(0)
	s_barrier
	s_setprio 1
	s_waitcnt lgkmcnt(0)
	v_mfma_f32_16x16x32_bf16 v[128:131], v[132:135], v[182:185], v[128:131]
	v_mfma_f32_16x16x32_bf16 v[124:127], v[158:161], v[182:185], v[124:127]
	v_mfma_f32_16x16x32_bf16 v[112:115], v[132:135], v[190:193], v[112:115]
	v_mfma_f32_16x16x32_bf16 v[108:111], v[158:161], v[190:193], v[108:111]
	v_mfma_f32_16x16x32_bf16 v[96:99], v[132:135], v[198:201], v[96:99]
	v_mfma_f32_16x16x32_bf16 v[92:95], v[158:161], v[198:201], v[92:95]
	v_mfma_f32_16x16x32_bf16 v[80:83], v[132:135], v[206:209], v[80:83]
	v_mfma_f32_16x16x32_bf16 v[76:79], v[158:161], v[206:209], v[76:79]
	s_setprio 0
	s_setprio 1
	v_mfma_f32_16x16x32_bf16 v[128:131], v[136:139], v[186:189], v[128:131]
	v_mfma_f32_16x16x32_bf16 v[124:127], v[162:165], v[186:189], v[124:127]
	v_mfma_f32_16x16x32_bf16 v[112:115], v[136:139], v[194:197], v[112:115]
	v_mfma_f32_16x16x32_bf16 v[108:111], v[162:165], v[194:197], v[108:111]
	v_mfma_f32_16x16x32_bf16 v[96:99], v[136:139], v[202:205], v[96:99]
	v_mfma_f32_16x16x32_bf16 v[92:95], v[162:165], v[202:205], v[92:95]
	v_mfma_f32_16x16x32_bf16 v[80:83], v[136:139], v[210:213], v[80:83]
	v_mfma_f32_16x16x32_bf16 v[76:79], v[162:165], v[210:213], v[76:79]
	s_setprio 0
	s_setprio 1
	v_mfma_f32_16x16x32_bf16 v[120:123], v[166:169], v[182:185], v[120:123]
	v_mfma_f32_16x16x32_bf16 v[116:119], v[174:177], v[182:185], v[116:119]
	v_mfma_f32_16x16x32_bf16 v[104:107], v[166:169], v[190:193], v[104:107]
	v_mfma_f32_16x16x32_bf16 v[100:103], v[174:177], v[190:193], v[100:103]
	v_mfma_f32_16x16x32_bf16 v[88:91], v[166:169], v[198:201], v[88:91]
	v_mfma_f32_16x16x32_bf16 v[84:87], v[174:177], v[198:201], v[84:87]
	v_mfma_f32_16x16x32_bf16 v[72:75], v[166:169], v[206:209], v[72:75]
	v_mfma_f32_16x16x32_bf16 v[68:71], v[174:177], v[206:209], v[68:71]
	s_setprio 0
	s_setprio 1
	v_mfma_f32_16x16x32_bf16 v[120:123], v[170:173], v[186:189], v[120:123]
	v_mfma_f32_16x16x32_bf16 v[116:119], v[178:181], v[186:189], v[116:119]
	v_mfma_f32_16x16x32_bf16 v[104:107], v[170:173], v[194:197], v[104:107]
	v_mfma_f32_16x16x32_bf16 v[100:103], v[178:181], v[194:197], v[100:103]
	v_mfma_f32_16x16x32_bf16 v[88:91], v[170:173], v[202:205], v[88:91]
	v_mfma_f32_16x16x32_bf16 v[84:87], v[178:181], v[202:205], v[84:87]
	v_mfma_f32_16x16x32_bf16 v[72:75], v[170:173], v[210:213], v[72:75]
	v_mfma_f32_16x16x32_bf16 v[68:71], v[178:181], v[210:213], v[68:71]
	s_setprio 0
	s_barrier
; #define PG8_STAGE(bufoff, gbase, voff) do { _Pragma("unroll") for (int _i = 0; _i < 2; ++_i) \
;         __builtin_amdgcn_global_load_lds((const unsigned*)((const char*)(gbase) + (voff)[_i]), (LAS unsigned*)(lds + (bufoff) + ldsw + _i * 8192), 16, 0, 0); } while (0)
; #define PG8_LDA(dst, b, h) do { _Pragma("unroll") for (int m = 0; m < 4; ++m) _Pragma("unroll") for (int k = 0; k < 2; ++k) dst[m][k] = *(const LAS bf16x8*)(lds + PG8_SA(b, h) + aoff + m * 2048 + k * 1024); } while (0)
; #define PG8_MMA(ai, bj, At, Bt) do { __builtin_amdgcn_s_setprio(1); _Pragma("unroll") for (int m = 0; m < 4; ++m) _Pragma("unroll") for (int n = 0; n < 2; ++n) _Pragma("unroll") for (int k = 0; k < 2; ++k) \
;         acc[ai][bj][m][n] = __builtin_amdgcn_mfma_f32_16x16x32_bf16(Bt[n][k], At[m][k], acc[ai][bj][m][n], 0, 0, 0); __builtin_amdgcn_s_setprio(0); } while (0)
; #define PG8_WAIT_V(n) asm volatile("s_waitcnt vmcnt(" #n ")" ::: "memory")
; #define PG8_WAIT_L(n) asm volatile("s_waitcnt lgkmcnt(" #n ")" ::: "memory")
; #define PG8_BAR __builtin_amdgcn_s_barrier()
; #define PG8_SCHED __builtin_amdgcn_sched_barrier(0)
; template <class Epi, class Sched, bool ALIGN_EPI = false, bool SP2 = false, bool TWOA = false, bool AGM = false>
; __device__ __forceinline__ void gemm_phase(LAS unsigned char* lds, const Gemm g, const Sched& S, const Epi& E, int wid) {
;     ...
;             PG8_LDA(At, 1, 1); PG8_STAGE(PG8_SB(1, 0), b3, voffB); PG8_STAGE(PG8_SB(1, 1), b3 + hstep, voffB); PG8_STAGE(PG8_SA(1, 0), a3, voffA);
;             PG8_WAIT_V(8); PG8_WAIT_L(0); PG8_BAR; PG8_MMA(1, 0, At, B0); PG8_MMA(1, 1, At, B1); PG8_BAR; PG8_SCHED;
;     ...
;         }
;         if constexpr (ALIGN_EPI) { if (wr == 0) PG8_BAR; }
	s_add_i32 s34, s40, s47
	v_lshl_add_u64 v[6:7], v[214:215], 0, s[12:13]
	s_mov_b32 m0, s34
	ds_read_b128 v[182:185], v156 offset:49152
	ds_read_b128 v[186:189], v156 offset:50176
	ds_read_b128 v[190:193], v156 offset:51200
	ds_read_b128 v[194:197], v156 offset:52224
	ds_read_b128 v[198:201], v156 offset:53248
	ds_read_b128 v[202:205], v156 offset:54272
	ds_read_b128 v[206:209], v156 offset:55296
	ds_read_b128 v[210:213], v156 offset:56320
	global_load_lds_dwordx4 v[6:7], off
	s_add_i32 m0, s34, 0x2000
	s_add_u32 s34, s42, 0x100080
	v_lshl_add_u64 v[6:7], v[216:217], 0, s[12:13]
	s_addc_u32 s35, s43, 0
	s_add_i32 s38, s41, s47
	global_load_lds_dwordx4 v[6:7], off
	v_lshl_add_u64 v[6:7], s[34:35], 0, v[144:145]
	s_mov_b32 m0, s38
	s_nop 0
	global_load_lds_dwordx4 v[6:7], off
	v_lshl_add_u64 v[6:7], s[34:35], 0, v[140:141]
	s_add_i32 m0, s38, 0x2000
	s_nop 0
	global_load_lds_dwordx4 v[6:7], off
	v_lshl_add_u64 v[6:7], v[218:219], 0, s[12:13]
	s_mov_b32 m0, s55
	s_nop 0
	global_load_lds_dwordx4 v[6:7], off
	v_lshl_add_u64 v[6:7], v[220:221], 0, s[12:13]
	s_mov_b32 m0, s56
	s_nop 0
	global_load_lds_dwordx4 v[6:7], off
	s_waitcnt vmcnt(8)
	s_waitcnt lgkmcnt(0)
	s_barrier
	s_setprio 1
	s_waitcnt lgkmcnt(0)
	v_mfma_f32_16x16x32_bf16 v[64:67], v[132:135], v[182:185], v[64:67]
	v_mfma_f32_16x16x32_bf16 v[60:63], v[158:161], v[182:185], v[60:63]
	v_mfma_f32_16x16x32_bf16 v[48:51], v[132:135], v[190:193], v[48:51]
	v_mfma_f32_16x16x32_bf16 v[44:47], v[158:161], v[190:193], v[44:47]
	v_mfma_f32_16x16x32_bf16 v[32:35], v[132:135], v[198:201], v[32:35]
	v_mfma_f32_16x16x32_bf16 v[28:31], v[158:161], v[198:201], v[28:31]
	v_mfma_f32_16x16x32_bf16 v[16:19], v[132:135], v[206:209], v[16:19]
	v_mfma_f32_16x16x32_bf16 v[12:15], v[158:161], v[206:209], v[12:15]
	s_setprio 0
	s_setprio 1
	v_mfma_f32_16x16x32_bf16 v[64:67], v[136:139], v[186:189], v[64:67]
	v_mfma_f32_16x16x32_bf16 v[60:63], v[162:165], v[186:189], v[60:63]
	v_mfma_f32_16x16x32_bf16 v[48:51], v[136:139], v[194:197], v[48:51]
	v_mfma_f32_16x16x32_bf16 v[44:47], v[162:165], v[194:197], v[44:47]
	v_mfma_f32_16x16x32_bf16 v[32:35], v[136:139], v[202:205], v[32:35]
	v_mfma_f32_16x16x32_bf16 v[28:31], v[162:165], v[202:205], v[28:31]
	v_mfma_f32_16x16x32_bf16 v[16:19], v[136:139], v[210:213], v[16:19]
	v_mfma_f32_16x16x32_bf16 v[12:15], v[162:165], v[210:213], v[12:15]
	s_setprio 0
	s_setprio 1
	v_mfma_f32_16x16x32_bf16 v[56:59], v[166:169], v[182:185], v[56:59]
	v_mfma_f32_16x16x32_bf16 v[52:55], v[174:177], v[182:185], v[52:55]
	v_mfma_f32_16x16x32_bf16 v[40:43], v[166:169], v[190:193], v[40:43]
	v_mfma_f32_16x16x32_bf16 v[36:39], v[174:177], v[190:193], v[36:39]
	v_mfma_f32_16x16x32_bf16 v[24:27], v[166:169], v[198:201], v[24:27]
	v_mfma_f32_16x16x32_bf16 v[20:23], v[174:177], v[198:201], v[20:23]
	v_mfma_f32_16x16x32_bf16 v[6:9], v[166:169], v[206:209], v[8:11]
	v_mfma_f32_16x16x32_bf16 v[2:5], v[174:177], v[206:209], v[2:5]
	s_setprio 0
	s_setprio 1
	v_mfma_f32_16x16x32_bf16 v[56:59], v[170:173], v[186:189], v[56:59]
	v_mfma_f32_16x16x32_bf16 v[52:55], v[178:181], v[186:189], v[52:55]
	v_mfma_f32_16x16x32_bf16 v[40:43], v[170:173], v[194:197], v[40:43]
	v_mfma_f32_16x16x32_bf16 v[36:39], v[178:181], v[194:197], v[36:39]
	v_mfma_f32_16x16x32_bf16 v[24:27], v[170:173], v[202:205], v[24:27]
	v_mfma_f32_16x16x32_bf16 v[20:23], v[178:181], v[202:205], v[20:23]
	v_mfma_f32_16x16x32_bf16 v[8:11], v[170:173], v[210:213], v[6:9]
	v_mfma_f32_16x16x32_bf16 v[4:7], v[178:181], v[210:213], v[2:5]
	s_setprio 0
	s_barrier
	s_add_u32 s36, s36, 0x100
	s_addc_u32 s37, s37, 0
	s_cmp_gt_u32 s73, 61
	s_cbranch_scc1 .LBB0_829

; #define PG8_STAGE(bufoff, gbase, voff) do { _Pragma("unroll") for (int _i = 0; _i < 2; ++_i) \
;         __builtin_amdgcn_global_load_lds((const unsigned*)((const char*)(gbase) + (voff)[_i]), (LAS unsigned*)(lds + (bufoff) + ldsw + _i * 8192), 16, 0, 0); } while (0)
; #define PG8_LDA(dst, b, h) do { _Pragma("unroll") for (int m = 0; m < 4; ++m) _Pragma("unroll") for (int k = 0; k < 2; ++k) dst[m][k] = *(const LAS bf16x8*)(lds + PG8_SA(b, h) + aoff + m * 2048 + k * 1024); } while (0)
; #define PG8_LDB(dst, b, h) do { _Pragma("unroll") for (int n = 0; n < 2; ++n) _Pragma("unroll") for (int k = 0; k < 2; ++k) dst[n][k] = *(const LAS bf16x8*)(lds + PG8_SB(b, h) + boff + n * 2048 + k * 1024); } while (0)
; #define PG8_WAIT_V(n) asm volatile("s_waitcnt vmcnt(" #n ")" ::: "memory")
; template <class Epi, class Sched, bool ALIGN_EPI = false, bool SP2 = false, bool TWOA = false, bool AGM = false>
; __device__ __forceinline__ void gemm_phase(LAS unsigned char* lds, const Gemm g, const Sched& S, const Epi& E, int wid) {
;     ...
;             const bool last = (t == nt - 2);
;             const char* cA2 = TWOA ? (const char*)g.A2 + (cA - (const char*)g.A) - (size_t)nh * kstepA : cA;
;             const char* a1_ = (TWOA && t + 1 >= nh ? cA2 : cA) + (size_t)(t + 1) * kstepA;
;             const char* a2_ = last ? nA : (TWOA && t + 2 >= nh ? cA2 : cA) + (size_t)(t + 2) * kstepA; const char* a1 = a1_; const char* a2 = a2_; const char* b2 = last ? nB : cB + (size_t)(t + 2) * kstep;
;             if constexpr (TWOA) { asm volatile("" : "+s"(a1)); asm volatile("" : "+s"(a2)); }
;             const char* a3 = a2 + kstepA; const char* b3 = b2 + kstep;
;             if (last && has_next) S.a_ready(nxt);
;             if constexpr (has_mid<Epi>::value) { if (t == nh) E.mid(acc, cur, wr, wc, fr, fq); }
;             if constexpr (SP2) {
;             PG8_LDB(B0, 0, 0); PG8_LDB(B1, 0, 1); PG8_SCHED; PG8_LDA(At, 0, 0); PG8_STAGE(PG8_SA(1, 1), a1 + hstepA, voffA);
;             PG8_WAIT_V(8); PG8_WAIT_L(0); PG8_BAR; PG8_MMA(0, 0, At, B0); PG8_MMA(0, 1, At, B1); PG8_BAR; PG8_SCHED;
;             PG8_LDA(At, 0, 1); PG8_STAGE(PG8_SB(0, 0), b2, voffB); PG8_STAGE(PG8_SB(0, 1), b2 + hstep, voffB); PG8_STAGE(PG8_SA(0, 0), a2, voffA);
;             PG8_WAIT_V(8); PG8_WAIT_L(0); PG8_BAR; PG8_MMA(1, 0, At, B0); PG8_MMA(1, 1, At, B1); PG8_BAR; PG8_SCHED;
.LBB0_901:
	ds_read_b128 v[146:149], v155
	ds_read_b128 v[158:161], v155 offset:1024
	ds_read_b128 v[162:165], v155 offset:2048
	ds_read_b128 v[166:169], v155 offset:3072
	ds_read_b128 v[170:173], v156
	ds_read_b128 v[174:177], v156 offset:1024
	ds_read_b128 v[178:181], v156 offset:2048
	ds_read_b128 v[182:185], v156 offset:3072
	s_add_u32 s38, s36, 0xfff00080
	s_addc_u32 s39, s37, -1
	s_cmp_eq_u32 s67, 60
	s_cselect_b32 s41, s27, s39
	s_cselect_b32 s40, s63, s38
	s_cselect_b32 s39, s25, s66
	s_cselect_b32 s38, s64, s65
	v_lshl_add_u64 v[150:151], s[36:37], 0, v[138:139]
	s_add_i32 m0, s35, 0xc000
	ds_read_b128 v[186:189], v157
	ds_read_b128 v[190:193], v157 offset:1024
	ds_read_b128 v[194:197], v157 offset:2048
	ds_read_b128 v[198:201], v157 offset:3072
	ds_read_b128 v[202:205], v157 offset:4096
	ds_read_b128 v[206:209], v157 offset:5120
	ds_read_b128 v[210:213], v157 offset:6144
	ds_read_b128 v[214:217], v157 offset:7168
	global_load_lds_dwordx4 v[150:151], off
	v_lshl_add_u64 v[150:151], s[36:37], 0, v[140:141]
	s_add_i32 m0, s35, 0xe000
	s_nop 0
	global_load_lds_dwordx4 v[150:151], off
	s_waitcnt vmcnt(8)
	s_waitcnt lgkmcnt(0)
	s_barrier
	s_setprio 1
	s_waitcnt lgkmcnt(0)
	v_mfma_f32_16x16x32_bf16 v[124:127], v[146:149], v[186:189], v[124:127]
	v_mfma_f32_16x16x32_bf16 v[120:123], v[162:165], v[186:189], v[120:123]
	v_mfma_f32_16x16x32_bf16 v[116:119], v[146:149], v[194:197], v[116:119]
	v_mfma_f32_16x16x32_bf16 v[108:111], v[162:165], v[194:197], v[108:111]
	v_mfma_f32_16x16x32_bf16 v[100:103], v[146:149], v[202:205], v[100:103]
	v_mfma_f32_16x16x32_bf16 v[92:95], v[162:165], v[202:205], v[92:95]
	v_mfma_f32_16x16x32_bf16 v[84:87], v[146:149], v[210:213], v[84:87]
	v_mfma_f32_16x16x32_bf16 v[76:79], v[162:165], v[210:213], v[76:79]
	s_setprio 0
	s_setprio 1
	v_mfma_f32_16x16x32_bf16 v[124:127], v[158:161], v[190:193], v[124:127]
	v_mfma_f32_16x16x32_bf16 v[120:123], v[166:169], v[190:193], v[120:123]
	v_mfma_f32_16x16x32_bf16 v[116:119], v[158:161], v[198:201], v[116:119]
	v_mfma_f32_16x16x32_bf16 v[108:111], v[166:169], v[198:201], v[108:111]
	v_mfma_f32_16x16x32_bf16 v[100:103], v[158:161], v[206:209], v[100:103]
	v_mfma_f32_16x16x32_bf16 v[92:95], v[166:169], v[206:209], v[92:95]
	v_mfma_f32_16x16x32_bf16 v[84:87], v[158:161], v[214:217], v[84:87]
	v_mfma_f32_16x16x32_bf16 v[76:79], v[166:169], v[214:217], v[76:79]
	s_setprio 0
	s_setprio 1
	v_mfma_f32_16x16x32_bf16 v[112:115], v[170:173], v[186:189], v[112:115]
	v_mfma_f32_16x16x32_bf16 v[104:107], v[178:181], v[186:189], v[104:107]
	v_mfma_f32_16x16x32_bf16 v[96:99], v[170:173], v[194:197], v[96:99]
	v_mfma_f32_16x16x32_bf16 v[88:91], v[178:181], v[194:197], v[88:91]
	v_mfma_f32_16x16x32_bf16 v[80:83], v[170:173], v[202:205], v[80:83]
	v_mfma_f32_16x16x32_bf16 v[72:75], v[178:181], v[202:205], v[72:75]
	v_mfma_f32_16x16x32_bf16 v[68:71], v[170:173], v[210:213], v[68:71]
	v_mfma_f32_16x16x32_bf16 v[64:67], v[178:181], v[210:213], v[64:67]
	s_setprio 0
	s_setprio 1
	v_mfma_f32_16x16x32_bf16 v[112:115], v[174:177], v[190:193], v[112:115]
	v_mfma_f32_16x16x32_bf16 v[104:107], v[182:185], v[190:193], v[104:107]
	v_mfma_f32_16x16x32_bf16 v[96:99], v[174:177], v[198:201], v[96:99]
	v_mfma_f32_16x16x32_bf16 v[88:91], v[182:185], v[198:201], v[88:91]
	v_mfma_f32_16x16x32_bf16 v[80:83], v[174:177], v[206:209], v[80:83]
	v_mfma_f32_16x16x32_bf16 v[72:75], v[182:185], v[206:209], v[72:75]
	v_mfma_f32_16x16x32_bf16 v[68:71], v[174:177], v[214:217], v[68:71]
	v_mfma_f32_16x16x32_bf16 v[64:67], v[182:185], v[214:217], v[64:67]
	s_setprio 0
	s_barrier
	s_add_i32 s68, s54, s44
	v_lshl_add_u64 v[150:151], s[38:39], 0, v[132:133]
	s_mov_b32 m0, s68
	ds_read_b128 v[186:189], v157 offset:16384
	ds_read_b128 v[190:193], v157 offset:17408
	ds_read_b128 v[194:197], v157 offset:18432
	ds_read_b128 v[198:201], v157 offset:19456
	ds_read_b128 v[202:205], v157 offset:20480
	ds_read_b128 v[206:209], v157 offset:21504
	ds_read_b128 v[210:213], v157 offset:22528
	ds_read_b128 v[214:217], v157 offset:23552
	global_load_lds_dwordx4 v[150:151], off
	s_add_i32 m0, s68, 0x2000
	s_add_u32 s68, s38, 0x100000
	v_lshl_add_u64 v[218:219], s[38:39], 0, v[128:129]
	s_addc_u32 s69, s39, 0
	s_add_i32 s70, s55, s44
	global_load_lds_dwordx4 v[218:219], off
	v_lshl_add_u64 v[220:221], s[68:69], 0, v[132:133]
	s_mov_b32 m0, s70
	v_lshl_add_u64 v[222:223], s[40:41], 0, v[130:131]
	global_load_lds_dwordx4 v[220:221], off
	v_lshl_add_u64 v[220:221], s[68:69], 0, v[128:129]
	s_add_i32 m0, s70, 0x2000
	s_nop 0
	global_load_lds_dwordx4 v[220:221], off
	v_lshl_add_u64 v[220:221], s[40:41], 0, v[134:135]
	s_mov_b32 m0, s35
	s_nop 0
	global_load_lds_dwordx4 v[220:221], off
	s_mov_b32 m0, s47
	s_nop 0
	global_load_lds_dwordx4 v[222:223], off
	s_waitcnt vmcnt(8)
	s_waitcnt lgkmcnt(0)
	s_barrier
; #define PG8_STAGE(bufoff, gbase, voff) do { _Pragma("unroll") for (int _i = 0; _i < 2; ++_i) \
;         __builtin_amdgcn_global_load_lds((const unsigned*)((const char*)(gbase) + (voff)[_i]), (LAS unsigned*)(lds + (bufoff) + ldsw + _i * 8192), 16, 0, 0); } while (0)
; #define PG8_LDA(dst, b, h) do { _Pragma("unroll") for (int m = 0; m < 4; ++m) _Pragma("unroll") for (int k = 0; k < 2; ++k) dst[m][k] = *(const LAS bf16x8*)(lds + PG8_SA(b, h) + aoff + m * 2048 + k * 1024); } while (0)
; #define PG8_LDB(dst, b, h) do { _Pragma("unroll") for (int n = 0; n < 2; ++n) _Pragma("unroll") for (int k = 0; k < 2; ++k) dst[n][k] = *(const LAS bf16x8*)(lds + PG8_SB(b, h) + boff + n * 2048 + k * 1024); } while (0)
; #define PG8_MMA(ai, bj, At, Bt) do { __builtin_amdgcn_s_setprio(1); _Pragma("unroll") for (int m = 0; m < 4; ++m) _Pragma("unroll") for (int n = 0; n < 2; ++n) _Pragma("unroll") for (int k = 0; k < 2; ++k) \
;         acc[ai][bj][m][n] = __builtin_amdgcn_mfma_f32_16x16x32_bf16(Bt[n][k], At[m][k], acc[ai][bj][m][n], 0, 0, 0); __builtin_amdgcn_s_setprio(0); } while (0)
; #define PG8_WAIT_V(n) asm volatile("s_waitcnt vmcnt(" #n ")" ::: "memory")
; #define PG8_WAIT_L(n) asm volatile("s_waitcnt lgkmcnt(" #n ")" ::: "memory")
; #define PG8_BAR __builtin_amdgcn_s_barrier()
; #define PG8_SCHED __builtin_amdgcn_sched_barrier(0)
; template <class Epi, class Sched, bool ALIGN_EPI = false, bool SP2 = false, bool TWOA = false, bool AGM = false>
; __device__ __forceinline__ void gemm_phase(LAS unsigned char* lds, const Gemm g, const Sched& S, const Epi& E, int wid) {
;     ...
;             PG8_WAIT_V(8); PG8_WAIT_L(0); PG8_BAR; PG8_MMA(1, 0, At, B0); PG8_MMA(1, 1, At, B1); PG8_BAR; PG8_SCHED;
;             PG8_LDB(B0, 1, 0); PG8_LDB(B1, 1, 1); PG8_SCHED; PG8_LDA(At, 1, 0); PG8_STAGE(PG8_SA(0, 1), a2 + hstepA, voffA);
;             PG8_WAIT_V(8); PG8_WAIT_L(0); PG8_BAR; PG8_MMA(0, 0, At, B0); PG8_MMA(0, 1, At, B1); PG8_BAR; PG8_SCHED;
;             PG8_LDA(At, 1, 1); PG8_STAGE(PG8_SB(1, 0), b3, voffB); PG8_STAGE(PG8_SB(1, 1), b3 + hstep, voffB); PG8_STAGE(PG8_SA(1, 0), a3, voffA);
	s_setprio 1
	s_waitcnt lgkmcnt(0)
	v_mfma_f32_16x16x32_bf16 v[60:63], v[146:149], v[186:189], v[60:63]
	v_mfma_f32_16x16x32_bf16 v[56:59], v[162:165], v[186:189], v[56:59]
	v_mfma_f32_16x16x32_bf16 v[52:55], v[146:149], v[194:197], v[52:55]
	v_mfma_f32_16x16x32_bf16 v[44:47], v[162:165], v[194:197], v[44:47]
	v_mfma_f32_16x16x32_bf16 v[36:39], v[146:149], v[202:205], v[36:39]
	v_mfma_f32_16x16x32_bf16 v[28:31], v[162:165], v[202:205], v[28:31]
	v_mfma_f32_16x16x32_bf16 v[20:23], v[146:149], v[210:213], v[20:23]
	v_mfma_f32_16x16x32_bf16 v[12:15], v[162:165], v[210:213], v[12:15]
	s_setprio 0
	s_setprio 1
	v_mfma_f32_16x16x32_bf16 v[60:63], v[158:161], v[190:193], v[60:63]
	v_mfma_f32_16x16x32_bf16 v[56:59], v[166:169], v[190:193], v[56:59]
	v_mfma_f32_16x16x32_bf16 v[52:55], v[158:161], v[198:201], v[52:55]
	v_mfma_f32_16x16x32_bf16 v[44:47], v[166:169], v[198:201], v[44:47]
	v_mfma_f32_16x16x32_bf16 v[36:39], v[158:161], v[206:209], v[36:39]
	v_mfma_f32_16x16x32_bf16 v[28:31], v[166:169], v[206:209], v[28:31]
	v_mfma_f32_16x16x32_bf16 v[20:23], v[158:161], v[214:217], v[20:23]
	v_mfma_f32_16x16x32_bf16 v[12:15], v[166:169], v[214:217], v[12:15]
	s_setprio 0
	s_setprio 1
	v_mfma_f32_16x16x32_bf16 v[48:51], v[170:173], v[186:189], v[48:51]
	v_mfma_f32_16x16x32_bf16 v[40:43], v[178:181], v[186:189], v[40:43]
	v_mfma_f32_16x16x32_bf16 v[32:35], v[170:173], v[194:197], v[32:35]
	v_mfma_f32_16x16x32_bf16 v[24:27], v[178:181], v[194:197], v[24:27]
	v_mfma_f32_16x16x32_bf16 v[16:19], v[170:173], v[202:205], v[16:19]
	v_mfma_f32_16x16x32_bf16 v[8:11], v[178:181], v[202:205], v[8:11]
	v_mfma_f32_16x16x32_bf16 v[4:7], v[170:173], v[210:213], v[4:7]
	v_mfma_f32_16x16x32_bf16 v[0:3], v[178:181], v[210:213], v[0:3]
	s_setprio 0
	s_setprio 1
	v_mfma_f32_16x16x32_bf16 v[48:51], v[174:177], v[190:193], v[48:51]
	v_mfma_f32_16x16x32_bf16 v[40:43], v[182:185], v[190:193], v[40:43]
	v_mfma_f32_16x16x32_bf16 v[32:35], v[174:177], v[198:201], v[32:35]
	v_mfma_f32_16x16x32_bf16 v[24:27], v[182:185], v[198:201], v[24:27]
	v_mfma_f32_16x16x32_bf16 v[16:19], v[174:177], v[206:209], v[16:19]
	v_mfma_f32_16x16x32_bf16 v[8:11], v[182:185], v[206:209], v[8:11]
	v_mfma_f32_16x16x32_bf16 v[4:7], v[174:177], v[214:217], v[4:7]
	v_mfma_f32_16x16x32_bf16 v[0:3], v[182:185], v[214:217], v[0:3]
	s_setprio 0
	s_barrier
	s_add_i32 s68, 0, 0x18000
	v_add_u32_e32 v136, s68, v153
	s_add_i32 s69, 0, 0x1c000
	ds_read_b128 v[146:149], v136
	ds_read_b128 v[158:161], v136 offset:1024
	ds_read_b128 v[162:165], v136 offset:2048
	ds_read_b128 v[166:169], v136 offset:3072
	v_add_u32_e32 v136, s69, v153
	ds_read_b128 v[170:173], v136
	ds_read_b128 v[174:177], v136 offset:1024
	ds_read_b128 v[178:181], v136 offset:2048
	ds_read_b128 v[182:185], v136 offset:3072
	s_add_u32 s40, s40, 0x100000
	s_addc_u32 s41, s41, 0
	s_mov_b32 m0, s48
	v_lshl_add_u64 v[224:225], s[40:41], 0, v[134:135]
	ds_read_b128 v[186:189], v157 offset:32768
	ds_read_b128 v[190:193], v157 offset:33792
	ds_read_b128 v[194:197], v157 offset:34816
	ds_read_b128 v[198:201], v157 offset:35840
	ds_read_b128 v[202:205], v157 offset:36864
	ds_read_b128 v[206:209], v157 offset:37888
	ds_read_b128 v[210:213], v157 offset:38912
	ds_read_b128 v[214:217], v157 offset:39936
	global_load_lds_dwordx4 v[224:225], off
	v_lshl_add_u64 v[224:225], s[40:41], 0, v[130:131]
	s_mov_b32 m0, s49
	s_nop 0
	global_load_lds_dwordx4 v[224:225], off
	s_waitcnt vmcnt(8)
	s_waitcnt lgkmcnt(0)
	s_barrier
	s_setprio 1
	s_waitcnt lgkmcnt(0)
	v_mfma_f32_16x16x32_bf16 v[124:127], v[146:149], v[186:189], v[124:127]
	v_mfma_f32_16x16x32_bf16 v[120:123], v[162:165], v[186:189], v[120:123]
	v_mfma_f32_16x16x32_bf16 v[116:119], v[146:149], v[194:197], v[116:119]
	v_mfma_f32_16x16x32_bf16 v[108:111], v[162:165], v[194:197], v[108:111]
	v_mfma_f32_16x16x32_bf16 v[100:103], v[146:149], v[202:205], v[100:103]
	v_mfma_f32_16x16x32_bf16 v[92:95], v[162:165], v[202:205], v[92:95]
	v_mfma_f32_16x16x32_bf16 v[84:87], v[146:149], v[210:213], v[84:87]
	v_mfma_f32_16x16x32_bf16 v[76:79], v[162:165], v[210:213], v[76:79]
	s_setprio 0
	s_setprio 1
	v_mfma_f32_16x16x32_bf16 v[124:127], v[158:161], v[190:193], v[124:127]
	v_mfma_f32_16x16x32_bf16 v[120:123], v[166:169], v[190:193], v[120:123]
	v_mfma_f32_16x16x32_bf16 v[116:119], v[158:161], v[198:201], v[116:119]
	v_mfma_f32_16x16x32_bf16 v[108:111], v[166:169], v[198:201], v[108:111]
	v_mfma_f32_16x16x32_bf16 v[100:103], v[158:161], v[206:209], v[100:103]
	v_mfma_f32_16x16x32_bf16 v[92:95], v[166:169], v[206:209], v[92:95]
	v_mfma_f32_16x16x32_bf16 v[84:87], v[158:161], v[214:217], v[84:87]
	v_mfma_f32_16x16x32_bf16 v[76:79], v[166:169], v[214:217], v[76:79]
	s_setprio 0
	s_setprio 1
	v_mfma_f32_16x16x32_bf16 v[112:115], v[170:173], v[186:189], v[112:115]
	v_mfma_f32_16x16x32_bf16 v[104:107], v[178:181], v[186:189], v[104:107]
	v_mfma_f32_16x16x32_bf16 v[96:99], v[170:173], v[194:197], v[96:99]
	v_mfma_f32_16x16x32_bf16 v[88:91], v[178:181], v[194:197], v[88:91]
	v_mfma_f32_16x16x32_bf16 v[80:83], v[170:173], v[202:205], v[80:83]
	v_mfma_f32_16x16x32_bf16 v[72:75], v[178:181], v[202:205], v[72:75]
	v_mfma_f32_16x16x32_bf16 v[68:71], v[170:173], v[210:213], v[68:71]
	v_mfma_f32_16x16x32_bf16 v[64:67], v[178:181], v[210:213], v[64:67]
	s_setprio 0
	s_setprio 1
	v_mfma_f32_16x16x32_bf16 v[112:115], v[174:177], v[190:193], v[112:115]
	v_mfma_f32_16x16x32_bf16 v[104:107], v[182:185], v[190:193], v[104:107]
	v_mfma_f32_16x16x32_bf16 v[96:99], v[174:177], v[198:201], v[96:99]
	v_mfma_f32_16x16x32_bf16 v[88:91], v[182:185], v[198:201], v[88:91]
	v_mfma_f32_16x16x32_bf16 v[80:83], v[174:177], v[206:209], v[80:83]
	v_mfma_f32_16x16x32_bf16 v[72:75], v[182:185], v[206:209], v[72:75]
	v_mfma_f32_16x16x32_bf16 v[68:71], v[174:177], v[214:217], v[68:71]
	v_mfma_f32_16x16x32_bf16 v[64:67], v[182:185], v[214:217], v[64:67]
	s_setprio 0
	s_barrier
; #define PG8_STAGE(bufoff, gbase, voff) do { _Pragma("unroll") for (int _i = 0; _i < 2; ++_i) \
;         __builtin_amdgcn_global_load_lds((const unsigned*)((const char*)(gbase) + (voff)[_i]), (LAS unsigned*)(lds + (bufoff) + ldsw + _i * 8192), 16, 0, 0); } while (0)
; #define PG8_LDA(dst, b, h) do { _Pragma("unroll") for (int m = 0; m < 4; ++m) _Pragma("unroll") for (int k = 0; k < 2; ++k) dst[m][k] = *(const LAS bf16x8*)(lds + PG8_SA(b, h) + aoff + m * 2048 + k * 1024); } while (0)
; #define PG8_MMA(ai, bj, At, Bt) do { __builtin_amdgcn_s_setprio(1); _Pragma("unroll") for (int m = 0; m < 4; ++m) _Pragma("unroll") for (int n = 0; n < 2; ++n) _Pragma("unroll") for (int k = 0; k < 2; ++k) \
;         acc[ai][bj][m][n] = __builtin_amdgcn_mfma_f32_16x16x32_bf16(Bt[n][k], At[m][k], acc[ai][bj][m][n], 0, 0, 0); __builtin_amdgcn_s_setprio(0); } while (0)
; #define PG8_WAIT_V(n) asm volatile("s_waitcnt vmcnt(" #n ")" ::: "memory")
; #define PG8_WAIT_L(n) asm volatile("s_waitcnt lgkmcnt(" #n ")" ::: "memory")
; #define PG8_BAR __builtin_amdgcn_s_barrier()
; #define PG8_SCHED __builtin_amdgcn_sched_barrier(0)
; template <class Epi, class Sched, bool ALIGN_EPI = false, bool SP2 = false, bool TWOA = false, bool AGM = false>
; __device__ __forceinline__ void gemm_phase(LAS unsigned char* lds, const Gemm g, const Sched& S, const Epi& E, int wid) {
;     ...
;             PG8_LDA(At, 1, 1); PG8_STAGE(PG8_SB(1, 0), b3, voffB); PG8_STAGE(PG8_SB(1, 1), b3 + hstep, voffB); PG8_STAGE(PG8_SA(1, 0), a3, voffA);
;             PG8_WAIT_V(8); PG8_WAIT_L(0); PG8_BAR; PG8_MMA(1, 0, At, B0); PG8_MMA(1, 1, At, B1); PG8_BAR; PG8_SCHED;
;     ...
;         }
;         if constexpr (ALIGN_EPI) { if (wr == 0) PG8_BAR; }
	s_add_i32 s40, s68, s44
	v_lshl_add_u64 v[150:151], v[150:151], 0, s[6:7]
	s_mov_b32 m0, s40
	ds_read_b128 v[186:189], v157 offset:49152
	ds_read_b128 v[190:193], v157 offset:50176
	ds_read_b128 v[194:197], v157 offset:51200
	ds_read_b128 v[198:201], v157 offset:52224
	ds_read_b128 v[202:205], v157 offset:53248
	ds_read_b128 v[206:209], v157 offset:54272
	ds_read_b128 v[210:213], v157 offset:55296
	ds_read_b128 v[214:217], v157 offset:56320
	global_load_lds_dwordx4 v[150:151], off
	s_add_i32 m0, s40, 0x2000
	s_add_u32 s38, s38, 0x100080
	v_lshl_add_u64 v[150:151], v[218:219], 0, s[6:7]
	s_addc_u32 s39, s39, 0
	s_add_i32 s40, s69, s44
	global_load_lds_dwordx4 v[150:151], off
	v_lshl_add_u64 v[150:151], s[38:39], 0, v[132:133]
	s_mov_b32 m0, s40
	s_nop 0
	global_load_lds_dwordx4 v[150:151], off
	v_lshl_add_u64 v[150:151], s[38:39], 0, v[128:129]
	s_add_i32 m0, s40, 0x2000
	s_nop 0
	global_load_lds_dwordx4 v[150:151], off
	v_lshl_add_u64 v[150:151], v[220:221], 0, s[6:7]
	s_mov_b32 m0, s52
	s_nop 0
	global_load_lds_dwordx4 v[150:151], off
	v_lshl_add_u64 v[150:151], v[222:223], 0, s[6:7]
	s_mov_b32 m0, s53
	s_nop 0
	global_load_lds_dwordx4 v[150:151], off
	s_waitcnt vmcnt(8)
	s_waitcnt lgkmcnt(0)
	s_barrier
	s_setprio 1
	s_waitcnt lgkmcnt(0)
	v_mfma_f32_16x16x32_bf16 v[60:63], v[146:149], v[186:189], v[60:63]
	v_mfma_f32_16x16x32_bf16 v[56:59], v[162:165], v[186:189], v[56:59]
	v_mfma_f32_16x16x32_bf16 v[52:55], v[146:149], v[194:197], v[52:55]
	v_mfma_f32_16x16x32_bf16 v[44:47], v[162:165], v[194:197], v[44:47]
	v_mfma_f32_16x16x32_bf16 v[36:39], v[146:149], v[202:205], v[36:39]
	v_mfma_f32_16x16x32_bf16 v[28:31], v[162:165], v[202:205], v[28:31]
	v_mfma_f32_16x16x32_bf16 v[20:23], v[146:149], v[210:213], v[20:23]
	v_mfma_f32_16x16x32_bf16 v[12:15], v[162:165], v[210:213], v[12:15]
	s_setprio 0
	s_setprio 1
	v_mfma_f32_16x16x32_bf16 v[60:63], v[158:161], v[190:193], v[60:63]
	v_mfma_f32_16x16x32_bf16 v[56:59], v[166:169], v[190:193], v[56:59]
	v_mfma_f32_16x16x32_bf16 v[52:55], v[158:161], v[198:201], v[52:55]
	v_mfma_f32_16x16x32_bf16 v[44:47], v[166:169], v[198:201], v[44:47]
	v_mfma_f32_16x16x32_bf16 v[36:39], v[158:161], v[206:209], v[36:39]
	v_mfma_f32_16x16x32_bf16 v[28:31], v[166:169], v[206:209], v[28:31]
	v_mfma_f32_16x16x32_bf16 v[20:23], v[158:161], v[214:217], v[20:23]
	v_mfma_f32_16x16x32_bf16 v[12:15], v[166:169], v[214:217], v[12:15]
	s_setprio 0
	s_setprio 1
	v_mfma_f32_16x16x32_bf16 v[48:51], v[170:173], v[186:189], v[48:51]
	v_mfma_f32_16x16x32_bf16 v[40:43], v[178:181], v[186:189], v[40:43]
	v_mfma_f32_16x16x32_bf16 v[32:35], v[170:173], v[194:197], v[32:35]
	v_mfma_f32_16x16x32_bf16 v[24:27], v[178:181], v[194:197], v[24:27]
	v_mfma_f32_16x16x32_bf16 v[16:19], v[170:173], v[202:205], v[16:19]
	v_mfma_f32_16x16x32_bf16 v[8:11], v[178:181], v[202:205], v[8:11]
	v_mfma_f32_16x16x32_bf16 v[4:7], v[170:173], v[210:213], v[4:7]
	v_mfma_f32_16x16x32_bf16 v[0:3], v[178:181], v[210:213], v[0:3]
	s_setprio 0
	s_setprio 1
	v_mfma_f32_16x16x32_bf16 v[48:51], v[174:177], v[190:193], v[48:51]
	v_mfma_f32_16x16x32_bf16 v[40:43], v[182:185], v[190:193], v[40:43]
	v_mfma_f32_16x16x32_bf16 v[32:35], v[174:177], v[198:201], v[32:35]
	v_mfma_f32_16x16x32_bf16 v[24:27], v[182:185], v[198:201], v[24:27]
	v_mfma_f32_16x16x32_bf16 v[16:19], v[174:177], v[206:209], v[16:19]
	v_mfma_f32_16x16x32_bf16 v[8:11], v[182:185], v[206:209], v[8:11]
	v_mfma_f32_16x16x32_bf16 v[4:7], v[174:177], v[214:217], v[4:7]
	v_mfma_f32_16x16x32_bf16 v[0:3], v[182:185], v[214:217], v[0:3]
	s_setprio 0
	s_barrier
	s_add_i32 s67, s67, 2
	s_add_u32 s36, s36, 0x100
	s_addc_u32 s37, s37, 0
	s_add_u32 s65, s65, 0x100
	s_addc_u32 s66, s66, 0
	s_cmp_gt_u32 s67, 61
	s_cbranch_scc0 .LBB0_901
	s_and_b64 vcc, exec, s[8:9]
	s_cbranch_vccz .LBB0_904
	s_barrier
